# GEMM main loops: A-fragment ds_read addresses from one base register plus offset immediates (96 per-iteration VALU ops removed)
# speedup vs baseline: 1.0274x; 1.0091x over previous
.LBB0_139:
	v_add_u32_e32 v253, 0x10000, v146
	ds_read_b128 v[140:143], v253
	ds_read_b128 v[150:153], v253 offset:1024
	ds_read_b128 v[154:157], v253 offset:2048
	ds_read_b128 v[158:161], v253 offset:3072
	s_add_u32 s10, s6, 0xfff80080
	s_addc_u32 s11, s7, -1
	s_cmp_eq_u32 s41, 28
	s_cselect_b32 s11, s63, s11
	s_cselect_b32 s10, s62, s10
	s_cselect_b32 s53, s61, s29
	s_cselect_b32 s52, s60, s28
	s_mov_b32 m0, s12
	v_lshl_add_u64 v[206:207], s[6:7], 0, v[136:137]
	ds_read_b128 v[162:165], v145
	ds_read_b128 v[166:169], v145 offset:1024
	ds_read_b128 v[170:173], v145 offset:2048
	ds_read_b128 v[174:177], v145 offset:3072
	ds_read_b128 v[178:181], v145 offset:4096
	ds_read_b128 v[182:185], v145 offset:5120
	ds_read_b128 v[186:189], v145 offset:6144
	ds_read_b128 v[190:193], v145 offset:7168
	global_load_lds_dwordx4 v[206:207], off
	v_lshl_add_u64 v[206:207], s[6:7], 0, v[138:139]
	s_mov_b32 m0, s78
	s_nop 0
	global_load_lds_dwordx4 v[206:207], off
	s_waitcnt lgkmcnt(8)
	s_setprio 1
	s_barrier
	s_waitcnt lgkmcnt(0)
	v_mfma_f32_16x16x32_bf16 v[126:129], v[140:143], v[162:165], v[126:129]
	v_mfma_f32_16x16x32_bf16 v[122:125], v[154:157], v[162:165], v[122:125]
	v_mfma_f32_16x16x32_bf16 v[118:121], v[140:143], v[170:173], v[118:121]
	v_mfma_f32_16x16x32_bf16 v[110:113], v[154:157], v[170:173], v[110:113]
	v_mfma_f32_16x16x32_bf16 v[102:105], v[140:143], v[178:181], v[102:105]
	v_mfma_f32_16x16x32_bf16 v[94:97], v[154:157], v[178:181], v[94:97]
	v_mfma_f32_16x16x32_bf16 v[86:89], v[140:143], v[186:189], v[86:89]
	v_mfma_f32_16x16x32_bf16 v[78:81], v[154:157], v[186:189], v[78:81]
	v_mfma_f32_16x16x32_bf16 v[126:129], v[150:153], v[166:169], v[126:129]
	v_mfma_f32_16x16x32_bf16 v[122:125], v[158:161], v[166:169], v[122:125]
	v_mfma_f32_16x16x32_bf16 v[118:121], v[150:153], v[174:177], v[118:121]
	v_mfma_f32_16x16x32_bf16 v[110:113], v[158:161], v[174:177], v[110:113]
	v_mfma_f32_16x16x32_bf16 v[102:105], v[150:153], v[182:185], v[102:105]
	v_mfma_f32_16x16x32_bf16 v[94:97], v[158:161], v[182:185], v[94:97]
	v_mfma_f32_16x16x32_bf16 v[86:89], v[150:153], v[190:193], v[86:89]
	v_mfma_f32_16x16x32_bf16 v[78:81], v[158:161], v[190:193], v[78:81]
	s_barrier
	s_setprio 0
	s_mov_b32 m0, s83
	ds_read_b128 v[206:209], v253 offset:16384
	ds_read_b128 v[210:213], v253 offset:17408
	v_lshl_add_u64 v[222:223], s[52:53], 0, v[194:195]
	ds_read_b128 v[214:217], v253 offset:18432
	ds_read_b128 v[218:221], v253 offset:19456
	global_load_lds_dwordx4 v[222:223], off
	v_lshl_add_u64 v[224:225], s[52:53], 0, v[134:135]
	s_mov_b32 m0, s54
	s_nop 0
	global_load_lds_dwordx4 v[224:225], off
	s_setprio 1
	s_barrier
	s_waitcnt lgkmcnt(0)
	v_mfma_f32_16x16x32_bf16 v[114:117], v[206:209], v[162:165], v[114:117]
	v_mfma_f32_16x16x32_bf16 v[106:109], v[214:217], v[162:165], v[106:109]
	v_mfma_f32_16x16x32_bf16 v[98:101], v[206:209], v[170:173], v[98:101]
	v_mfma_f32_16x16x32_bf16 v[90:93], v[214:217], v[170:173], v[90:93]
	v_mfma_f32_16x16x32_bf16 v[82:85], v[206:209], v[178:181], v[82:85]
	v_mfma_f32_16x16x32_bf16 v[74:77], v[214:217], v[178:181], v[74:77]
	v_mfma_f32_16x16x32_bf16 v[70:73], v[206:209], v[186:189], v[70:73]
	v_mfma_f32_16x16x32_bf16 v[66:69], v[214:217], v[186:189], v[66:69]
	v_mfma_f32_16x16x32_bf16 v[114:117], v[210:213], v[166:169], v[114:117]
	v_mfma_f32_16x16x32_bf16 v[106:109], v[218:221], v[166:169], v[106:109]
	v_mfma_f32_16x16x32_bf16 v[98:101], v[210:213], v[174:177], v[98:101]
	v_mfma_f32_16x16x32_bf16 v[90:93], v[218:221], v[174:177], v[90:93]
	v_mfma_f32_16x16x32_bf16 v[82:85], v[210:213], v[182:185], v[82:85]
	v_mfma_f32_16x16x32_bf16 v[74:77], v[218:221], v[182:185], v[74:77]
	s_mov_b32 m0, s55
	v_mfma_f32_16x16x32_bf16 v[70:73], v[210:213], v[190:193], v[70:73]
	v_lshl_add_u64 v[226:227], s[10:11], 0, v[130:131]
	v_mfma_f32_16x16x32_bf16 v[66:69], v[218:221], v[190:193], v[66:69]
	s_barrier
	s_setprio 0
	ds_read_b128 v[162:165], v145 offset:16384
	ds_read_b128 v[166:169], v145 offset:17408
	ds_read_b128 v[170:173], v145 offset:18432
	ds_read_b128 v[174:177], v145 offset:19456
	ds_read_b128 v[178:181], v145 offset:20480
	ds_read_b128 v[182:185], v145 offset:21504
	ds_read_b128 v[186:189], v145 offset:22528
	ds_read_b128 v[190:193], v145 offset:23552
	global_load_lds_dwordx4 v[226:227], off
	v_lshl_add_u64 v[228:229], s[10:11], 0, v[132:133]
	s_mov_b32 m0, s34
	s_nop 0
	global_load_lds_dwordx4 v[228:229], off
	s_setprio 1
	s_barrier
	s_waitcnt lgkmcnt(0)
	v_mfma_f32_16x16x32_bf16 v[62:65], v[140:143], v[162:165], v[62:65]
	v_mfma_f32_16x16x32_bf16 v[58:61], v[154:157], v[162:165], v[58:61]
	v_mfma_f32_16x16x32_bf16 v[54:57], v[140:143], v[170:173], v[54:57]
	v_mfma_f32_16x16x32_bf16 v[46:49], v[154:157], v[170:173], v[46:49]
	v_mfma_f32_16x16x32_bf16 v[38:41], v[140:143], v[178:181], v[38:41]
	v_mfma_f32_16x16x32_bf16 v[30:33], v[154:157], v[178:181], v[30:33]
	v_mfma_f32_16x16x32_bf16 v[22:25], v[140:143], v[186:189], v[22:25]
	v_mfma_f32_16x16x32_bf16 v[14:17], v[154:157], v[186:189], v[14:17]
	v_mfma_f32_16x16x32_bf16 v[62:65], v[150:153], v[166:169], v[62:65]
	v_mfma_f32_16x16x32_bf16 v[58:61], v[158:161], v[166:169], v[58:61]
	v_mfma_f32_16x16x32_bf16 v[54:57], v[150:153], v[174:177], v[54:57]
	v_mfma_f32_16x16x32_bf16 v[46:49], v[158:161], v[174:177], v[46:49]
	v_mfma_f32_16x16x32_bf16 v[38:41], v[150:153], v[182:185], v[38:41]
	v_mfma_f32_16x16x32_bf16 v[30:33], v[158:161], v[182:185], v[30:33]
	v_mfma_f32_16x16x32_bf16 v[22:25], v[150:153], v[190:193], v[22:25]
	v_mfma_f32_16x16x32_bf16 v[14:17], v[158:161], v[190:193], v[14:17]
	s_barrier
	s_setprio 0
	s_add_u32 s58, s52, 0x80000
	s_addc_u32 s59, s53, 0
	s_mov_b32 m0, s4
	v_lshl_add_u64 v[140:141], s[58:59], 0, v[194:195]
	global_load_lds_dwordx4 v[140:141], off
	v_lshl_add_u64 v[140:141], s[58:59], 0, v[134:135]
	s_mov_b32 m0, s5
	s_nop 0
	global_load_lds_dwordx4 v[140:141], off
	s_waitcnt vmcnt(6)
	s_setprio 1
	s_barrier
	v_mfma_f32_16x16x32_bf16 v[50:53], v[206:209], v[162:165], v[50:53]
	v_mfma_f32_16x16x32_bf16 v[42:45], v[214:217], v[162:165], v[42:45]
	v_mfma_f32_16x16x32_bf16 v[34:37], v[206:209], v[170:173], v[34:37]
	v_mfma_f32_16x16x32_bf16 v[26:29], v[214:217], v[170:173], v[26:29]
	v_mfma_f32_16x16x32_bf16 v[18:21], v[206:209], v[178:181], v[18:21]
	v_mfma_f32_16x16x32_bf16 v[10:13], v[214:217], v[178:181], v[10:13]
	v_mfma_f32_16x16x32_bf16 v[6:9], v[206:209], v[186:189], v[6:9]
	v_mfma_f32_16x16x32_bf16 v[2:5], v[214:217], v[186:189], v[2:5]
	v_mfma_f32_16x16x32_bf16 v[50:53], v[210:213], v[166:169], v[50:53]
	v_mfma_f32_16x16x32_bf16 v[42:45], v[218:221], v[166:169], v[42:45]
	v_mfma_f32_16x16x32_bf16 v[34:37], v[210:213], v[174:177], v[34:37]
	v_mfma_f32_16x16x32_bf16 v[26:29], v[218:221], v[174:177], v[26:29]
	v_mfma_f32_16x16x32_bf16 v[18:21], v[210:213], v[182:185], v[18:21]
	v_mfma_f32_16x16x32_bf16 v[10:13], v[218:221], v[182:185], v[10:13]
	v_mfma_f32_16x16x32_bf16 v[6:9], v[210:213], v[190:193], v[6:9]
	v_mfma_f32_16x16x32_bf16 v[2:5], v[218:221], v[190:193], v[2:5]
	s_barrier
	s_setprio 0
	ds_read_b128 v[140:143], v253 offset:32768
	ds_read_b128 v[150:153], v253 offset:33792
	ds_read_b128 v[154:157], v253 offset:34816
	ds_read_b128 v[158:161], v253 offset:35840
	s_add_u32 s10, s10, 0x80000
	s_addc_u32 s11, s11, 0
	s_mov_b32 m0, s56
	v_lshl_add_u64 v[206:207], s[10:11], 0, v[130:131]
	ds_read_b128 v[162:165], v145 offset:32768
	ds_read_b128 v[166:169], v145 offset:33792
	ds_read_b128 v[170:173], v145 offset:34816
	ds_read_b128 v[174:177], v145 offset:35840
	ds_read_b128 v[178:181], v145 offset:36864
	ds_read_b128 v[182:185], v145 offset:37888
	ds_read_b128 v[186:189], v145 offset:38912
	ds_read_b128 v[190:193], v145 offset:39936
	global_load_lds_dwordx4 v[206:207], off
	v_lshl_add_u64 v[206:207], s[10:11], 0, v[132:133]
	s_mov_b32 m0, s57
	s_nop 0
	global_load_lds_dwordx4 v[206:207], off
	s_waitcnt lgkmcnt(8)
	s_setprio 1
	s_barrier
	s_waitcnt lgkmcnt(0)
	v_mfma_f32_16x16x32_bf16 v[126:129], v[140:143], v[162:165], v[126:129]
	v_mfma_f32_16x16x32_bf16 v[122:125], v[154:157], v[162:165], v[122:125]
	v_mfma_f32_16x16x32_bf16 v[118:121], v[140:143], v[170:173], v[118:121]
	v_mfma_f32_16x16x32_bf16 v[110:113], v[154:157], v[170:173], v[110:113]
	v_mfma_f32_16x16x32_bf16 v[102:105], v[140:143], v[178:181], v[102:105]
	v_mfma_f32_16x16x32_bf16 v[94:97], v[154:157], v[178:181], v[94:97]
	v_mfma_f32_16x16x32_bf16 v[86:89], v[140:143], v[186:189], v[86:89]
	v_mfma_f32_16x16x32_bf16 v[78:81], v[154:157], v[186:189], v[78:81]
	v_mfma_f32_16x16x32_bf16 v[126:129], v[150:153], v[166:169], v[126:129]
	v_mfma_f32_16x16x32_bf16 v[122:125], v[158:161], v[166:169], v[122:125]
	v_mfma_f32_16x16x32_bf16 v[118:121], v[150:153], v[174:177], v[118:121]
	v_mfma_f32_16x16x32_bf16 v[110:113], v[158:161], v[174:177], v[110:113]
	v_mfma_f32_16x16x32_bf16 v[102:105], v[150:153], v[182:185], v[102:105]
	v_mfma_f32_16x16x32_bf16 v[94:97], v[158:161], v[182:185], v[94:97]
	v_mfma_f32_16x16x32_bf16 v[86:89], v[150:153], v[190:193], v[86:89]
	v_mfma_f32_16x16x32_bf16 v[78:81], v[158:161], v[190:193], v[78:81]
	s_barrier
	s_setprio 0
	s_mov_b32 m0, s70
	ds_read_b128 v[206:209], v253 offset:49152
	ds_read_b128 v[210:213], v253 offset:50176
	v_lshl_add_u64 v[222:223], v[222:223], 0, s[76:77]
	ds_read_b128 v[214:217], v253 offset:51200
	ds_read_b128 v[218:221], v253 offset:52224
	global_load_lds_dwordx4 v[222:223], off
	v_lshl_add_u64 v[222:223], v[224:225], 0, s[76:77]
	s_mov_b32 m0, s71
	s_nop 0
	global_load_lds_dwordx4 v[222:223], off
	s_setprio 1
	s_barrier
	s_waitcnt lgkmcnt(0)
	v_mfma_f32_16x16x32_bf16 v[114:117], v[206:209], v[162:165], v[114:117]
	v_mfma_f32_16x16x32_bf16 v[106:109], v[214:217], v[162:165], v[106:109]
	v_mfma_f32_16x16x32_bf16 v[98:101], v[206:209], v[170:173], v[98:101]
	v_mfma_f32_16x16x32_bf16 v[90:93], v[214:217], v[170:173], v[90:93]
	v_mfma_f32_16x16x32_bf16 v[82:85], v[206:209], v[178:181], v[82:85]
	v_mfma_f32_16x16x32_bf16 v[74:77], v[214:217], v[178:181], v[74:77]
	v_mfma_f32_16x16x32_bf16 v[70:73], v[206:209], v[186:189], v[70:73]
	v_mfma_f32_16x16x32_bf16 v[66:69], v[214:217], v[186:189], v[66:69]
	v_mfma_f32_16x16x32_bf16 v[114:117], v[210:213], v[166:169], v[114:117]
	v_mfma_f32_16x16x32_bf16 v[106:109], v[218:221], v[166:169], v[106:109]
	v_mfma_f32_16x16x32_bf16 v[98:101], v[210:213], v[174:177], v[98:101]
	v_mfma_f32_16x16x32_bf16 v[90:93], v[218:221], v[174:177], v[90:93]
	v_mfma_f32_16x16x32_bf16 v[82:85], v[210:213], v[182:185], v[82:85]
	v_mfma_f32_16x16x32_bf16 v[74:77], v[218:221], v[182:185], v[74:77]
	s_mov_b32 m0, s33
	v_mfma_f32_16x16x32_bf16 v[70:73], v[210:213], v[190:193], v[70:73]
	v_lshl_add_u64 v[222:223], v[226:227], 0, s[76:77]
	v_mfma_f32_16x16x32_bf16 v[66:69], v[218:221], v[190:193], v[66:69]
	s_barrier
	s_setprio 0
	ds_read_b128 v[162:165], v145 offset:49152
	ds_read_b128 v[166:169], v145 offset:50176
	ds_read_b128 v[170:173], v145 offset:51200
	ds_read_b128 v[174:177], v145 offset:52224
	ds_read_b128 v[178:181], v145 offset:53248
	ds_read_b128 v[182:185], v145 offset:54272
	ds_read_b128 v[186:189], v145 offset:55296
	ds_read_b128 v[190:193], v145 offset:56320
	global_load_lds_dwordx4 v[222:223], off
	v_lshl_add_u64 v[222:223], v[228:229], 0, s[76:77]
	s_mov_b32 m0, s35
	s_nop 0
	global_load_lds_dwordx4 v[222:223], off
	s_setprio 1
	s_barrier
	s_waitcnt lgkmcnt(0)
	v_mfma_f32_16x16x32_bf16 v[62:65], v[140:143], v[162:165], v[62:65]
	v_mfma_f32_16x16x32_bf16 v[58:61], v[154:157], v[162:165], v[58:61]
	v_mfma_f32_16x16x32_bf16 v[54:57], v[140:143], v[170:173], v[54:57]
	v_mfma_f32_16x16x32_bf16 v[46:49], v[154:157], v[170:173], v[46:49]
	v_mfma_f32_16x16x32_bf16 v[38:41], v[140:143], v[178:181], v[38:41]
	v_mfma_f32_16x16x32_bf16 v[30:33], v[154:157], v[178:181], v[30:33]
	v_mfma_f32_16x16x32_bf16 v[22:25], v[140:143], v[186:189], v[22:25]
	v_mfma_f32_16x16x32_bf16 v[14:17], v[154:157], v[186:189], v[14:17]
	v_mfma_f32_16x16x32_bf16 v[62:65], v[150:153], v[166:169], v[62:65]
	v_mfma_f32_16x16x32_bf16 v[58:61], v[158:161], v[166:169], v[58:61]
	v_mfma_f32_16x16x32_bf16 v[54:57], v[150:153], v[174:177], v[54:57]
	v_mfma_f32_16x16x32_bf16 v[46:49], v[158:161], v[174:177], v[46:49]
	v_mfma_f32_16x16x32_bf16 v[38:41], v[150:153], v[182:185], v[38:41]
	v_mfma_f32_16x16x32_bf16 v[30:33], v[158:161], v[182:185], v[30:33]
	v_mfma_f32_16x16x32_bf16 v[22:25], v[150:153], v[190:193], v[22:25]
	v_mfma_f32_16x16x32_bf16 v[14:17], v[158:161], v[190:193], v[14:17]
	s_barrier
	s_setprio 0
	s_add_u32 s10, s52, 0x80080
	s_addc_u32 s11, s53, 0
	s_mov_b32 m0, s67
	v_lshl_add_u64 v[140:141], s[10:11], 0, v[194:195]
	global_load_lds_dwordx4 v[140:141], off
	v_lshl_add_u64 v[140:141], s[10:11], 0, v[134:135]
	s_mov_b32 m0, s17
	s_nop 0
	global_load_lds_dwordx4 v[140:141], off
	s_waitcnt vmcnt(6)
	s_setprio 1
	s_barrier
	v_mfma_f32_16x16x32_bf16 v[50:53], v[206:209], v[162:165], v[50:53]
	v_mfma_f32_16x16x32_bf16 v[42:45], v[214:217], v[162:165], v[42:45]
	v_mfma_f32_16x16x32_bf16 v[34:37], v[206:209], v[170:173], v[34:37]
	v_mfma_f32_16x16x32_bf16 v[26:29], v[214:217], v[170:173], v[26:29]
	v_mfma_f32_16x16x32_bf16 v[18:21], v[206:209], v[178:181], v[18:21]
	v_mfma_f32_16x16x32_bf16 v[10:13], v[214:217], v[178:181], v[10:13]
	v_mfma_f32_16x16x32_bf16 v[6:9], v[206:209], v[186:189], v[6:9]
	v_mfma_f32_16x16x32_bf16 v[2:5], v[214:217], v[186:189], v[2:5]
	v_mfma_f32_16x16x32_bf16 v[50:53], v[210:213], v[166:169], v[50:53]
	v_mfma_f32_16x16x32_bf16 v[42:45], v[218:221], v[166:169], v[42:45]
	v_mfma_f32_16x16x32_bf16 v[34:37], v[210:213], v[174:177], v[34:37]
	v_mfma_f32_16x16x32_bf16 v[26:29], v[218:221], v[174:177], v[26:29]
	v_mfma_f32_16x16x32_bf16 v[18:21], v[210:213], v[182:185], v[18:21]
	v_mfma_f32_16x16x32_bf16 v[10:13], v[218:221], v[182:185], v[10:13]
	v_mfma_f32_16x16x32_bf16 v[6:9], v[210:213], v[190:193], v[6:9]
	v_mfma_f32_16x16x32_bf16 v[2:5], v[218:221], v[190:193], v[2:5]
	s_setprio 0
	s_add_i32 s41, s41, 2
	s_add_u32 s6, s6, 0x100
	s_addc_u32 s7, s7, 0
	s_add_u32 s28, s28, 0x100
	s_addc_u32 s29, s29, 0
	s_cmp_gt_u32 s41, 29
	s_barrier
	s_cbranch_scc0 .LBB0_139
	s_cmp_gt_i32 s79, 3
	s_mov_b64 s[6:7], -1
	s_cbranch_scc0 .LBB0_146
	s_lshl_b32 s10, s82, 8
	v_lshl_or_b32 v140, s80, 8, v149
	s_cmp_lg_u32 s79, 4
	v_ashrrev_i32_e32 v141, 31, v140
	s_cbranch_scc0 .LBB0_143
	v_readlane_b32 s6, v252, 55
	v_readlane_b32 s7, v252, 56
	v_add_u32_e32 v150, s10, v147
	s_nop 0
	v_mov_b64_e32 v[142:143], s[6:7]
	s_mov_b32 s6, 0x9000
	v_mad_i64_i32 v[142:143], s[6:7], v150, s6, v[142:143]
	v_lshl_add_u64 v[142:143], v[140:141], 1, v[142:143]
	v_cvt_pk_bf16_f32 v150, v126, v127
	v_cvt_pk_bf16_f32 v151, v128, v129
	v_cvt_pk_bf16_f32 v152, v122, v123
	v_cvt_pk_bf16_f32 v153, v124, v125
	global_store_dwordx4 v[142:143], v[150:153], off
	v_add_co_u32_e32 v154, vcc, s44, v142
	s_nop 0
	v_cvt_pk_bf16_f32 v150, v114, v115
	v_cvt_pk_bf16_f32 v151, v116, v117
	v_cvt_pk_bf16_f32 v152, v106, v107
	v_cvt_pk_bf16_f32 v153, v108, v109
	global_store_dwordx4 v[142:143], v[150:153], off offset:256
	v_addc_co_u32_e32 v155, vcc, 0, v143, vcc
	s_nop 0
	v_cvt_pk_bf16_f32 v150, v118, v119
	v_cvt_pk_bf16_f32 v151, v120, v121
	v_cvt_pk_bf16_f32 v152, v110, v111
	v_cvt_pk_bf16_f32 v153, v112, v113
	global_store_dwordx4 v[154:155], v[150:153], off
	s_mov_b64 s[6:7], 0
	s_nop 0
	v_cvt_pk_bf16_f32 v150, v98, v99
	v_cvt_pk_bf16_f32 v151, v100, v101
	v_cvt_pk_bf16_f32 v152, v90, v91
	v_cvt_pk_bf16_f32 v153, v92, v93
	global_store_dwordx4 v[154:155], v[150:153], off offset:256
	v_add_co_u32_e32 v154, vcc, s45, v142
	s_nop 0
	v_cvt_pk_bf16_f32 v150, v102, v103
	v_cvt_pk_bf16_f32 v151, v104, v105
	v_cvt_pk_bf16_f32 v152, v94, v95
	v_cvt_pk_bf16_f32 v153, v96, v97
	s_nop 0
	v_addc_co_u32_e32 v155, vcc, 0, v143, vcc
	global_store_dwordx4 v[154:155], v[150:153], off
	s_nop 1
	v_cvt_pk_bf16_f32 v150, v82, v83
	v_cvt_pk_bf16_f32 v151, v84, v85
	v_cvt_pk_bf16_f32 v152, v74, v75
	v_cvt_pk_bf16_f32 v153, v76, v77
	global_store_dwordx4 v[154:155], v[150:153], off offset:256
	v_add_co_u32_e32 v154, vcc, s90, v142
	s_nop 0
	v_cvt_pk_bf16_f32 v150, v86, v87
	v_cvt_pk_bf16_f32 v151, v88, v89
	v_cvt_pk_bf16_f32 v152, v78, v79
	v_cvt_pk_bf16_f32 v153, v80, v81
	s_nop 0
	v_addc_co_u32_e32 v155, vcc, 0, v143, vcc
	global_store_dwordx4 v[154:155], v[150:153], off
	s_nop 1
	v_cvt_pk_bf16_f32 v150, v70, v71
	v_cvt_pk_bf16_f32 v151, v72, v73
	v_cvt_pk_bf16_f32 v152, v66, v67
	v_cvt_pk_bf16_f32 v153, v68, v69
	global_store_dwordx4 v[154:155], v[150:153], off offset:256
	v_add_co_u32_e32 v154, vcc, s20, v142
	s_nop 0
	v_cvt_pk_bf16_f32 v150, v62, v63
	v_cvt_pk_bf16_f32 v151, v64, v65
	v_cvt_pk_bf16_f32 v152, v58, v59
	v_cvt_pk_bf16_f32 v153, v60, v61
	s_nop 0
	v_addc_co_u32_e32 v155, vcc, 0, v143, vcc
	global_store_dwordx4 v[154:155], v[150:153], off
	s_nop 1
	v_cvt_pk_bf16_f32 v150, v50, v51
	v_cvt_pk_bf16_f32 v151, v52, v53
	v_cvt_pk_bf16_f32 v152, v42, v43
	v_cvt_pk_bf16_f32 v153, v44, v45
	global_store_dwordx4 v[154:155], v[150:153], off offset:256
	v_add_co_u32_e32 v154, vcc, s21, v142
	s_nop 0
	v_cvt_pk_bf16_f32 v150, v54, v55
	v_cvt_pk_bf16_f32 v151, v56, v57
	v_cvt_pk_bf16_f32 v152, v46, v47
	v_cvt_pk_bf16_f32 v153, v48, v49
	s_nop 0
	v_addc_co_u32_e32 v155, vcc, 0, v143, vcc
	global_store_dwordx4 v[154:155], v[150:153], off
	s_nop 1
	v_cvt_pk_bf16_f32 v150, v34, v35
	v_cvt_pk_bf16_f32 v151, v36, v37
	v_cvt_pk_bf16_f32 v152, v26, v27
	v_cvt_pk_bf16_f32 v153, v28, v29
	global_store_dwordx4 v[154:155], v[150:153], off offset:256
	v_add_co_u32_e32 v154, vcc, s22, v142
	s_nop 0
	v_cvt_pk_bf16_f32 v150, v38, v39
	v_cvt_pk_bf16_f32 v151, v40, v41
	v_cvt_pk_bf16_f32 v152, v30, v31
	v_cvt_pk_bf16_f32 v153, v32, v33
	s_nop 0
	v_addc_co_u32_e32 v155, vcc, 0, v143, vcc
	global_store_dwordx4 v[154:155], v[150:153], off
	v_add_co_u32_e32 v142, vcc, s23, v142
	s_nop 0
	v_cvt_pk_bf16_f32 v150, v18, v19
	v_cvt_pk_bf16_f32 v151, v20, v21
	v_cvt_pk_bf16_f32 v152, v10, v11
	v_cvt_pk_bf16_f32 v153, v12, v13
	global_store_dwordx4 v[154:155], v[150:153], off offset:256
	v_addc_co_u32_e32 v143, vcc, 0, v143, vcc
	s_nop 0
	v_cvt_pk_bf16_f32 v150, v22, v23
	v_cvt_pk_bf16_f32 v151, v24, v25
	v_cvt_pk_bf16_f32 v152, v14, v15
	v_cvt_pk_bf16_f32 v153, v16, v17
	global_store_dwordx4 v[142:143], v[150:153], off
	s_nop 1
	v_cvt_pk_bf16_f32 v150, v6, v7
	v_cvt_pk_bf16_f32 v151, v8, v9
	v_cvt_pk_bf16_f32 v152, v2, v3
	v_cvt_pk_bf16_f32 v153, v4, v5
	global_store_dwordx4 v[142:143], v[150:153], off offset:256

.LBB0_204:
	s_add_u32 s80, s54, s62
	s_addc_u32 s81, s55, s63
	s_add_u32 s82, s80, 0x100
	s_addc_u32 s83, s81, 0
	s_and_b64 s[10:11], s[8:9], exec
	s_cselect_b32 s83, s1, s83
	s_cselect_b32 s82, s0, s82
	s_add_u32 s10, s52, s62
	s_addc_u32 s11, s53, s63
	s_add_u32 s10, s10, 0x100
	s_addc_u32 s11, s11, 0
	s_and_b64 s[8:9], s[8:9], exec
	s_cselect_b32 vcc_hi, s7, s11
	s_cselect_b32 vcc_lo, s6, s10
	s_add_u32 s10, s80, 0x10080
	v_add_u32_e32 v253, 0x10000, v142
	s_addc_u32 s11, s81, 0
	s_add_i32 m0, s5, 0xc000
	s_add_i32 s87, s5, 0xe000
	ds_read_b128 v[144:147], v253
	s_add_u32 s80, vcc_lo, 0x340000
	ds_read_b128 v[148:151], v253 offset:1024
	s_addc_u32 s81, vcc_hi, 0
	ds_read_b128 v[152:155], v253 offset:2048
	s_add_u32 s62, s82, 0x10000
	ds_read_b128 v[156:159], v253 offset:3072
	s_addc_u32 s63, s83, 0
	s_add_u32 s8, vcc_lo, 0x340080
	s_addc_u32 s9, vcc_hi, 0
	v_lshl_add_u64 v[138:139], s[10:11], 0, v[136:137]
	ds_read_b128 v[160:163], v141
	ds_read_b128 v[164:167], v141 offset:1024
	ds_read_b128 v[168:171], v141 offset:2048
	ds_read_b128 v[172:175], v141 offset:3072
	ds_read_b128 v[176:179], v141 offset:4096
	ds_read_b128 v[180:183], v141 offset:5120
	ds_read_b128 v[184:187], v141 offset:6144
	ds_read_b128 v[188:191], v141 offset:7168
	global_load_lds_dwordx4 v[138:139], off
	v_lshl_add_u64 v[138:139], s[10:11], 0, v[132:133]
	s_mov_b32 m0, s87
	s_nop 0
	global_load_lds_dwordx4 v[138:139], off
	s_waitcnt lgkmcnt(8)
	s_setprio 1
	s_barrier
	s_waitcnt lgkmcnt(0)
	v_mfma_f32_16x16x32_bf16 v[126:129], v[144:147], v[160:163], v[126:129]
	v_mfma_f32_16x16x32_bf16 v[122:125], v[152:155], v[160:163], v[122:125]
	v_mfma_f32_16x16x32_bf16 v[118:121], v[144:147], v[168:171], v[118:121]
	v_mfma_f32_16x16x32_bf16 v[110:113], v[152:155], v[168:171], v[110:113]
	v_mfma_f32_16x16x32_bf16 v[102:105], v[144:147], v[176:179], v[102:105]
	v_mfma_f32_16x16x32_bf16 v[94:97], v[152:155], v[176:179], v[94:97]
	v_mfma_f32_16x16x32_bf16 v[86:89], v[144:147], v[184:187], v[86:89]
	v_mfma_f32_16x16x32_bf16 v[78:81], v[152:155], v[184:187], v[78:81]
	v_mfma_f32_16x16x32_bf16 v[126:129], v[148:151], v[164:167], v[126:129]
	v_mfma_f32_16x16x32_bf16 v[122:125], v[156:159], v[164:167], v[122:125]
	v_mfma_f32_16x16x32_bf16 v[118:121], v[148:151], v[172:175], v[118:121]
	v_mfma_f32_16x16x32_bf16 v[110:113], v[156:159], v[172:175], v[110:113]
	v_mfma_f32_16x16x32_bf16 v[102:105], v[148:151], v[180:183], v[102:105]
	v_mfma_f32_16x16x32_bf16 v[94:97], v[156:159], v[180:183], v[94:97]
	v_mfma_f32_16x16x32_bf16 v[86:89], v[148:151], v[188:191], v[86:89]
	v_mfma_f32_16x16x32_bf16 v[78:81], v[156:159], v[188:191], v[78:81]
	s_barrier
	s_setprio 0
	ds_read_b128 v[206:209], v253 offset:16384
	ds_read_b128 v[210:213], v253 offset:17408
	s_mov_b32 m0, s12
	ds_read_b128 v[214:217], v253 offset:18432
	ds_read_b128 v[218:221], v253 offset:19456
	v_lshl_add_u64 v[138:139], vcc, 0, v[134:135]
	global_load_lds_dwordx4 v[138:139], off
	v_lshl_add_u64 v[192:193], vcc, 0, v[130:131]
	s_mov_b32 m0, s17
	s_nop 0
	global_load_lds_dwordx4 v[192:193], off
	s_setprio 1
	s_barrier
	s_waitcnt lgkmcnt(0)
	v_mfma_f32_16x16x32_bf16 v[114:117], v[206:209], v[160:163], v[114:117]
	v_mfma_f32_16x16x32_bf16 v[106:109], v[214:217], v[160:163], v[106:109]
	v_mfma_f32_16x16x32_bf16 v[98:101], v[206:209], v[168:171], v[98:101]
	v_mfma_f32_16x16x32_bf16 v[90:93], v[214:217], v[168:171], v[90:93]
	v_mfma_f32_16x16x32_bf16 v[82:85], v[206:209], v[176:179], v[82:85]
	v_mfma_f32_16x16x32_bf16 v[74:77], v[214:217], v[176:179], v[74:77]
	v_mfma_f32_16x16x32_bf16 v[70:73], v[206:209], v[184:187], v[70:73]
	v_mfma_f32_16x16x32_bf16 v[66:69], v[214:217], v[184:187], v[66:69]
	v_mfma_f32_16x16x32_bf16 v[114:117], v[210:213], v[164:167], v[114:117]
	v_mfma_f32_16x16x32_bf16 v[106:109], v[218:221], v[164:167], v[106:109]
	v_mfma_f32_16x16x32_bf16 v[98:101], v[210:213], v[172:175], v[98:101]
	v_mfma_f32_16x16x32_bf16 v[90:93], v[218:221], v[172:175], v[90:93]
	v_mfma_f32_16x16x32_bf16 v[82:85], v[210:213], v[180:183], v[82:85]
	v_mfma_f32_16x16x32_bf16 v[74:77], v[218:221], v[180:183], v[74:77]
	s_mov_b32 m0, s5
	v_mfma_f32_16x16x32_bf16 v[70:73], v[210:213], v[188:191], v[70:73]
	v_lshl_add_u64 v[222:223], s[82:83], 0, v[136:137]
	v_mfma_f32_16x16x32_bf16 v[66:69], v[218:221], v[188:191], v[66:69]
	s_barrier
	s_setprio 0
	ds_read_b128 v[160:163], v141 offset:16384
	ds_read_b128 v[164:167], v141 offset:17408
	ds_read_b128 v[168:171], v141 offset:18432
	ds_read_b128 v[172:175], v141 offset:19456
	ds_read_b128 v[176:179], v141 offset:20480
	ds_read_b128 v[180:183], v141 offset:21504
	ds_read_b128 v[184:187], v141 offset:22528
	ds_read_b128 v[188:191], v141 offset:23552
	global_load_lds_dwordx4 v[222:223], off
	v_lshl_add_u64 v[224:225], s[82:83], 0, v[132:133]
	s_mov_b32 m0, s26
	s_nop 0
	global_load_lds_dwordx4 v[224:225], off
	s_setprio 1
	s_barrier
	s_waitcnt lgkmcnt(0)
	v_mfma_f32_16x16x32_bf16 v[62:65], v[144:147], v[160:163], v[62:65]
	v_mfma_f32_16x16x32_bf16 v[58:61], v[152:155], v[160:163], v[58:61]
	v_mfma_f32_16x16x32_bf16 v[54:57], v[144:147], v[168:171], v[54:57]
	v_mfma_f32_16x16x32_bf16 v[46:49], v[152:155], v[168:171], v[46:49]
	v_mfma_f32_16x16x32_bf16 v[38:41], v[144:147], v[176:179], v[38:41]
	v_mfma_f32_16x16x32_bf16 v[30:33], v[152:155], v[176:179], v[30:33]
	v_mfma_f32_16x16x32_bf16 v[22:25], v[144:147], v[184:187], v[22:25]
	v_mfma_f32_16x16x32_bf16 v[14:17], v[152:155], v[184:187], v[14:17]
	v_mfma_f32_16x16x32_bf16 v[62:65], v[148:151], v[164:167], v[62:65]
	v_mfma_f32_16x16x32_bf16 v[58:61], v[156:159], v[164:167], v[58:61]
	v_mfma_f32_16x16x32_bf16 v[54:57], v[148:151], v[172:175], v[54:57]
	v_mfma_f32_16x16x32_bf16 v[46:49], v[156:159], v[172:175], v[46:49]
	v_mfma_f32_16x16x32_bf16 v[38:41], v[148:151], v[180:183], v[38:41]
	v_mfma_f32_16x16x32_bf16 v[30:33], v[156:159], v[180:183], v[30:33]
	v_mfma_f32_16x16x32_bf16 v[22:25], v[148:151], v[188:191], v[22:25]
	v_mfma_f32_16x16x32_bf16 v[14:17], v[156:159], v[188:191], v[14:17]
	s_barrier
	s_setprio 0
	s_mov_b32 m0, s34
	v_lshl_add_u64 v[144:145], s[80:81], 0, v[134:135]
	global_load_lds_dwordx4 v[144:145], off
	v_lshl_add_u64 v[144:145], s[80:81], 0, v[130:131]
	s_mov_b32 m0, s35
	s_nop 0
	global_load_lds_dwordx4 v[144:145], off
	s_waitcnt vmcnt(6)
	s_setprio 1
	s_barrier
	v_mfma_f32_16x16x32_bf16 v[50:53], v[206:209], v[160:163], v[50:53]
	v_mfma_f32_16x16x32_bf16 v[42:45], v[214:217], v[160:163], v[42:45]
	v_mfma_f32_16x16x32_bf16 v[34:37], v[206:209], v[168:171], v[34:37]
	v_mfma_f32_16x16x32_bf16 v[26:29], v[214:217], v[168:171], v[26:29]
	v_mfma_f32_16x16x32_bf16 v[18:21], v[206:209], v[176:179], v[18:21]
	v_mfma_f32_16x16x32_bf16 v[10:13], v[214:217], v[176:179], v[10:13]
	v_mfma_f32_16x16x32_bf16 v[6:9], v[206:209], v[184:187], v[6:9]
	v_mfma_f32_16x16x32_bf16 v[2:5], v[214:217], v[184:187], v[2:5]
	v_mfma_f32_16x16x32_bf16 v[50:53], v[210:213], v[164:167], v[50:53]
	v_mfma_f32_16x16x32_bf16 v[42:45], v[218:221], v[164:167], v[42:45]
	v_mfma_f32_16x16x32_bf16 v[34:37], v[210:213], v[172:175], v[34:37]
	v_mfma_f32_16x16x32_bf16 v[26:29], v[218:221], v[172:175], v[26:29]
	v_mfma_f32_16x16x32_bf16 v[18:21], v[210:213], v[180:183], v[18:21]
	v_mfma_f32_16x16x32_bf16 v[10:13], v[218:221], v[180:183], v[10:13]
	v_mfma_f32_16x16x32_bf16 v[6:9], v[210:213], v[188:191], v[6:9]
	v_mfma_f32_16x16x32_bf16 v[2:5], v[218:221], v[188:191], v[2:5]
	s_barrier
	s_setprio 0
	ds_read_b128 v[144:147], v253 offset:32768
	ds_read_b128 v[148:151], v253 offset:33792
	ds_read_b128 v[152:155], v253 offset:34816
	ds_read_b128 v[156:159], v253 offset:35840
	s_mov_b32 m0, s56
	v_lshl_add_u64 v[206:207], s[62:63], 0, v[136:137]
	ds_read_b128 v[160:163], v141 offset:32768
	ds_read_b128 v[164:167], v141 offset:33792
	ds_read_b128 v[168:171], v141 offset:34816
	ds_read_b128 v[172:175], v141 offset:35840
	ds_read_b128 v[176:179], v141 offset:36864
	ds_read_b128 v[180:183], v141 offset:37888
	ds_read_b128 v[184:187], v141 offset:38912
	ds_read_b128 v[188:191], v141 offset:39936
	global_load_lds_dwordx4 v[206:207], off
	v_lshl_add_u64 v[206:207], s[62:63], 0, v[132:133]
	s_mov_b32 m0, s57
	s_nop 0
	global_load_lds_dwordx4 v[206:207], off
	s_waitcnt lgkmcnt(8)
	s_setprio 1
	s_barrier
	s_waitcnt lgkmcnt(0)
	v_mfma_f32_16x16x32_bf16 v[126:129], v[144:147], v[160:163], v[126:129]
	v_mfma_f32_16x16x32_bf16 v[122:125], v[152:155], v[160:163], v[122:125]
	v_mfma_f32_16x16x32_bf16 v[118:121], v[144:147], v[168:171], v[118:121]
	v_mfma_f32_16x16x32_bf16 v[110:113], v[152:155], v[168:171], v[110:113]
	v_mfma_f32_16x16x32_bf16 v[102:105], v[144:147], v[176:179], v[102:105]
	v_mfma_f32_16x16x32_bf16 v[94:97], v[152:155], v[176:179], v[94:97]
	v_mfma_f32_16x16x32_bf16 v[86:89], v[144:147], v[184:187], v[86:89]
	v_mfma_f32_16x16x32_bf16 v[78:81], v[152:155], v[184:187], v[78:81]
	v_mfma_f32_16x16x32_bf16 v[126:129], v[148:151], v[164:167], v[126:129]
	v_mfma_f32_16x16x32_bf16 v[122:125], v[156:159], v[164:167], v[122:125]
	v_mfma_f32_16x16x32_bf16 v[118:121], v[148:151], v[172:175], v[118:121]
	v_mfma_f32_16x16x32_bf16 v[110:113], v[156:159], v[172:175], v[110:113]
	v_mfma_f32_16x16x32_bf16 v[102:105], v[148:151], v[180:183], v[102:105]
	v_mfma_f32_16x16x32_bf16 v[94:97], v[156:159], v[180:183], v[94:97]
	v_mfma_f32_16x16x32_bf16 v[86:89], v[148:151], v[188:191], v[86:89]
	v_mfma_f32_16x16x32_bf16 v[78:81], v[156:159], v[188:191], v[78:81]
	s_barrier
	s_setprio 0
	s_mov_b32 m0, s58
	ds_read_b128 v[206:209], v253 offset:49152
	ds_read_b128 v[210:213], v253 offset:50176
	v_lshl_add_u64 v[138:139], v[138:139], 0, s[76:77]
	ds_read_b128 v[214:217], v253 offset:51200
	ds_read_b128 v[218:221], v253 offset:52224
	global_load_lds_dwordx4 v[138:139], off
	v_lshl_add_u64 v[138:139], v[192:193], 0, s[76:77]
	s_mov_b32 m0, s59
	s_nop 0
	global_load_lds_dwordx4 v[138:139], off
	s_setprio 1
	s_barrier
	s_waitcnt lgkmcnt(0)
	v_mfma_f32_16x16x32_bf16 v[114:117], v[206:209], v[160:163], v[114:117]
	v_mfma_f32_16x16x32_bf16 v[106:109], v[214:217], v[160:163], v[106:109]
	v_mfma_f32_16x16x32_bf16 v[98:101], v[206:209], v[168:171], v[98:101]
	v_mfma_f32_16x16x32_bf16 v[90:93], v[214:217], v[168:171], v[90:93]
	v_mfma_f32_16x16x32_bf16 v[82:85], v[206:209], v[176:179], v[82:85]
	v_mfma_f32_16x16x32_bf16 v[74:77], v[214:217], v[176:179], v[74:77]
	v_mfma_f32_16x16x32_bf16 v[70:73], v[206:209], v[184:187], v[70:73]
	v_mfma_f32_16x16x32_bf16 v[66:69], v[214:217], v[184:187], v[66:69]
	v_mfma_f32_16x16x32_bf16 v[114:117], v[210:213], v[164:167], v[114:117]
	v_mfma_f32_16x16x32_bf16 v[106:109], v[218:221], v[164:167], v[106:109]
	v_mfma_f32_16x16x32_bf16 v[98:101], v[210:213], v[172:175], v[98:101]
	v_mfma_f32_16x16x32_bf16 v[90:93], v[218:221], v[172:175], v[90:93]
	v_mfma_f32_16x16x32_bf16 v[82:85], v[210:213], v[180:183], v[82:85]
	v_mfma_f32_16x16x32_bf16 v[74:77], v[218:221], v[180:183], v[74:77]
	s_mov_b32 m0, s67
	v_mfma_f32_16x16x32_bf16 v[70:73], v[210:213], v[188:191], v[70:73]
	v_lshl_add_u64 v[138:139], v[222:223], 0, s[76:77]
	v_mfma_f32_16x16x32_bf16 v[66:69], v[218:221], v[188:191], v[66:69]
	s_barrier
	s_setprio 0
	ds_read_b128 v[160:163], v141 offset:49152
	ds_read_b128 v[164:167], v141 offset:50176
	ds_read_b128 v[168:171], v141 offset:51200
	ds_read_b128 v[172:175], v141 offset:52224
	ds_read_b128 v[176:179], v141 offset:53248
	ds_read_b128 v[180:183], v141 offset:54272
	ds_read_b128 v[184:187], v141 offset:55296
	ds_read_b128 v[188:191], v141 offset:56320
	global_load_lds_dwordx4 v[138:139], off
	v_lshl_add_u64 v[138:139], v[224:225], 0, s[76:77]
	s_mov_b32 m0, s70
	s_nop 0
	global_load_lds_dwordx4 v[138:139], off
	s_setprio 1
	s_barrier
	s_waitcnt lgkmcnt(0)
	v_mfma_f32_16x16x32_bf16 v[62:65], v[144:147], v[160:163], v[62:65]
	v_mfma_f32_16x16x32_bf16 v[58:61], v[152:155], v[160:163], v[58:61]
	v_mfma_f32_16x16x32_bf16 v[54:57], v[144:147], v[168:171], v[54:57]
	v_mfma_f32_16x16x32_bf16 v[46:49], v[152:155], v[168:171], v[46:49]
	v_mfma_f32_16x16x32_bf16 v[38:41], v[144:147], v[176:179], v[38:41]
	v_mfma_f32_16x16x32_bf16 v[30:33], v[152:155], v[176:179], v[30:33]
	v_mfma_f32_16x16x32_bf16 v[22:25], v[144:147], v[184:187], v[22:25]
	v_mfma_f32_16x16x32_bf16 v[14:17], v[152:155], v[184:187], v[14:17]
	v_mfma_f32_16x16x32_bf16 v[62:65], v[148:151], v[164:167], v[62:65]
	v_mfma_f32_16x16x32_bf16 v[58:61], v[156:159], v[164:167], v[58:61]
	v_mfma_f32_16x16x32_bf16 v[54:57], v[148:151], v[172:175], v[54:57]
	v_mfma_f32_16x16x32_bf16 v[46:49], v[156:159], v[172:175], v[46:49]
	v_mfma_f32_16x16x32_bf16 v[38:41], v[148:151], v[180:183], v[38:41]
	v_mfma_f32_16x16x32_bf16 v[30:33], v[156:159], v[180:183], v[30:33]
	v_mfma_f32_16x16x32_bf16 v[22:25], v[148:151], v[188:191], v[22:25]
	v_mfma_f32_16x16x32_bf16 v[14:17], v[156:159], v[188:191], v[14:17]
	s_barrier
	s_setprio 0
	s_mov_b32 m0, s71
	v_lshl_add_u64 v[138:139], s[8:9], 0, v[134:135]
	global_load_lds_dwordx4 v[138:139], off
	v_lshl_add_u64 v[138:139], s[8:9], 0, v[130:131]
	s_mov_b32 m0, s78
	s_nop 0
	global_load_lds_dwordx4 v[138:139], off
	s_waitcnt vmcnt(6)
	s_setprio 1
	s_barrier
	v_mfma_f32_16x16x32_bf16 v[50:53], v[206:209], v[160:163], v[50:53]
	v_mfma_f32_16x16x32_bf16 v[42:45], v[214:217], v[160:163], v[42:45]
	v_mfma_f32_16x16x32_bf16 v[34:37], v[206:209], v[168:171], v[34:37]
	v_mfma_f32_16x16x32_bf16 v[26:29], v[214:217], v[168:171], v[26:29]
	v_mfma_f32_16x16x32_bf16 v[18:21], v[206:209], v[176:179], v[18:21]
	v_mfma_f32_16x16x32_bf16 v[10:13], v[214:217], v[176:179], v[10:13]
	v_mfma_f32_16x16x32_bf16 v[6:9], v[206:209], v[184:187], v[6:9]
	v_mfma_f32_16x16x32_bf16 v[2:5], v[214:217], v[184:187], v[2:5]
	v_mfma_f32_16x16x32_bf16 v[50:53], v[210:213], v[164:167], v[50:53]
	v_mfma_f32_16x16x32_bf16 v[42:45], v[218:221], v[164:167], v[42:45]
	v_mfma_f32_16x16x32_bf16 v[34:37], v[210:213], v[172:175], v[34:37]
	v_mfma_f32_16x16x32_bf16 v[26:29], v[218:221], v[172:175], v[26:29]
	v_mfma_f32_16x16x32_bf16 v[18:21], v[210:213], v[180:183], v[18:21]
	v_mfma_f32_16x16x32_bf16 v[10:13], v[218:221], v[180:183], v[10:13]
	v_mfma_f32_16x16x32_bf16 v[6:9], v[210:213], v[188:191], v[6:9]
	v_mfma_f32_16x16x32_bf16 v[2:5], v[218:221], v[188:191], v[2:5]
	s_setprio 0
	s_andn2_b64 vcc, exec, s[60:61]
	s_mov_b64 s[8:9], -1
	s_mov_b64 s[60:61], 0
	s_mov_b64 s[62:63], 0x100
	s_barrier
	s_cbranch_vccz .LBB0_204
	s_cmp_gt_i32 s29, 63
	s_cbranch_scc0 .LBB0_207
	s_lshl_b32 s8, s29, 10
	s_lshl_b32 s9, s94, 8
	s_add_i32 s9, s9, s8
	v_add_u32_e32 v138, s9, v143
	v_ashrrev_i32_e32 v139, 31, v138
	v_lshlrev_b64 v[138:139], 10, v[138:139]
	s_lshl_b32 s8, s42, 8
	v_lshl_add_u64 v[138:139], s[64:65], 0, v[138:139]
	s_ashr_i32 s9, s8, 31
	v_lshl_add_u64 v[138:139], s[8:9], 1, v[138:139]
	s_mov_b64 s[8:9], 0

.LBB0_255:
	v_add_u32_e32 v253, 0x10000, v182
	ds_read_b128 v[130:133], v253
	ds_read_b128 v[134:137], v253 offset:1024
	ds_read_b128 v[138:141], v253 offset:2048
	ds_read_b128 v[142:145], v253 offset:3072
	s_add_u32 s8, s6, 0xfff00080
	s_addc_u32 s9, s7, -1
	s_cmp_eq_u32 s79, 60
	s_cselect_b32 s11, s53, s9
	s_cselect_b32 s10, s52, s8
	s_cselect_b32 s9, s61, s78
	s_cselect_b32 s8, s60, s1
	v_lshl_add_u64 v[178:179], s[6:7], 0, v[166:167]
	s_add_i32 m0, s5, 0xc000
	ds_read_b128 v[146:149], v181
	ds_read_b128 v[150:153], v181 offset:1024
	ds_read_b128 v[154:157], v181 offset:2048
	ds_read_b128 v[170:173], v181 offset:3072
	ds_read_b128 v[174:177], v181 offset:4096
	ds_read_b128 v[184:187], v181 offset:5120
	ds_read_b128 v[188:191], v181 offset:6144
	ds_read_b128 v[206:209], v181 offset:7168
	global_load_lds_dwordx4 v[178:179], off
	v_lshl_add_u64 v[178:179], s[6:7], 0, v[168:169]
	s_add_i32 m0, s5, 0xe000
	s_nop 0
	global_load_lds_dwordx4 v[178:179], off
	s_waitcnt lgkmcnt(8)
	s_setprio 1
	s_barrier
	s_waitcnt lgkmcnt(0)
	v_mfma_f32_16x16x32_bf16 v[126:129], v[130:133], v[146:149], v[126:129]
	v_mfma_f32_16x16x32_bf16 v[122:125], v[138:141], v[146:149], v[122:125]
	v_mfma_f32_16x16x32_bf16 v[110:113], v[130:133], v[154:157], v[110:113]
	v_mfma_f32_16x16x32_bf16 v[106:109], v[138:141], v[154:157], v[106:109]
	v_mfma_f32_16x16x32_bf16 v[94:97], v[130:133], v[174:177], v[94:97]
	v_mfma_f32_16x16x32_bf16 v[90:93], v[138:141], v[174:177], v[90:93]
	v_mfma_f32_16x16x32_bf16 v[78:81], v[130:133], v[188:191], v[78:81]
	v_mfma_f32_16x16x32_bf16 v[74:77], v[138:141], v[188:191], v[74:77]
	v_mfma_f32_16x16x32_bf16 v[126:129], v[134:137], v[150:153], v[126:129]
	v_mfma_f32_16x16x32_bf16 v[122:125], v[142:145], v[150:153], v[122:125]
	v_mfma_f32_16x16x32_bf16 v[110:113], v[134:137], v[170:173], v[110:113]
	v_mfma_f32_16x16x32_bf16 v[106:109], v[142:145], v[170:173], v[106:109]
	v_mfma_f32_16x16x32_bf16 v[94:97], v[134:137], v[184:187], v[94:97]
	v_mfma_f32_16x16x32_bf16 v[90:93], v[142:145], v[184:187], v[90:93]
	v_mfma_f32_16x16x32_bf16 v[78:81], v[134:137], v[206:209], v[78:81]
	v_mfma_f32_16x16x32_bf16 v[74:77], v[142:145], v[206:209], v[74:77]
	s_barrier
	s_setprio 0
	ds_read_b128 v[210:213], v253 offset:16384
	ds_read_b128 v[214:217], v253 offset:17408
	s_mov_b32 m0, s12
	ds_read_b128 v[218:221], v253 offset:18432
	ds_read_b128 v[222:225], v253 offset:19456
	v_lshl_add_u64 v[178:179], s[8:9], 0, v[162:163]
	global_load_lds_dwordx4 v[178:179], off
	v_lshl_add_u64 v[192:193], s[8:9], 0, v[158:159]
	s_mov_b32 m0, s17
	s_nop 0
	global_load_lds_dwordx4 v[192:193], off
	s_setprio 1
	s_barrier
	s_waitcnt lgkmcnt(0)
	v_mfma_f32_16x16x32_bf16 v[118:121], v[210:213], v[146:149], v[118:121]
	v_mfma_f32_16x16x32_bf16 v[114:117], v[218:221], v[146:149], v[114:117]
	v_mfma_f32_16x16x32_bf16 v[102:105], v[210:213], v[154:157], v[102:105]
	v_mfma_f32_16x16x32_bf16 v[98:101], v[218:221], v[154:157], v[98:101]
	v_mfma_f32_16x16x32_bf16 v[86:89], v[210:213], v[174:177], v[86:89]
	v_mfma_f32_16x16x32_bf16 v[82:85], v[218:221], v[174:177], v[82:85]
	v_mfma_f32_16x16x32_bf16 v[70:73], v[210:213], v[188:191], v[70:73]
	v_mfma_f32_16x16x32_bf16 v[66:69], v[218:221], v[188:191], v[66:69]
	v_mfma_f32_16x16x32_bf16 v[118:121], v[214:217], v[150:153], v[118:121]
	v_mfma_f32_16x16x32_bf16 v[114:117], v[222:225], v[150:153], v[114:117]
	v_mfma_f32_16x16x32_bf16 v[102:105], v[214:217], v[170:173], v[102:105]
	v_mfma_f32_16x16x32_bf16 v[98:101], v[222:225], v[170:173], v[98:101]
	v_mfma_f32_16x16x32_bf16 v[86:89], v[214:217], v[184:187], v[86:89]
	v_mfma_f32_16x16x32_bf16 v[82:85], v[222:225], v[184:187], v[82:85]
	s_mov_b32 m0, s5
	v_mfma_f32_16x16x32_bf16 v[70:73], v[214:217], v[206:209], v[70:73]
	v_lshl_add_u64 v[226:227], s[10:11], 0, v[164:165]
	v_mfma_f32_16x16x32_bf16 v[66:69], v[222:225], v[206:209], v[66:69]
	s_barrier
	s_setprio 0
	ds_read_b128 v[146:149], v181 offset:16384
	ds_read_b128 v[150:153], v181 offset:17408
	ds_read_b128 v[154:157], v181 offset:18432
	ds_read_b128 v[170:173], v181 offset:19456
	ds_read_b128 v[174:177], v181 offset:20480
	ds_read_b128 v[184:187], v181 offset:21504
	ds_read_b128 v[188:191], v181 offset:22528
	ds_read_b128 v[206:209], v181 offset:23552
	global_load_lds_dwordx4 v[226:227], off
	v_lshl_add_u64 v[228:229], s[10:11], 0, v[160:161]
	s_mov_b32 m0, s26
	s_nop 0
	global_load_lds_dwordx4 v[228:229], off
	s_setprio 1
	s_barrier
	s_waitcnt lgkmcnt(0)
	v_mfma_f32_16x16x32_bf16 v[62:65], v[130:133], v[146:149], v[62:65]
	v_mfma_f32_16x16x32_bf16 v[58:61], v[138:141], v[146:149], v[58:61]
	v_mfma_f32_16x16x32_bf16 v[46:49], v[130:133], v[154:157], v[46:49]
	v_mfma_f32_16x16x32_bf16 v[42:45], v[138:141], v[154:157], v[42:45]
	v_mfma_f32_16x16x32_bf16 v[30:33], v[130:133], v[174:177], v[30:33]
	v_mfma_f32_16x16x32_bf16 v[26:29], v[138:141], v[174:177], v[26:29]
	v_mfma_f32_16x16x32_bf16 v[14:17], v[130:133], v[188:191], v[14:17]
	v_mfma_f32_16x16x32_bf16 v[10:13], v[138:141], v[188:191], v[10:13]
	v_mfma_f32_16x16x32_bf16 v[62:65], v[134:137], v[150:153], v[62:65]
	v_mfma_f32_16x16x32_bf16 v[58:61], v[142:145], v[150:153], v[58:61]
	v_mfma_f32_16x16x32_bf16 v[46:49], v[134:137], v[170:173], v[46:49]
	v_mfma_f32_16x16x32_bf16 v[42:45], v[142:145], v[170:173], v[42:45]
	v_mfma_f32_16x16x32_bf16 v[30:33], v[134:137], v[184:187], v[30:33]
	v_mfma_f32_16x16x32_bf16 v[26:29], v[142:145], v[184:187], v[26:29]
	v_mfma_f32_16x16x32_bf16 v[14:17], v[134:137], v[206:209], v[14:17]
	v_mfma_f32_16x16x32_bf16 v[10:13], v[142:145], v[206:209], v[10:13]
	s_barrier
	s_setprio 0
	s_add_u32 s80, s8, 0x100000
	s_addc_u32 s81, s9, 0
	s_mov_b32 m0, s34
	v_lshl_add_u64 v[130:131], s[80:81], 0, v[162:163]
	global_load_lds_dwordx4 v[130:131], off
	v_lshl_add_u64 v[130:131], s[80:81], 0, v[158:159]
	s_mov_b32 m0, s35
	s_nop 0
	global_load_lds_dwordx4 v[130:131], off
	s_waitcnt vmcnt(6)
	s_setprio 1
	s_barrier
	v_mfma_f32_16x16x32_bf16 v[54:57], v[210:213], v[146:149], v[54:57]
	v_mfma_f32_16x16x32_bf16 v[50:53], v[218:221], v[146:149], v[50:53]
	v_mfma_f32_16x16x32_bf16 v[38:41], v[210:213], v[154:157], v[38:41]
	v_mfma_f32_16x16x32_bf16 v[34:37], v[218:221], v[154:157], v[34:37]
	v_mfma_f32_16x16x32_bf16 v[22:25], v[210:213], v[174:177], v[22:25]
	v_mfma_f32_16x16x32_bf16 v[18:21], v[218:221], v[174:177], v[18:21]
	v_mfma_f32_16x16x32_bf16 v[6:9], v[210:213], v[188:191], v[6:9]
	v_mfma_f32_16x16x32_bf16 v[2:5], v[218:221], v[188:191], v[2:5]
	v_mfma_f32_16x16x32_bf16 v[54:57], v[214:217], v[150:153], v[54:57]
	v_mfma_f32_16x16x32_bf16 v[50:53], v[222:225], v[150:153], v[50:53]
	v_mfma_f32_16x16x32_bf16 v[38:41], v[214:217], v[170:173], v[38:41]
	v_mfma_f32_16x16x32_bf16 v[34:37], v[222:225], v[170:173], v[34:37]
	v_mfma_f32_16x16x32_bf16 v[22:25], v[214:217], v[184:187], v[22:25]
	v_mfma_f32_16x16x32_bf16 v[18:21], v[222:225], v[184:187], v[18:21]
	v_mfma_f32_16x16x32_bf16 v[6:9], v[214:217], v[206:209], v[6:9]
	v_mfma_f32_16x16x32_bf16 v[2:5], v[222:225], v[206:209], v[2:5]
	s_barrier
	s_setprio 0
	ds_read_b128 v[130:133], v253 offset:32768
	ds_read_b128 v[134:137], v253 offset:33792
	ds_read_b128 v[138:141], v253 offset:34816
	ds_read_b128 v[142:145], v253 offset:35840
	s_add_u32 s10, s10, 0x100000
	s_addc_u32 s11, s11, 0
	s_mov_b32 m0, s42
	v_lshl_add_u64 v[210:211], s[10:11], 0, v[164:165]
	ds_read_b128 v[146:149], v181 offset:32768
	ds_read_b128 v[150:153], v181 offset:33792
	ds_read_b128 v[154:157], v181 offset:34816
	ds_read_b128 v[170:173], v181 offset:35840
	ds_read_b128 v[174:177], v181 offset:36864
	ds_read_b128 v[184:187], v181 offset:37888
	ds_read_b128 v[188:191], v181 offset:38912
	ds_read_b128 v[206:209], v181 offset:39936
	global_load_lds_dwordx4 v[210:211], off
	v_lshl_add_u64 v[210:211], s[10:11], 0, v[160:161]
	s_mov_b32 m0, s54
	s_nop 0
	global_load_lds_dwordx4 v[210:211], off
	s_waitcnt lgkmcnt(8)
	s_setprio 1
	s_barrier
	s_waitcnt lgkmcnt(0)
	v_mfma_f32_16x16x32_bf16 v[126:129], v[130:133], v[146:149], v[126:129]
	v_mfma_f32_16x16x32_bf16 v[122:125], v[138:141], v[146:149], v[122:125]
	v_mfma_f32_16x16x32_bf16 v[110:113], v[130:133], v[154:157], v[110:113]
	v_mfma_f32_16x16x32_bf16 v[106:109], v[138:141], v[154:157], v[106:109]
	v_mfma_f32_16x16x32_bf16 v[94:97], v[130:133], v[174:177], v[94:97]
	v_mfma_f32_16x16x32_bf16 v[90:93], v[138:141], v[174:177], v[90:93]
	v_mfma_f32_16x16x32_bf16 v[78:81], v[130:133], v[188:191], v[78:81]
	v_mfma_f32_16x16x32_bf16 v[74:77], v[138:141], v[188:191], v[74:77]
	v_mfma_f32_16x16x32_bf16 v[126:129], v[134:137], v[150:153], v[126:129]
	v_mfma_f32_16x16x32_bf16 v[122:125], v[142:145], v[150:153], v[122:125]
	v_mfma_f32_16x16x32_bf16 v[110:113], v[134:137], v[170:173], v[110:113]
	v_mfma_f32_16x16x32_bf16 v[106:109], v[142:145], v[170:173], v[106:109]
	v_mfma_f32_16x16x32_bf16 v[94:97], v[134:137], v[184:187], v[94:97]
	v_mfma_f32_16x16x32_bf16 v[90:93], v[142:145], v[184:187], v[90:93]
	v_mfma_f32_16x16x32_bf16 v[78:81], v[134:137], v[206:209], v[78:81]
	v_mfma_f32_16x16x32_bf16 v[74:77], v[142:145], v[206:209], v[74:77]
	s_barrier
	s_setprio 0
	s_mov_b32 m0, s55
	ds_read_b128 v[210:213], v253 offset:49152
	ds_read_b128 v[214:217], v253 offset:50176
	v_lshl_add_u64 v[178:179], v[178:179], 0, s[76:77]
	ds_read_b128 v[218:221], v253 offset:51200
	ds_read_b128 v[222:225], v253 offset:52224
	global_load_lds_dwordx4 v[178:179], off
	v_lshl_add_u64 v[178:179], v[192:193], 0, s[76:77]
	s_mov_b32 m0, s56
	s_nop 0
	global_load_lds_dwordx4 v[178:179], off
	s_setprio 1
	s_barrier
	s_waitcnt lgkmcnt(0)
	v_mfma_f32_16x16x32_bf16 v[118:121], v[210:213], v[146:149], v[118:121]
	v_mfma_f32_16x16x32_bf16 v[114:117], v[218:221], v[146:149], v[114:117]
	v_mfma_f32_16x16x32_bf16 v[102:105], v[210:213], v[154:157], v[102:105]
	v_mfma_f32_16x16x32_bf16 v[98:101], v[218:221], v[154:157], v[98:101]
	v_mfma_f32_16x16x32_bf16 v[86:89], v[210:213], v[174:177], v[86:89]
	v_mfma_f32_16x16x32_bf16 v[82:85], v[218:221], v[174:177], v[82:85]
	v_mfma_f32_16x16x32_bf16 v[70:73], v[210:213], v[188:191], v[70:73]
	v_mfma_f32_16x16x32_bf16 v[66:69], v[218:221], v[188:191], v[66:69]
	v_mfma_f32_16x16x32_bf16 v[118:121], v[214:217], v[150:153], v[118:121]
	v_mfma_f32_16x16x32_bf16 v[114:117], v[222:225], v[150:153], v[114:117]
	v_mfma_f32_16x16x32_bf16 v[102:105], v[214:217], v[170:173], v[102:105]
	v_mfma_f32_16x16x32_bf16 v[98:101], v[222:225], v[170:173], v[98:101]
	v_mfma_f32_16x16x32_bf16 v[86:89], v[214:217], v[184:187], v[86:89]
	v_mfma_f32_16x16x32_bf16 v[82:85], v[222:225], v[184:187], v[82:85]
	s_mov_b32 m0, s57
	v_mfma_f32_16x16x32_bf16 v[70:73], v[214:217], v[206:209], v[70:73]
	v_lshl_add_u64 v[178:179], v[226:227], 0, s[76:77]
	v_mfma_f32_16x16x32_bf16 v[66:69], v[222:225], v[206:209], v[66:69]
	s_barrier
	s_setprio 0
	ds_read_b128 v[146:149], v181 offset:49152
	ds_read_b128 v[150:153], v181 offset:50176
	ds_read_b128 v[154:157], v181 offset:51200
	ds_read_b128 v[170:173], v181 offset:52224
	ds_read_b128 v[174:177], v181 offset:53248
	ds_read_b128 v[184:187], v181 offset:54272
	ds_read_b128 v[188:191], v181 offset:55296
	ds_read_b128 v[206:209], v181 offset:56320
	global_load_lds_dwordx4 v[178:179], off
	v_lshl_add_u64 v[178:179], v[228:229], 0, s[76:77]
	s_mov_b32 m0, s58
	s_nop 0
	global_load_lds_dwordx4 v[178:179], off
	s_setprio 1
	s_barrier
	s_waitcnt lgkmcnt(0)
	v_mfma_f32_16x16x32_bf16 v[62:65], v[130:133], v[146:149], v[62:65]
	v_mfma_f32_16x16x32_bf16 v[58:61], v[138:141], v[146:149], v[58:61]
	v_mfma_f32_16x16x32_bf16 v[46:49], v[130:133], v[154:157], v[46:49]
	v_mfma_f32_16x16x32_bf16 v[42:45], v[138:141], v[154:157], v[42:45]
	v_mfma_f32_16x16x32_bf16 v[30:33], v[130:133], v[174:177], v[30:33]
	v_mfma_f32_16x16x32_bf16 v[26:29], v[138:141], v[174:177], v[26:29]
	v_mfma_f32_16x16x32_bf16 v[14:17], v[130:133], v[188:191], v[14:17]
	v_mfma_f32_16x16x32_bf16 v[10:13], v[138:141], v[188:191], v[10:13]
	v_mfma_f32_16x16x32_bf16 v[62:65], v[134:137], v[150:153], v[62:65]
	v_mfma_f32_16x16x32_bf16 v[58:61], v[142:145], v[150:153], v[58:61]
	v_mfma_f32_16x16x32_bf16 v[46:49], v[134:137], v[170:173], v[46:49]
	v_mfma_f32_16x16x32_bf16 v[42:45], v[142:145], v[170:173], v[42:45]
	v_mfma_f32_16x16x32_bf16 v[30:33], v[134:137], v[184:187], v[30:33]
	v_mfma_f32_16x16x32_bf16 v[26:29], v[142:145], v[184:187], v[26:29]
	v_mfma_f32_16x16x32_bf16 v[14:17], v[134:137], v[206:209], v[14:17]
	v_mfma_f32_16x16x32_bf16 v[10:13], v[142:145], v[206:209], v[10:13]
	s_barrier
	s_setprio 0
	s_add_u32 s8, s8, 0x100080
	s_addc_u32 s9, s9, 0
	s_mov_b32 m0, s59
	v_lshl_add_u64 v[130:131], s[8:9], 0, v[162:163]
	global_load_lds_dwordx4 v[130:131], off
	v_lshl_add_u64 v[130:131], s[8:9], 0, v[158:159]
	s_mov_b32 m0, s67
	s_nop 0
	global_load_lds_dwordx4 v[130:131], off
	s_waitcnt vmcnt(6)
	s_setprio 1
	s_barrier
	v_mfma_f32_16x16x32_bf16 v[54:57], v[210:213], v[146:149], v[54:57]
	v_mfma_f32_16x16x32_bf16 v[50:53], v[218:221], v[146:149], v[50:53]
	v_mfma_f32_16x16x32_bf16 v[38:41], v[210:213], v[154:157], v[38:41]
	v_mfma_f32_16x16x32_bf16 v[34:37], v[218:221], v[154:157], v[34:37]
	v_mfma_f32_16x16x32_bf16 v[22:25], v[210:213], v[174:177], v[22:25]
	v_mfma_f32_16x16x32_bf16 v[18:21], v[218:221], v[174:177], v[18:21]
	v_mfma_f32_16x16x32_bf16 v[6:9], v[210:213], v[188:191], v[6:9]
	v_mfma_f32_16x16x32_bf16 v[2:5], v[218:221], v[188:191], v[2:5]
	v_mfma_f32_16x16x32_bf16 v[54:57], v[214:217], v[150:153], v[54:57]
	v_mfma_f32_16x16x32_bf16 v[50:53], v[222:225], v[150:153], v[50:53]
	v_mfma_f32_16x16x32_bf16 v[38:41], v[214:217], v[170:173], v[38:41]
	v_mfma_f32_16x16x32_bf16 v[34:37], v[222:225], v[170:173], v[34:37]
	v_mfma_f32_16x16x32_bf16 v[22:25], v[214:217], v[184:187], v[22:25]
	v_mfma_f32_16x16x32_bf16 v[18:21], v[222:225], v[184:187], v[18:21]
	v_mfma_f32_16x16x32_bf16 v[6:9], v[214:217], v[206:209], v[6:9]
	v_mfma_f32_16x16x32_bf16 v[2:5], v[222:225], v[206:209], v[2:5]
	s_setprio 0
	s_add_i32 s79, s79, 2
	s_add_u32 s6, s6, 0x100
	s_addc_u32 s7, s7, 0
	s_add_u32 s1, s1, 0x100
	s_addc_u32 s78, s78, 0
	s_cmp_gt_u32 s79, 61
	s_barrier
	s_cbranch_scc0 .LBB0_255
	s_lshl_b32 s1, s28, 9
	s_and_b32 s1, s1, 0xfffff800
	s_lshl_b32 s6, s29, 8
	s_add_i32 s1, s1, s6
	v_add_u32_e32 v172, s1, v180
	s_lshl_b32 s1, s28, 8
	s_and_b32 s1, s1, 0x300
	v_or_b32_e32 v132, s1, v183
	v_mov_b64_e32 v[170:171], s[50:51]
	v_mad_i64_i32 v[130:131], s[6:7], v172, s37, v[170:171]
	v_lshlrev_b32_e32 v194, 1, v132
	v_lshl_add_u64 v[130:131], v[130:131], 0, v[194:195]
	v_lshl_add_u64 v[132:133], v[130:131], 0, s[84:85]
	v_add_co_u32_e32 v130, vcc, s16, v130
	v_or_b32_e32 v178, 16, v172
	s_nop 0
	v_addc_co_u32_e32 v131, vcc, 0, v131, vcc
	global_load_dwordx4 v[184:187], v[130:131], off offset:2048
	global_load_dwordx4 v[154:157], v[132:133], off offset:256
	v_mad_i64_i32 v[130:131], s[6:7], v178, s37, v[170:171]
	v_lshl_add_u64 v[130:131], v[130:131], 0, v[194:195]
	v_lshl_add_u64 v[132:133], v[130:131], 0, s[84:85]
	v_add_co_u32_e32 v130, vcc, s16, v130
	v_or_b32_e32 v176, 32, v172
	s_nop 0
	v_addc_co_u32_e32 v131, vcc, 0, v131, vcc
	global_load_dwordx4 v[150:153], v[130:131], off offset:2048
	global_load_dwordx4 v[146:149], v[132:133], off offset:256
	v_mad_i64_i32 v[130:131], s[6:7], v176, s37, v[170:171]
	v_lshl_add_u64 v[130:131], v[130:131], 0, v[194:195]
	v_lshl_add_u64 v[132:133], v[130:131], 0, s[84:85]
	v_add_co_u32_e32 v130, vcc, s16, v130
	v_or_b32_e32 v174, 48, v172
	s_nop 0
	v_addc_co_u32_e32 v131, vcc, 0, v131, vcc
	global_load_dwordx4 v[142:145], v[130:131], off offset:2048
	global_load_dwordx4 v[138:141], v[132:133], off offset:256
	v_mad_i64_i32 v[130:131], s[6:7], v174, s37, v[170:171]
	v_lshl_add_u64 v[130:131], v[130:131], 0, v[194:195]
	v_lshl_add_u64 v[132:133], v[130:131], 0, s[84:85]
	v_add_co_u32_e32 v130, vcc, s16, v130
	v_pk_mul_f32 v[126:127], v[126:127], s[72:73] op_sel_hi:[1,0]
	s_nop 0
	v_addc_co_u32_e32 v131, vcc, 0, v131, vcc
	global_load_dwordx4 v[134:137], v[130:131], off offset:2048
	s_nop 0
	global_load_dwordx4 v[130:133], v[132:133], off offset:256
	v_pk_mul_f32 v[190:191], v[124:125], s[72:73] op_sel_hi:[1,0]
	v_pk_mul_f32 v[128:129], v[128:129], s[72:73] op_sel_hi:[1,0]
	v_pk_mul_f32 v[122:123], v[122:123], s[72:73] op_sel_hi:[1,0]
	v_ashrrev_i32_e32 v173, 31, v172
	v_lshlrev_b64 v[188:189], 11, v[172:173]
	v_pk_mul_f32 v[118:119], v[118:119], s[72:73] op_sel_hi:[1,0]
	v_pk_mul_f32 v[120:121], v[120:121], s[72:73] op_sel_hi:[1,0]
	v_pk_mul_f32 v[110:111], v[110:111], s[72:73] op_sel_hi:[1,0]
	v_pk_mul_f32 v[112:113], v[112:113], s[72:73] op_sel_hi:[1,0]
	v_ashrrev_i32_e32 v179, 31, v178
	v_pk_mul_f32 v[102:103], v[102:103], s[72:73] op_sel_hi:[1,0]
	v_pk_mul_f32 v[104:105], v[104:105], s[72:73] op_sel_hi:[1,0]
	v_pk_mul_f32 v[94:95], v[94:95], s[72:73] op_sel_hi:[1,0]
	v_pk_mul_f32 v[96:97], v[96:97], s[72:73] op_sel_hi:[1,0]
	v_ashrrev_i32_e32 v177, 31, v176
	v_pk_mul_f32 v[86:87], v[86:87], s[72:73] op_sel_hi:[1,0]
	v_pk_mul_f32 v[88:89], v[88:89], s[72:73] op_sel_hi:[1,0]
	v_pk_mul_f32 v[78:79], v[78:79], s[72:73] op_sel_hi:[1,0]
	v_pk_mul_f32 v[80:81], v[80:81], s[72:73] op_sel_hi:[1,0]
	v_ashrrev_i32_e32 v175, 31, v174
	v_pk_mul_f32 v[70:71], v[70:71], s[72:73] op_sel_hi:[1,0]
	v_pk_mul_f32 v[72:73], v[72:73], s[72:73] op_sel_hi:[1,0]
	s_waitcnt vmcnt(0)
	v_lshlrev_b32_e32 v124, 16, v184
	v_and_b32_e32 v125, 0xffff0000, v184
	v_mul_f32_e32 v124, v126, v124
	v_mul_f32_e32 v125, v127, v125
	v_cvt_pk_bf16_f32 v124, v124, v125
	v_lshlrev_b32_e32 v125, 16, v185
	v_and_b32_e32 v126, 0xffff0000, v185
	v_mul_f32_e32 v125, v128, v125
	v_mul_f32_e32 v126, v129, v126
	v_cvt_pk_bf16_f32 v125, v125, v126
	v_lshlrev_b32_e32 v126, 16, v186
	v_mul_f32_e32 v122, v122, v126
	v_and_b32_e32 v126, 0xffff0000, v186
	v_mul_f32_e32 v123, v123, v126
	v_cvt_pk_bf16_f32 v126, v122, v123
	v_lshlrev_b32_e32 v122, 16, v187
	v_and_b32_e32 v123, 0xffff0000, v187
	v_mul_f32_e32 v122, v190, v122
	v_mul_f32_e32 v123, v191, v123
	v_cvt_pk_bf16_f32 v127, v122, v123
	v_lshl_add_u64 v[122:123], s[74:75], 0, v[188:189]
	v_lshl_add_u64 v[122:123], v[122:123], 0, v[194:195]
	global_store_dwordx4 v[122:123], v[124:127], off
	s_nop 1
	v_pk_mul_f32 v[124:125], v[116:117], s[72:73] op_sel_hi:[1,0]
	v_pk_mul_f32 v[116:117], v[114:115], s[72:73] op_sel_hi:[1,0]
	v_lshlrev_b32_e32 v114, 16, v154
	v_and_b32_e32 v115, 0xffff0000, v154
	v_mul_f32_e32 v114, v118, v114
	v_mul_f32_e32 v115, v119, v115
	v_cvt_pk_bf16_f32 v114, v114, v115
	v_lshlrev_b32_e32 v115, 16, v155
	v_and_b32_e32 v118, 0xffff0000, v155
	v_mul_f32_e32 v115, v120, v115
	v_mul_f32_e32 v118, v121, v118
	v_cvt_pk_bf16_f32 v115, v115, v118
	v_lshlrev_b32_e32 v118, 16, v156
	v_mul_f32_e32 v116, v116, v118
	v_and_b32_e32 v118, 0xffff0000, v156
	v_mul_f32_e32 v117, v117, v118
	v_cvt_pk_bf16_f32 v116, v116, v117
	v_lshlrev_b32_e32 v117, 16, v157
	v_mul_f32_e32 v117, v124, v117
	v_and_b32_e32 v118, 0xffff0000, v157
	v_mul_f32_e32 v118, v125, v118
	v_cvt_pk_bf16_f32 v117, v117, v118
	global_store_dwordx4 v[122:123], v[114:117], off offset:256
	s_nop 1
	v_pk_mul_f32 v[116:117], v[108:109], s[72:73] op_sel_hi:[1,0]
	v_pk_mul_f32 v[108:109], v[106:107], s[72:73] op_sel_hi:[1,0]
	v_lshlrev_b32_e32 v106, 16, v150
	v_and_b32_e32 v107, 0xffff0000, v150
	v_mul_f32_e32 v106, v110, v106
	v_mul_f32_e32 v107, v111, v107
	v_cvt_pk_bf16_f32 v106, v106, v107
	v_lshlrev_b32_e32 v107, 16, v151
	v_and_b32_e32 v110, 0xffff0000, v151
	v_mul_f32_e32 v107, v112, v107
	v_mul_f32_e32 v110, v113, v110
	v_cvt_pk_bf16_f32 v107, v107, v110
	v_lshlrev_b32_e32 v110, 16, v152
	v_mul_f32_e32 v108, v108, v110
	v_and_b32_e32 v110, 0xffff0000, v152
	v_mul_f32_e32 v109, v109, v110
	v_cvt_pk_bf16_f32 v108, v108, v109
	v_lshlrev_b32_e32 v109, 16, v153
	v_and_b32_e32 v110, 0xffff0000, v153
	v_lshlrev_b64 v[114:115], 11, v[178:179]
	v_mul_f32_e32 v109, v116, v109
	v_mul_f32_e32 v110, v117, v110
	v_cvt_pk_bf16_f32 v109, v109, v110
	v_lshl_add_u64 v[110:111], s[74:75], 0, v[114:115]
	v_lshl_add_u64 v[110:111], v[110:111], 0, v[194:195]
	global_store_dwordx4 v[110:111], v[106:109], off
	s_nop 1
	v_pk_mul_f32 v[106:107], v[100:101], s[72:73] op_sel_hi:[1,0]
	v_pk_mul_f32 v[100:101], v[98:99], s[72:73] op_sel_hi:[1,0]
	v_lshlrev_b32_e32 v98, 16, v146
	v_and_b32_e32 v99, 0xffff0000, v146
	v_mul_f32_e32 v98, v102, v98
	v_mul_f32_e32 v99, v103, v99
	v_cvt_pk_bf16_f32 v98, v98, v99
	v_lshlrev_b32_e32 v99, 16, v147
	v_and_b32_e32 v102, 0xffff0000, v147
	v_mul_f32_e32 v99, v104, v99
	v_mul_f32_e32 v102, v105, v102
	v_cvt_pk_bf16_f32 v99, v99, v102
	v_lshlrev_b32_e32 v102, 16, v148
	v_mul_f32_e32 v100, v100, v102
	v_and_b32_e32 v102, 0xffff0000, v148
	v_mul_f32_e32 v101, v101, v102
	v_cvt_pk_bf16_f32 v100, v100, v101
	v_lshlrev_b32_e32 v101, 16, v149
	v_mul_f32_e32 v101, v106, v101
	v_and_b32_e32 v102, 0xffff0000, v149
	v_mul_f32_e32 v102, v107, v102
	v_cvt_pk_bf16_f32 v101, v101, v102
	global_store_dwordx4 v[110:111], v[98:101], off offset:256
	s_nop 1
	v_pk_mul_f32 v[100:101], v[92:93], s[72:73] op_sel_hi:[1,0]
	v_pk_mul_f32 v[92:93], v[90:91], s[72:73] op_sel_hi:[1,0]
	v_lshlrev_b32_e32 v90, 16, v142
	v_and_b32_e32 v91, 0xffff0000, v142
	v_mul_f32_e32 v90, v94, v90
	v_mul_f32_e32 v91, v95, v91
	v_cvt_pk_bf16_f32 v90, v90, v91
	v_lshlrev_b32_e32 v91, 16, v143
	v_and_b32_e32 v94, 0xffff0000, v143
	v_mul_f32_e32 v91, v96, v91
	v_mul_f32_e32 v94, v97, v94
	v_cvt_pk_bf16_f32 v91, v91, v94
	v_lshlrev_b32_e32 v94, 16, v144
	v_mul_f32_e32 v92, v92, v94
	v_and_b32_e32 v94, 0xffff0000, v144
	v_mul_f32_e32 v93, v93, v94
	v_cvt_pk_bf16_f32 v92, v92, v93
	v_lshlrev_b32_e32 v93, 16, v145
	v_and_b32_e32 v94, 0xffff0000, v145
	v_lshlrev_b64 v[98:99], 11, v[176:177]
	v_mul_f32_e32 v93, v100, v93
	v_mul_f32_e32 v94, v101, v94
	v_cvt_pk_bf16_f32 v93, v93, v94
	v_lshl_add_u64 v[94:95], s[74:75], 0, v[98:99]
	v_lshl_add_u64 v[94:95], v[94:95], 0, v[194:195]
	global_store_dwordx4 v[94:95], v[90:93], off
	s_nop 1
	v_pk_mul_f32 v[90:91], v[84:85], s[72:73] op_sel_hi:[1,0]
	v_pk_mul_f32 v[84:85], v[82:83], s[72:73] op_sel_hi:[1,0]
	v_lshlrev_b32_e32 v82, 16, v138
	v_and_b32_e32 v83, 0xffff0000, v138
	v_mul_f32_e32 v82, v86, v82
	v_mul_f32_e32 v83, v87, v83
	v_cvt_pk_bf16_f32 v82, v82, v83
	v_lshlrev_b32_e32 v83, 16, v139
	v_and_b32_e32 v86, 0xffff0000, v139
	v_mul_f32_e32 v83, v88, v83
	v_mul_f32_e32 v86, v89, v86
	v_cvt_pk_bf16_f32 v83, v83, v86
	v_lshlrev_b32_e32 v86, 16, v140
	v_mul_f32_e32 v84, v84, v86
	v_and_b32_e32 v86, 0xffff0000, v140
	v_mul_f32_e32 v85, v85, v86
	v_cvt_pk_bf16_f32 v84, v84, v85
	v_lshlrev_b32_e32 v85, 16, v141
	v_mul_f32_e32 v85, v90, v85
	v_and_b32_e32 v86, 0xffff0000, v141
	v_mul_f32_e32 v86, v91, v86
	v_cvt_pk_bf16_f32 v85, v85, v86
	global_store_dwordx4 v[94:95], v[82:85], off offset:256
	s_nop 1
	v_pk_mul_f32 v[84:85], v[76:77], s[72:73] op_sel_hi:[1,0]
	v_pk_mul_f32 v[76:77], v[74:75], s[72:73] op_sel_hi:[1,0]
	v_lshlrev_b32_e32 v74, 16, v134
	v_and_b32_e32 v75, 0xffff0000, v134
	v_mul_f32_e32 v74, v78, v74
	v_mul_f32_e32 v75, v79, v75
	v_cvt_pk_bf16_f32 v74, v74, v75
	v_lshlrev_b32_e32 v75, 16, v135
	v_and_b32_e32 v78, 0xffff0000, v135
	v_mul_f32_e32 v75, v80, v75
	v_mul_f32_e32 v78, v81, v78
	v_cvt_pk_bf16_f32 v75, v75, v78
	v_lshlrev_b32_e32 v78, 16, v136
	v_mul_f32_e32 v76, v76, v78
	v_and_b32_e32 v78, 0xffff0000, v136
	v_mul_f32_e32 v77, v77, v78
	v_cvt_pk_bf16_f32 v76, v76, v77
	v_lshlrev_b32_e32 v77, 16, v137
	v_and_b32_e32 v78, 0xffff0000, v137
	v_lshlrev_b64 v[82:83], 11, v[174:175]
	v_mul_f32_e32 v77, v84, v77
	v_mul_f32_e32 v78, v85, v78
	v_cvt_pk_bf16_f32 v77, v77, v78
	v_lshl_add_u64 v[78:79], s[74:75], 0, v[82:83]
	v_lshl_add_u64 v[78:79], v[78:79], 0, v[194:195]
	global_store_dwordx4 v[78:79], v[74:77], off
	s_nop 1
	v_pk_mul_f32 v[74:75], v[68:69], s[72:73] op_sel_hi:[1,0]
	v_pk_mul_f32 v[68:69], v[66:67], s[72:73] op_sel_hi:[1,0]
	v_lshlrev_b32_e32 v66, 16, v130
	v_and_b32_e32 v67, 0xffff0000, v130
	v_mul_f32_e32 v66, v70, v66
	v_mul_f32_e32 v67, v71, v67
	v_cvt_pk_bf16_f32 v66, v66, v67
	v_lshlrev_b32_e32 v67, 16, v131
	v_and_b32_e32 v70, 0xffff0000, v131
	v_mul_f32_e32 v67, v72, v67
	v_mul_f32_e32 v70, v73, v70
	v_cvt_pk_bf16_f32 v67, v67, v70
	v_lshlrev_b32_e32 v70, 16, v132
	v_mul_f32_e32 v68, v68, v70
	v_and_b32_e32 v70, 0xffff0000, v132
	v_mul_f32_e32 v69, v69, v70
	v_cvt_pk_bf16_f32 v68, v68, v69
	v_lshlrev_b32_e32 v69, 16, v133
	v_mul_f32_e32 v69, v74, v69
	v_and_b32_e32 v70, 0xffff0000, v133
	v_mul_f32_e32 v70, v75, v70
	v_cvt_pk_bf16_f32 v69, v69, v70
	global_store_dwordx4 v[78:79], v[66:69], off offset:256
	v_add_u32_e32 v78, 0x80, v172
	s_nop 0
	v_mad_i64_i32 v[66:67], s[6:7], v78, s37, v[170:171]
	v_lshl_add_u64 v[66:67], v[66:67], 0, v[194:195]
	v_add_co_u32_e32 v68, vcc, s16, v66
	v_add_u32_e32 v86, 0x90, v172
	s_nop 0
	v_addc_co_u32_e32 v69, vcc, 0, v67, vcc
	global_load_dwordx4 v[70:73], v[68:69], off offset:2048
	v_lshl_add_u64 v[66:67], v[66:67], 0, s[84:85]
	global_load_dwordx4 v[74:77], v[66:67], off offset:256
	v_pk_mul_f32 v[96:97], v[56:57], s[72:73] op_sel_hi:[1,0]
	v_mad_i64_i32 v[56:57], s[6:7], v86, s37, v[170:171]
	v_lshl_add_u64 v[56:57], v[56:57], 0, v[194:195]
	v_pk_mul_f32 v[94:95], v[58:59], s[72:73] op_sel_hi:[1,0]
	v_add_co_u32_e32 v58, vcc, s16, v56
	v_pk_mul_f32 v[92:93], v[60:61], s[72:73] op_sel_hi:[1,0]
	s_nop 0
	v_addc_co_u32_e32 v59, vcc, 0, v57, vcc
	global_load_dwordx4 v[58:61], v[58:59], off offset:2048
	v_add_u32_e32 v68, 0xa0, v172
	v_pk_mul_f32 v[102:103], v[50:51], s[72:73] op_sel_hi:[1,0]
	v_mad_i64_i32 v[50:51], s[6:7], v68, s37, v[170:171]
	v_add_u32_e32 v66, 0xb0, v172
	v_lshl_add_u64 v[50:51], v[50:51], 0, v[194:195]
	v_pk_mul_f32 v[100:101], v[52:53], s[72:73] op_sel_hi:[1,0]
	v_mad_i64_i32 v[52:53], s[6:7], v66, s37, v[170:171]
	v_lshl_add_u64 v[82:83], v[50:51], 0, s[84:85]
	v_add_co_u32_e32 v50, vcc, s16, v50
	v_lshl_add_u64 v[52:53], v[52:53], 0, v[194:195]
	s_nop 0
	v_addc_co_u32_e32 v51, vcc, 0, v51, vcc
	v_ashrrev_i32_e32 v79, 31, v78
	v_lshl_add_u64 v[104:105], v[52:53], 0, s[84:85]
	v_add_co_u32_e32 v52, vcc, s16, v52
	v_pk_mul_f32 v[98:99], v[54:55], s[72:73] op_sel_hi:[1,0]
	v_lshlrev_b64 v[54:55], 11, v[78:79]
	v_lshl_add_u64 v[56:57], v[56:57], 0, s[84:85]
	v_addc_co_u32_e32 v53, vcc, 0, v53, vcc
	v_pk_mul_f32 v[88:89], v[64:65], s[72:73] op_sel_hi:[1,0]
	v_pk_mul_f32 v[90:91], v[62:63], s[72:73] op_sel_hi:[1,0]
	v_lshl_add_u64 v[106:107], s[74:75], 0, v[54:55]
	global_load_dwordx4 v[62:65], v[56:57], off offset:256
	global_load_dwordx4 v[78:81], v[50:51], off offset:2048
	s_nop 0
	global_load_dwordx4 v[82:85], v[82:83], off offset:256
	s_nop 0
	global_load_dwordx4 v[54:57], v[52:53], off offset:2048
	s_nop 0
	global_load_dwordx4 v[50:53], v[104:105], off offset:256
	v_lshl_add_u64 v[104:105], v[106:107], 0, v[194:195]
	v_pk_mul_f32 v[46:47], v[46:47], s[72:73] op_sel_hi:[1,0]
	v_pk_mul_f32 v[48:49], v[48:49], s[72:73] op_sel_hi:[1,0]
	v_ashrrev_i32_e32 v87, 31, v86
	v_pk_mul_f32 v[38:39], v[38:39], s[72:73] op_sel_hi:[1,0]
	v_pk_mul_f32 v[40:41], v[40:41], s[72:73] op_sel_hi:[1,0]
	v_pk_mul_f32 v[30:31], v[30:31], s[72:73] op_sel_hi:[1,0]
	v_pk_mul_f32 v[32:33], v[32:33], s[72:73] op_sel_hi:[1,0]
	v_ashrrev_i32_e32 v69, 31, v68
	v_pk_mul_f32 v[22:23], v[22:23], s[72:73] op_sel_hi:[1,0]
	v_pk_mul_f32 v[24:25], v[24:25], s[72:73] op_sel_hi:[1,0]
	v_pk_mul_f32 v[14:15], v[14:15], s[72:73] op_sel_hi:[1,0]
	v_pk_mul_f32 v[16:17], v[16:17], s[72:73] op_sel_hi:[1,0]
	v_ashrrev_i32_e32 v67, 31, v66
	v_pk_mul_f32 v[6:7], v[6:7], s[72:73] op_sel_hi:[1,0]
	v_pk_mul_f32 v[8:9], v[8:9], s[72:73] op_sel_hi:[1,0]
	s_waitcnt vmcnt(0)
	v_lshlrev_b32_e32 v106, 16, v70
	v_and_b32_e32 v70, 0xffff0000, v70
	v_lshlrev_b32_e32 v107, 16, v71
	v_and_b32_e32 v71, 0xffff0000, v71
	v_lshlrev_b32_e32 v108, 16, v72
	v_and_b32_e32 v72, 0xffff0000, v72
	v_lshlrev_b32_e32 v109, 16, v73
	v_and_b32_e32 v73, 0xffff0000, v73
	v_mul_f32_e32 v70, v91, v70
	v_mul_f32_e32 v71, v89, v71
	v_mul_f32_e32 v72, v95, v72
	v_mul_f32_e32 v73, v93, v73
	v_mul_f32_e32 v90, v90, v106
	v_mul_f32_e32 v88, v88, v107
	v_mul_f32_e32 v89, v94, v108
	v_mul_f32_e32 v91, v92, v109
	v_cvt_pk_bf16_f32 v70, v90, v70
	v_cvt_pk_bf16_f32 v71, v88, v71
	v_cvt_pk_bf16_f32 v72, v89, v72
	v_cvt_pk_bf16_f32 v73, v91, v73
	v_lshlrev_b32_e32 v111, 16, v75
	v_and_b32_e32 v75, 0xffff0000, v75
	global_store_dwordx4 v[104:105], v[70:73], off
	v_lshlrev_b32_e32 v110, 16, v74
	v_and_b32_e32 v74, 0xffff0000, v74
	v_lshlrev_b32_e32 v72, 16, v76
	v_and_b32_e32 v73, 0xffff0000, v76
	v_mul_f32_e32 v71, v97, v75
	v_mul_f32_e32 v72, v102, v72
	v_mul_f32_e32 v73, v103, v73
	v_mul_f32_e32 v92, v98, v110
	v_mul_f32_e32 v74, v99, v74
	v_mul_f32_e32 v93, v96, v111
	v_cvt_pk_bf16_f32 v70, v92, v74
	v_cvt_pk_bf16_f32 v71, v93, v71
	v_cvt_pk_bf16_f32 v72, v72, v73
	v_lshlrev_b32_e32 v73, 16, v77
	v_mul_f32_e32 v73, v100, v73
	v_and_b32_e32 v74, 0xffff0000, v77
	v_mul_f32_e32 v74, v101, v74
	v_cvt_pk_bf16_f32 v73, v73, v74
	global_store_dwordx4 v[104:105], v[70:73], off offset:256
	s_nop 1
	v_pk_mul_f32 v[72:73], v[44:45], s[72:73] op_sel_hi:[1,0]
	v_pk_mul_f32 v[44:45], v[42:43], s[72:73] op_sel_hi:[1,0]
	v_lshlrev_b32_e32 v42, 16, v58
	v_and_b32_e32 v43, 0xffff0000, v58
	v_mul_f32_e32 v42, v46, v42
	v_mul_f32_e32 v43, v47, v43
	v_cvt_pk_bf16_f32 v42, v42, v43
	v_lshlrev_b32_e32 v43, 16, v59
	v_and_b32_e32 v46, 0xffff0000, v59
	v_mul_f32_e32 v43, v48, v43
	v_mul_f32_e32 v46, v49, v46
	v_cvt_pk_bf16_f32 v43, v43, v46
	v_lshlrev_b32_e32 v46, 16, v60
	v_mul_f32_e32 v44, v44, v46
	v_and_b32_e32 v46, 0xffff0000, v60
	v_mul_f32_e32 v45, v45, v46
	v_cvt_pk_bf16_f32 v44, v44, v45
	v_lshlrev_b32_e32 v45, 16, v61
	v_and_b32_e32 v46, 0xffff0000, v61
	v_lshlrev_b64 v[70:71], 11, v[86:87]
	v_mul_f32_e32 v45, v72, v45
	v_mul_f32_e32 v46, v73, v46
	v_cvt_pk_bf16_f32 v45, v45, v46
	v_lshl_add_u64 v[46:47], s[74:75], 0, v[70:71]
	v_lshl_add_u64 v[46:47], v[46:47], 0, v[194:195]
	global_store_dwordx4 v[46:47], v[42:45], off
	s_nop 1
	v_pk_mul_f32 v[42:43], v[36:37], s[72:73] op_sel_hi:[1,0]
	v_pk_mul_f32 v[36:37], v[34:35], s[72:73] op_sel_hi:[1,0]
	v_lshlrev_b32_e32 v34, 16, v62
	v_and_b32_e32 v35, 0xffff0000, v62
	v_mul_f32_e32 v34, v38, v34
	v_mul_f32_e32 v35, v39, v35
	v_cvt_pk_bf16_f32 v34, v34, v35
	v_lshlrev_b32_e32 v35, 16, v63
	v_and_b32_e32 v38, 0xffff0000, v63
	v_mul_f32_e32 v35, v40, v35
	v_mul_f32_e32 v38, v41, v38
	v_cvt_pk_bf16_f32 v35, v35, v38
	v_lshlrev_b32_e32 v38, 16, v64
	v_mul_f32_e32 v36, v36, v38
	v_and_b32_e32 v38, 0xffff0000, v64
	v_mul_f32_e32 v37, v37, v38
	v_cvt_pk_bf16_f32 v36, v36, v37
	v_lshlrev_b32_e32 v37, 16, v65
	v_mul_f32_e32 v37, v42, v37
	v_and_b32_e32 v38, 0xffff0000, v65
	v_mul_f32_e32 v38, v43, v38
	v_cvt_pk_bf16_f32 v37, v37, v38
	global_store_dwordx4 v[46:47], v[34:37], off offset:256
	s_nop 1
	v_pk_mul_f32 v[36:37], v[28:29], s[72:73] op_sel_hi:[1,0]
	v_pk_mul_f32 v[28:29], v[26:27], s[72:73] op_sel_hi:[1,0]
	v_lshlrev_b32_e32 v26, 16, v78
	v_and_b32_e32 v27, 0xffff0000, v78
	v_mul_f32_e32 v26, v30, v26
	v_mul_f32_e32 v27, v31, v27
	v_cvt_pk_bf16_f32 v26, v26, v27
	v_lshlrev_b32_e32 v27, 16, v79
	v_and_b32_e32 v30, 0xffff0000, v79
	v_mul_f32_e32 v27, v32, v27
	v_mul_f32_e32 v30, v33, v30
	v_cvt_pk_bf16_f32 v27, v27, v30
	v_lshlrev_b32_e32 v30, 16, v80
	v_mul_f32_e32 v28, v28, v30
	v_and_b32_e32 v30, 0xffff0000, v80
	v_mul_f32_e32 v29, v29, v30
	v_cvt_pk_bf16_f32 v28, v28, v29
	v_lshlrev_b32_e32 v29, 16, v81
	v_and_b32_e32 v30, 0xffff0000, v81
	v_lshlrev_b64 v[34:35], 11, v[68:69]
	v_mul_f32_e32 v29, v36, v29
	v_mul_f32_e32 v30, v37, v30
	v_cvt_pk_bf16_f32 v29, v29, v30
	v_lshl_add_u64 v[30:31], s[74:75], 0, v[34:35]
	v_lshl_add_u64 v[30:31], v[30:31], 0, v[194:195]
	global_store_dwordx4 v[30:31], v[26:29], off
	s_nop 1
	v_pk_mul_f32 v[26:27], v[20:21], s[72:73] op_sel_hi:[1,0]
	v_pk_mul_f32 v[20:21], v[18:19], s[72:73] op_sel_hi:[1,0]
	v_lshlrev_b32_e32 v18, 16, v82
	v_and_b32_e32 v19, 0xffff0000, v82
	v_mul_f32_e32 v18, v22, v18
	v_mul_f32_e32 v19, v23, v19
	v_cvt_pk_bf16_f32 v18, v18, v19
	v_lshlrev_b32_e32 v19, 16, v83
	v_and_b32_e32 v22, 0xffff0000, v83
	v_mul_f32_e32 v19, v24, v19
	v_mul_f32_e32 v22, v25, v22
	v_cvt_pk_bf16_f32 v19, v19, v22
	v_lshlrev_b32_e32 v22, 16, v84
	v_mul_f32_e32 v20, v20, v22
	v_and_b32_e32 v22, 0xffff0000, v84
	v_mul_f32_e32 v21, v21, v22
	v_cvt_pk_bf16_f32 v20, v20, v21
	v_lshlrev_b32_e32 v21, 16, v85
	v_mul_f32_e32 v21, v26, v21
	v_and_b32_e32 v22, 0xffff0000, v85
	v_mul_f32_e32 v22, v27, v22
	v_cvt_pk_bf16_f32 v21, v21, v22
	global_store_dwordx4 v[30:31], v[18:21], off offset:256
	s_nop 1
	v_pk_mul_f32 v[20:21], v[12:13], s[72:73] op_sel_hi:[1,0]
	v_pk_mul_f32 v[12:13], v[10:11], s[72:73] op_sel_hi:[1,0]
	v_lshlrev_b32_e32 v10, 16, v54
	v_and_b32_e32 v11, 0xffff0000, v54
	v_mul_f32_e32 v10, v14, v10
	v_mul_f32_e32 v11, v15, v11
	v_cvt_pk_bf16_f32 v10, v10, v11
	v_lshlrev_b32_e32 v11, 16, v55
	v_and_b32_e32 v14, 0xffff0000, v55
	v_mul_f32_e32 v11, v16, v11
	v_mul_f32_e32 v14, v17, v14
	v_cvt_pk_bf16_f32 v11, v11, v14
	v_lshlrev_b32_e32 v14, 16, v56
	v_mul_f32_e32 v12, v12, v14
	v_and_b32_e32 v14, 0xffff0000, v56
	v_mul_f32_e32 v13, v13, v14
	v_cvt_pk_bf16_f32 v12, v12, v13
	v_lshlrev_b32_e32 v13, 16, v57
	v_and_b32_e32 v14, 0xffff0000, v57
	v_lshlrev_b64 v[18:19], 11, v[66:67]
	v_mul_f32_e32 v13, v20, v13
	v_mul_f32_e32 v14, v21, v14
	v_cvt_pk_bf16_f32 v13, v13, v14
	v_lshl_add_u64 v[14:15], s[74:75], 0, v[18:19]
	v_lshl_add_u64 v[14:15], v[14:15], 0, v[194:195]
	global_store_dwordx4 v[14:15], v[10:13], off
	s_nop 1
	v_pk_mul_f32 v[10:11], v[4:5], s[72:73] op_sel_hi:[1,0]
	v_pk_mul_f32 v[4:5], v[2:3], s[72:73] op_sel_hi:[1,0]
	v_lshlrev_b32_e32 v2, 16, v50
	v_and_b32_e32 v3, 0xffff0000, v50
	v_mul_f32_e32 v2, v6, v2
	v_mul_f32_e32 v3, v7, v3
	v_cvt_pk_bf16_f32 v2, v2, v3
	v_lshlrev_b32_e32 v3, 16, v51
	v_and_b32_e32 v6, 0xffff0000, v51
	v_mul_f32_e32 v3, v8, v3
	v_mul_f32_e32 v6, v9, v6
	v_cvt_pk_bf16_f32 v3, v3, v6
	v_lshlrev_b32_e32 v6, 16, v52
	v_mul_f32_e32 v4, v4, v6
	v_and_b32_e32 v6, 0xffff0000, v52
	v_mul_f32_e32 v5, v5, v6
	v_cvt_pk_bf16_f32 v4, v4, v5
	v_lshlrev_b32_e32 v5, 16, v53
	v_mul_f32_e32 v5, v10, v5
	v_and_b32_e32 v6, 0xffff0000, v53
	v_mul_f32_e32 v6, v11, v6
	v_cvt_pk_bf16_f32 v5, v5, v6
	global_store_dwordx4 v[14:15], v[2:5], off offset:256
	s_and_b64 vcc, exec, s[62:63]
	s_mov_b32 s29, s71
	s_mov_b32 s28, s0
	s_mov_b64 s[8:9], s[60:61]
	s_mov_b64 s[6:7], s[52:53]
	s_cbranch_vccz .LBB0_252
	s_waitcnt vmcnt(0)
	v_readlane_b32 s28, v250, 12
	s_cmpk_gt_u32 s4, 0xff
	v_readlane_b32 s29, v250, 13
	s_mov_b32 s70, 0x800000
	s_cbranch_scc1 .LBB0_259
	s_barrier

.LBB0_266:
	s_add_u32 s8, s6, 0x100
	s_addc_u32 s9, s7, 0
	v_add_u32_e32 v253, 0x10000, v147
	s_add_u32 s10, s71, s6
	ds_read_b128 v[142:145], v253
	ds_read_b128 v[150:153], v253 offset:1024
	ds_read_b128 v[154:157], v253 offset:2048
	ds_read_b128 v[158:161], v253 offset:3072
	s_addc_u32 s11, s78, s7
	s_cmp_eq_u32 s79, 4
	s_cselect_b32 s81, 0, s8
	s_cselect_b32 s80, 0, s9
	s_cselect_b32 s54, s29, s10
	s_cselect_b32 s55, s5, s11
	s_add_u32 s10, s18, s81
	s_addc_u32 s11, s19, s80
	v_lshl_add_u64 v[206:207], v[138:139], 0, s[6:7]
	s_add_i32 m0, s17, 0xc000
	ds_read_b128 v[162:165], v146
	ds_read_b128 v[166:169], v146 offset:1024
	ds_read_b128 v[170:173], v146 offset:2048
	ds_read_b128 v[174:177], v146 offset:3072
	ds_read_b128 v[178:181], v146 offset:4096
	ds_read_b128 v[182:185], v146 offset:5120
	ds_read_b128 v[186:189], v146 offset:6144
	ds_read_b128 v[190:193], v146 offset:7168
	global_load_lds_dwordx4 v[206:207], off
	v_lshl_add_u64 v[206:207], v[140:141], 0, s[6:7]
	s_add_i32 m0, s17, 0xe000
	s_nop 0
	global_load_lds_dwordx4 v[206:207], off
	s_waitcnt lgkmcnt(8)
	s_setprio 1
	s_barrier
	s_waitcnt lgkmcnt(0)
	v_mfma_f32_16x16x32_bf16 v[126:129], v[142:145], v[162:165], v[126:129]
	v_mfma_f32_16x16x32_bf16 v[122:125], v[154:157], v[162:165], v[122:125]
	v_mfma_f32_16x16x32_bf16 v[110:113], v[142:145], v[170:173], v[110:113]
	v_mfma_f32_16x16x32_bf16 v[106:109], v[154:157], v[170:173], v[106:109]
	v_mfma_f32_16x16x32_bf16 v[94:97], v[142:145], v[178:181], v[94:97]
	v_mfma_f32_16x16x32_bf16 v[90:93], v[154:157], v[178:181], v[90:93]
	v_mfma_f32_16x16x32_bf16 v[78:81], v[142:145], v[186:189], v[78:81]
	v_mfma_f32_16x16x32_bf16 v[74:77], v[154:157], v[186:189], v[74:77]
	v_mfma_f32_16x16x32_bf16 v[126:129], v[150:153], v[166:169], v[126:129]
	v_mfma_f32_16x16x32_bf16 v[122:125], v[158:161], v[166:169], v[122:125]
	v_mfma_f32_16x16x32_bf16 v[110:113], v[150:153], v[174:177], v[110:113]
	v_mfma_f32_16x16x32_bf16 v[106:109], v[158:161], v[174:177], v[106:109]
	v_mfma_f32_16x16x32_bf16 v[94:97], v[150:153], v[182:185], v[94:97]
	v_mfma_f32_16x16x32_bf16 v[90:93], v[158:161], v[182:185], v[90:93]
	v_mfma_f32_16x16x32_bf16 v[78:81], v[150:153], v[190:193], v[78:81]
	v_mfma_f32_16x16x32_bf16 v[74:77], v[158:161], v[190:193], v[74:77]
	s_barrier
	s_setprio 0
	s_mov_b32 m0, s26
	ds_read_b128 v[206:209], v253 offset:16384
	ds_read_b128 v[210:213], v253 offset:17408
	v_lshl_add_u64 v[222:223], s[54:55], 0, v[134:135]
	ds_read_b128 v[214:217], v253 offset:18432
	ds_read_b128 v[218:221], v253 offset:19456
	global_load_lds_dwordx4 v[222:223], off
	v_lshl_add_u64 v[224:225], s[54:55], 0, v[130:131]
	s_mov_b32 m0, s34
	s_nop 0
	global_load_lds_dwordx4 v[224:225], off
	s_setprio 1
	s_barrier
	s_waitcnt lgkmcnt(0)
	v_mfma_f32_16x16x32_bf16 v[118:121], v[206:209], v[162:165], v[118:121]
	v_mfma_f32_16x16x32_bf16 v[114:117], v[214:217], v[162:165], v[114:117]
	v_mfma_f32_16x16x32_bf16 v[102:105], v[206:209], v[170:173], v[102:105]
	v_mfma_f32_16x16x32_bf16 v[98:101], v[214:217], v[170:173], v[98:101]
	v_mfma_f32_16x16x32_bf16 v[86:89], v[206:209], v[178:181], v[86:89]
	v_mfma_f32_16x16x32_bf16 v[82:85], v[214:217], v[178:181], v[82:85]
	v_mfma_f32_16x16x32_bf16 v[70:73], v[206:209], v[186:189], v[70:73]
	v_mfma_f32_16x16x32_bf16 v[66:69], v[214:217], v[186:189], v[66:69]
	v_mfma_f32_16x16x32_bf16 v[118:121], v[210:213], v[166:169], v[118:121]
	v_mfma_f32_16x16x32_bf16 v[114:117], v[218:221], v[166:169], v[114:117]
	v_mfma_f32_16x16x32_bf16 v[102:105], v[210:213], v[174:177], v[102:105]
	v_mfma_f32_16x16x32_bf16 v[98:101], v[218:221], v[174:177], v[98:101]
	v_mfma_f32_16x16x32_bf16 v[86:89], v[210:213], v[182:185], v[86:89]
	v_mfma_f32_16x16x32_bf16 v[82:85], v[218:221], v[182:185], v[82:85]
	s_mov_b32 m0, s17
	v_mfma_f32_16x16x32_bf16 v[70:73], v[210:213], v[190:193], v[70:73]
	v_lshl_add_u64 v[226:227], s[10:11], 0, v[136:137]
	v_mfma_f32_16x16x32_bf16 v[66:69], v[218:221], v[190:193], v[66:69]
	s_barrier
	s_setprio 0
	ds_read_b128 v[162:165], v146 offset:16384
	ds_read_b128 v[166:169], v146 offset:17408
	ds_read_b128 v[170:173], v146 offset:18432
	ds_read_b128 v[174:177], v146 offset:19456
	ds_read_b128 v[178:181], v146 offset:20480
	ds_read_b128 v[182:185], v146 offset:21504
	ds_read_b128 v[186:189], v146 offset:22528
	ds_read_b128 v[190:193], v146 offset:23552
	global_load_lds_dwordx4 v[226:227], off
	v_lshl_add_u64 v[228:229], s[10:11], 0, v[132:133]
	s_mov_b32 m0, s35
	s_nop 0
	global_load_lds_dwordx4 v[228:229], off
	s_setprio 1
	s_barrier
	s_waitcnt lgkmcnt(0)
	v_mfma_f32_16x16x32_bf16 v[62:65], v[142:145], v[162:165], v[62:65]
	v_mfma_f32_16x16x32_bf16 v[58:61], v[154:157], v[162:165], v[58:61]
	v_mfma_f32_16x16x32_bf16 v[46:49], v[142:145], v[170:173], v[46:49]
	v_mfma_f32_16x16x32_bf16 v[42:45], v[154:157], v[170:173], v[42:45]
	v_mfma_f32_16x16x32_bf16 v[30:33], v[142:145], v[178:181], v[30:33]
	v_mfma_f32_16x16x32_bf16 v[26:29], v[154:157], v[178:181], v[26:29]
	v_mfma_f32_16x16x32_bf16 v[14:17], v[142:145], v[186:189], v[14:17]
	v_mfma_f32_16x16x32_bf16 v[10:13], v[154:157], v[186:189], v[10:13]
	v_mfma_f32_16x16x32_bf16 v[62:65], v[150:153], v[166:169], v[62:65]
	v_mfma_f32_16x16x32_bf16 v[58:61], v[158:161], v[166:169], v[58:61]
	v_mfma_f32_16x16x32_bf16 v[46:49], v[150:153], v[174:177], v[46:49]
	v_mfma_f32_16x16x32_bf16 v[42:45], v[158:161], v[174:177], v[42:45]
	v_mfma_f32_16x16x32_bf16 v[30:33], v[150:153], v[182:185], v[30:33]
	v_mfma_f32_16x16x32_bf16 v[26:29], v[158:161], v[182:185], v[26:29]
	v_mfma_f32_16x16x32_bf16 v[14:17], v[150:153], v[190:193], v[14:17]
	v_mfma_f32_16x16x32_bf16 v[10:13], v[158:161], v[190:193], v[10:13]
	s_barrier
	s_setprio 0
	s_add_u32 s6, s54, 0x20000
	s_addc_u32 s7, s55, 0
	s_mov_b32 m0, s42
	v_lshl_add_u64 v[142:143], s[6:7], 0, v[134:135]
	global_load_lds_dwordx4 v[142:143], off
	v_lshl_add_u64 v[142:143], s[6:7], 0, v[130:131]
	s_mov_b32 m0, s56
	s_nop 0
	global_load_lds_dwordx4 v[142:143], off
	s_waitcnt vmcnt(6)
	s_setprio 1
	s_barrier
	v_mfma_f32_16x16x32_bf16 v[54:57], v[206:209], v[162:165], v[54:57]
	v_mfma_f32_16x16x32_bf16 v[50:53], v[214:217], v[162:165], v[50:53]
	v_mfma_f32_16x16x32_bf16 v[38:41], v[206:209], v[170:173], v[38:41]
	v_mfma_f32_16x16x32_bf16 v[34:37], v[214:217], v[170:173], v[34:37]
	v_mfma_f32_16x16x32_bf16 v[22:25], v[206:209], v[178:181], v[22:25]
	v_mfma_f32_16x16x32_bf16 v[18:21], v[214:217], v[178:181], v[18:21]
	v_mfma_f32_16x16x32_bf16 v[6:9], v[206:209], v[186:189], v[6:9]
	v_mfma_f32_16x16x32_bf16 v[2:5], v[214:217], v[186:189], v[2:5]
	v_mfma_f32_16x16x32_bf16 v[54:57], v[210:213], v[166:169], v[54:57]
	v_mfma_f32_16x16x32_bf16 v[50:53], v[218:221], v[166:169], v[50:53]
	v_mfma_f32_16x16x32_bf16 v[38:41], v[210:213], v[174:177], v[38:41]
	v_mfma_f32_16x16x32_bf16 v[34:37], v[218:221], v[174:177], v[34:37]
	v_mfma_f32_16x16x32_bf16 v[22:25], v[210:213], v[182:185], v[22:25]
	v_mfma_f32_16x16x32_bf16 v[18:21], v[218:221], v[182:185], v[18:21]
	v_mfma_f32_16x16x32_bf16 v[6:9], v[210:213], v[190:193], v[6:9]
	v_mfma_f32_16x16x32_bf16 v[2:5], v[218:221], v[190:193], v[2:5]
	s_barrier
	s_setprio 0
	ds_read_b128 v[142:145], v253 offset:32768
	ds_read_b128 v[150:153], v253 offset:33792
	ds_read_b128 v[154:157], v253 offset:34816
	ds_read_b128 v[158:161], v253 offset:35840
	s_add_u32 s6, s10, 0x20000
	s_addc_u32 s7, s11, 0
	s_mov_b32 m0, s57
	v_lshl_add_u64 v[206:207], s[6:7], 0, v[136:137]
	ds_read_b128 v[162:165], v146 offset:32768
	ds_read_b128 v[166:169], v146 offset:33792
	ds_read_b128 v[170:173], v146 offset:34816
	ds_read_b128 v[174:177], v146 offset:35840
	ds_read_b128 v[178:181], v146 offset:36864
	ds_read_b128 v[182:185], v146 offset:37888
	ds_read_b128 v[186:189], v146 offset:38912
	ds_read_b128 v[190:193], v146 offset:39936
	global_load_lds_dwordx4 v[206:207], off
	v_lshl_add_u64 v[206:207], s[6:7], 0, v[132:133]
	s_mov_b32 m0, s58
	s_nop 0
	global_load_lds_dwordx4 v[206:207], off
	s_waitcnt lgkmcnt(8)
	s_setprio 1
	s_barrier
	s_waitcnt lgkmcnt(0)
	v_mfma_f32_16x16x32_bf16 v[126:129], v[142:145], v[162:165], v[126:129]
	v_mfma_f32_16x16x32_bf16 v[122:125], v[154:157], v[162:165], v[122:125]
	v_mfma_f32_16x16x32_bf16 v[110:113], v[142:145], v[170:173], v[110:113]
	v_mfma_f32_16x16x32_bf16 v[106:109], v[154:157], v[170:173], v[106:109]
	v_mfma_f32_16x16x32_bf16 v[94:97], v[142:145], v[178:181], v[94:97]
	v_mfma_f32_16x16x32_bf16 v[90:93], v[154:157], v[178:181], v[90:93]
	v_mfma_f32_16x16x32_bf16 v[78:81], v[142:145], v[186:189], v[78:81]
	v_mfma_f32_16x16x32_bf16 v[74:77], v[154:157], v[186:189], v[74:77]
	v_mfma_f32_16x16x32_bf16 v[126:129], v[150:153], v[166:169], v[126:129]
	v_mfma_f32_16x16x32_bf16 v[122:125], v[158:161], v[166:169], v[122:125]
	v_mfma_f32_16x16x32_bf16 v[110:113], v[150:153], v[174:177], v[110:113]
	v_mfma_f32_16x16x32_bf16 v[106:109], v[158:161], v[174:177], v[106:109]
	v_mfma_f32_16x16x32_bf16 v[94:97], v[150:153], v[182:185], v[94:97]
	v_mfma_f32_16x16x32_bf16 v[90:93], v[158:161], v[182:185], v[90:93]
	v_mfma_f32_16x16x32_bf16 v[78:81], v[150:153], v[190:193], v[78:81]
	v_mfma_f32_16x16x32_bf16 v[74:77], v[158:161], v[190:193], v[74:77]
	s_barrier
	s_setprio 0
	s_mov_b32 m0, s59
	ds_read_b128 v[206:209], v253 offset:49152
	ds_read_b128 v[210:213], v253 offset:50176
	v_lshl_add_u64 v[222:223], v[222:223], 0, s[76:77]
	ds_read_b128 v[214:217], v253 offset:51200
	ds_read_b128 v[218:221], v253 offset:52224
	global_load_lds_dwordx4 v[222:223], off
	v_lshl_add_u64 v[222:223], v[224:225], 0, s[76:77]
	s_mov_b32 m0, s60
	s_nop 0
	global_load_lds_dwordx4 v[222:223], off
	s_setprio 1
	s_barrier
	s_waitcnt lgkmcnt(0)
	v_mfma_f32_16x16x32_bf16 v[118:121], v[206:209], v[162:165], v[118:121]
	v_mfma_f32_16x16x32_bf16 v[114:117], v[214:217], v[162:165], v[114:117]
	v_mfma_f32_16x16x32_bf16 v[102:105], v[206:209], v[170:173], v[102:105]
	v_mfma_f32_16x16x32_bf16 v[98:101], v[214:217], v[170:173], v[98:101]
	v_mfma_f32_16x16x32_bf16 v[86:89], v[206:209], v[178:181], v[86:89]
	v_mfma_f32_16x16x32_bf16 v[82:85], v[214:217], v[178:181], v[82:85]
	v_mfma_f32_16x16x32_bf16 v[70:73], v[206:209], v[186:189], v[70:73]
	v_mfma_f32_16x16x32_bf16 v[66:69], v[214:217], v[186:189], v[66:69]
	v_mfma_f32_16x16x32_bf16 v[118:121], v[210:213], v[166:169], v[118:121]
	v_mfma_f32_16x16x32_bf16 v[114:117], v[218:221], v[166:169], v[114:117]
	v_mfma_f32_16x16x32_bf16 v[102:105], v[210:213], v[174:177], v[102:105]
	v_mfma_f32_16x16x32_bf16 v[98:101], v[218:221], v[174:177], v[98:101]
	v_mfma_f32_16x16x32_bf16 v[86:89], v[210:213], v[182:185], v[86:89]
	v_mfma_f32_16x16x32_bf16 v[82:85], v[218:221], v[182:185], v[82:85]
	s_mov_b32 m0, s61
	v_mfma_f32_16x16x32_bf16 v[70:73], v[210:213], v[190:193], v[70:73]
	v_lshl_add_u64 v[222:223], v[226:227], 0, s[76:77]
	v_mfma_f32_16x16x32_bf16 v[66:69], v[218:221], v[190:193], v[66:69]
	s_barrier
	s_setprio 0
	ds_read_b128 v[162:165], v146 offset:49152
	ds_read_b128 v[166:169], v146 offset:50176
	ds_read_b128 v[170:173], v146 offset:51200
	ds_read_b128 v[174:177], v146 offset:52224
	ds_read_b128 v[178:181], v146 offset:53248
	ds_read_b128 v[182:185], v146 offset:54272
	ds_read_b128 v[186:189], v146 offset:55296
	ds_read_b128 v[190:193], v146 offset:56320
	global_load_lds_dwordx4 v[222:223], off
	v_lshl_add_u64 v[222:223], v[228:229], 0, s[76:77]
	s_mov_b32 m0, s62
	s_nop 0
	global_load_lds_dwordx4 v[222:223], off
	s_setprio 1
	s_barrier
	s_waitcnt lgkmcnt(0)
	v_mfma_f32_16x16x32_bf16 v[62:65], v[142:145], v[162:165], v[62:65]
	v_mfma_f32_16x16x32_bf16 v[58:61], v[154:157], v[162:165], v[58:61]
	v_mfma_f32_16x16x32_bf16 v[46:49], v[142:145], v[170:173], v[46:49]
	v_mfma_f32_16x16x32_bf16 v[42:45], v[154:157], v[170:173], v[42:45]
	v_mfma_f32_16x16x32_bf16 v[30:33], v[142:145], v[178:181], v[30:33]
	v_mfma_f32_16x16x32_bf16 v[26:29], v[154:157], v[178:181], v[26:29]
	v_mfma_f32_16x16x32_bf16 v[14:17], v[142:145], v[186:189], v[14:17]
	v_mfma_f32_16x16x32_bf16 v[10:13], v[154:157], v[186:189], v[10:13]
	v_mfma_f32_16x16x32_bf16 v[62:65], v[150:153], v[166:169], v[62:65]
	v_mfma_f32_16x16x32_bf16 v[58:61], v[158:161], v[166:169], v[58:61]
	v_mfma_f32_16x16x32_bf16 v[46:49], v[150:153], v[174:177], v[46:49]
	v_mfma_f32_16x16x32_bf16 v[42:45], v[158:161], v[174:177], v[42:45]
	v_mfma_f32_16x16x32_bf16 v[30:33], v[150:153], v[182:185], v[30:33]
	v_mfma_f32_16x16x32_bf16 v[26:29], v[158:161], v[182:185], v[26:29]
	v_mfma_f32_16x16x32_bf16 v[14:17], v[150:153], v[190:193], v[14:17]
	v_mfma_f32_16x16x32_bf16 v[10:13], v[158:161], v[190:193], v[10:13]
	s_barrier
	s_setprio 0
	s_add_u32 s6, s54, 0x20080
	s_addc_u32 s7, s55, 0
	s_mov_b32 m0, s63
	v_lshl_add_u64 v[142:143], s[6:7], 0, v[134:135]
	global_load_lds_dwordx4 v[142:143], off
	v_lshl_add_u64 v[142:143], s[6:7], 0, v[130:131]
	s_mov_b32 m0, s67
	s_nop 0
	global_load_lds_dwordx4 v[142:143], off
	s_waitcnt vmcnt(6)
	s_setprio 1
	s_barrier
	v_mfma_f32_16x16x32_bf16 v[54:57], v[206:209], v[162:165], v[54:57]
	v_mfma_f32_16x16x32_bf16 v[50:53], v[214:217], v[162:165], v[50:53]
	v_mfma_f32_16x16x32_bf16 v[38:41], v[206:209], v[170:173], v[38:41]
	v_mfma_f32_16x16x32_bf16 v[34:37], v[214:217], v[170:173], v[34:37]
	v_mfma_f32_16x16x32_bf16 v[22:25], v[206:209], v[178:181], v[22:25]
	v_mfma_f32_16x16x32_bf16 v[18:21], v[214:217], v[178:181], v[18:21]
	v_mfma_f32_16x16x32_bf16 v[6:9], v[206:209], v[186:189], v[6:9]
	v_mfma_f32_16x16x32_bf16 v[2:5], v[214:217], v[186:189], v[2:5]
	v_mfma_f32_16x16x32_bf16 v[54:57], v[210:213], v[166:169], v[54:57]
	v_mfma_f32_16x16x32_bf16 v[50:53], v[218:221], v[166:169], v[50:53]
	v_mfma_f32_16x16x32_bf16 v[38:41], v[210:213], v[174:177], v[38:41]
	v_mfma_f32_16x16x32_bf16 v[34:37], v[218:221], v[174:177], v[34:37]
	v_mfma_f32_16x16x32_bf16 v[22:25], v[210:213], v[182:185], v[22:25]
	v_mfma_f32_16x16x32_bf16 v[18:21], v[218:221], v[182:185], v[18:21]
	v_mfma_f32_16x16x32_bf16 v[6:9], v[210:213], v[190:193], v[6:9]
	v_mfma_f32_16x16x32_bf16 v[2:5], v[218:221], v[190:193], v[2:5]
	s_setprio 0
	s_add_i32 s79, s79, 2
	s_cmp_gt_u32 s79, 5
	s_mov_b64 s[6:7], s[8:9]
	s_barrier
	s_cbranch_scc0 .LBB0_266
	s_lshl_b32 s5, s28, 6
	s_and_b32 s5, s5, 0xffffff00
	v_add_u32_e32 v144, s5, v148
	s_lshl_b32 s5, s28, 8
	s_and_b32 s5, s5, 0x300
	v_or_b32_e32 v145, s5, v149
	v_mov_b64_e32 v[142:143], s[50:51]
	v_mad_i64_i32 v[150:151], s[6:7], v144, s37, v[142:143]
	v_lshlrev_b32_e32 v194, 1, v145
	v_lshl_add_u64 v[154:155], v[150:151], 0, v[194:195]
	v_add_co_u32_e32 v150, vcc, 0x1000, v154
	v_or_b32_e32 v184, 16, v144
	s_nop 0
	v_addc_co_u32_e32 v151, vcc, 0, v155, vcc
	global_load_dwordx4 v[150:153], v[150:151], off offset:2048
	v_lshl_add_u64 v[154:155], v[154:155], 0, s[84:85]
	global_load_dwordx4 v[154:157], v[154:155], off offset:256
	v_pk_mul_f32 v[182:183], v[114:115], s[36:37] op_sel_hi:[1,0]
	v_mad_i64_i32 v[114:115], s[6:7], v184, s37, v[142:143]
	v_lshl_add_u64 v[114:115], v[114:115], 0, v[194:195]
	v_pk_mul_f32 v[180:181], v[116:117], s[36:37] op_sel_hi:[1,0]
	v_add_co_u32_e32 v116, vcc, 0x1000, v114
	v_pk_mul_f32 v[170:171], v[126:127], s[36:37] op_sel_hi:[1,0]
	s_nop 0
	v_addc_co_u32_e32 v117, vcc, 0, v115, vcc
	v_pk_mul_f32 v[172:173], v[124:125], s[36:37] op_sel_hi:[1,0]
	global_load_dwordx4 v[124:127], v[116:117], off offset:2048
	v_lshl_add_u64 v[114:115], v[114:115], 0, s[84:85]
	global_load_dwordx4 v[158:161], v[114:115], off offset:256
	v_or_b32_e32 v186, 32, v144
	v_mad_i64_i32 v[116:117], s[6:7], v186, s37, v[142:143]
	v_lshl_add_u64 v[116:117], v[116:117], 0, v[194:195]
	v_lshl_add_u64 v[166:167], v[116:117], 0, s[84:85]
	v_add_co_u32_e32 v116, vcc, 0x1000, v116
	v_pk_mul_f32 v[174:175], v[122:123], s[36:37] op_sel_hi:[1,0]
	s_nop 0
	v_addc_co_u32_e32 v117, vcc, 0, v117, vcc
	global_load_dwordx4 v[162:165], v[116:117], off offset:2048
	s_nop 0
	global_load_dwordx4 v[166:169], v[166:167], off offset:256
	v_or_b32_e32 v122, 48, v144
	v_pk_mul_f32 v[178:179], v[118:119], s[36:37] op_sel_hi:[1,0]
	v_mad_i64_i32 v[118:119], s[6:7], v122, s37, v[142:143]
	v_ashrrev_i32_e32 v145, 31, v144
	v_lshl_add_u64 v[118:119], v[118:119], 0, v[194:195]
	v_pk_mul_f32 v[176:177], v[120:121], s[36:37] op_sel_hi:[1,0]
	v_lshlrev_b64 v[120:121], 11, v[144:145]
	v_add_co_u32_e32 v114, vcc, 0x1000, v118
	v_lshl_add_u64 v[120:121], s[74:75], 0, v[120:121]
	s_nop 0
	v_addc_co_u32_e32 v115, vcc, 0, v119, vcc
	v_lshl_add_u64 v[188:189], v[118:119], 0, s[84:85]
	v_lshl_add_u64 v[190:191], v[120:121], 0, v[194:195]
	global_load_dwordx4 v[118:121], v[114:115], off offset:2048
	s_nop 0
	global_load_dwordx4 v[114:117], v[188:189], off offset:256
	v_pk_mul_f32 v[128:129], v[128:129], s[36:37] op_sel_hi:[1,0]
	v_pk_mul_f32 v[110:111], v[110:111], s[36:37] op_sel_hi:[1,0]
	v_pk_mul_f32 v[112:113], v[112:113], s[36:37] op_sel_hi:[1,0]
	v_ashrrev_i32_e32 v185, 31, v184
	v_pk_mul_f32 v[102:103], v[102:103], s[36:37] op_sel_hi:[1,0]
	v_pk_mul_f32 v[104:105], v[104:105], s[36:37] op_sel_hi:[1,0]
	v_pk_mul_f32 v[94:95], v[94:95], s[36:37] op_sel_hi:[1,0]
	v_pk_mul_f32 v[96:97], v[96:97], s[36:37] op_sel_hi:[1,0]
	v_ashrrev_i32_e32 v187, 31, v186
	v_pk_mul_f32 v[86:87], v[86:87], s[36:37] op_sel_hi:[1,0]
	v_pk_mul_f32 v[88:89], v[88:89], s[36:37] op_sel_hi:[1,0]
	v_pk_mul_f32 v[78:79], v[78:79], s[36:37] op_sel_hi:[1,0]
	v_pk_mul_f32 v[80:81], v[80:81], s[36:37] op_sel_hi:[1,0]
	v_ashrrev_i32_e32 v123, 31, v122
	v_pk_mul_f32 v[70:71], v[70:71], s[36:37] op_sel_hi:[1,0]
	v_pk_mul_f32 v[72:73], v[72:73], s[36:37] op_sel_hi:[1,0]
	s_waitcnt vmcnt(0)
	v_lshlrev_b32_e32 v145, 16, v150
	v_and_b32_e32 v150, 0xffff0000, v150
	v_lshlrev_b32_e32 v188, 16, v151
	v_and_b32_e32 v151, 0xffff0000, v151
	v_mul_f32_e32 v150, v171, v150
	v_mul_f32_e32 v128, v128, v188
	v_mul_f32_e32 v129, v129, v151
	v_lshlrev_b32_e32 v189, 16, v152
	v_and_b32_e32 v152, 0xffff0000, v152
	v_lshlrev_b32_e32 v192, 16, v153
	v_and_b32_e32 v153, 0xffff0000, v153
	v_mul_f32_e32 v145, v170, v145
	v_cvt_pk_bf16_f32 v150, v145, v150
	v_cvt_pk_bf16_f32 v151, v128, v129
	v_lshlrev_b32_e32 v128, 16, v154
	v_and_b32_e32 v129, 0xffff0000, v154
	v_mul_f32_e32 v152, v175, v152
	v_mul_f32_e32 v153, v173, v153
	v_mul_f32_e32 v128, v178, v128
	v_mul_f32_e32 v129, v179, v129
	v_mul_f32_e32 v170, v174, v189
	v_mul_f32_e32 v171, v172, v192
	v_cvt_pk_bf16_f32 v152, v170, v152
	v_cvt_pk_bf16_f32 v153, v171, v153
	global_store_dwordx4 v[190:191], v[150:153], off
	s_nop 1
	v_cvt_pk_bf16_f32 v150, v128, v129
	v_lshlrev_b32_e32 v128, 16, v155
	v_and_b32_e32 v129, 0xffff0000, v155
	v_mul_f32_e32 v128, v176, v128
	v_mul_f32_e32 v129, v177, v129
	v_cvt_pk_bf16_f32 v151, v128, v129
	v_lshlrev_b32_e32 v128, 16, v156
	v_and_b32_e32 v129, 0xffff0000, v156
	v_mul_f32_e32 v128, v182, v128
	v_mul_f32_e32 v129, v183, v129
	v_cvt_pk_bf16_f32 v152, v128, v129
	v_lshlrev_b32_e32 v128, 16, v157
	v_and_b32_e32 v129, 0xffff0000, v157
	v_mul_f32_e32 v128, v180, v128
	v_mul_f32_e32 v129, v181, v129
	v_cvt_pk_bf16_f32 v153, v128, v129
	global_store_dwordx4 v[190:191], v[150:153], off offset:256
	v_lshlrev_b64 v[128:129], 11, v[184:185]
	s_nop 0
	v_pk_mul_f32 v[150:151], v[108:109], s[36:37] op_sel_hi:[1,0]
	v_pk_mul_f32 v[108:109], v[106:107], s[36:37] op_sel_hi:[1,0]
	v_lshlrev_b32_e32 v106, 16, v124
	v_and_b32_e32 v107, 0xffff0000, v124
	v_mul_f32_e32 v106, v110, v106
	v_mul_f32_e32 v107, v111, v107
	v_cvt_pk_bf16_f32 v106, v106, v107
	v_lshlrev_b32_e32 v107, 16, v125
	v_and_b32_e32 v110, 0xffff0000, v125
	v_mul_f32_e32 v107, v112, v107
	v_mul_f32_e32 v110, v113, v110
	v_cvt_pk_bf16_f32 v107, v107, v110
	v_lshlrev_b32_e32 v110, 16, v126
	v_mul_f32_e32 v108, v108, v110
	v_and_b32_e32 v110, 0xffff0000, v126
	v_mul_f32_e32 v109, v109, v110
	v_cvt_pk_bf16_f32 v108, v108, v109
	v_lshlrev_b32_e32 v109, 16, v127
	v_and_b32_e32 v110, 0xffff0000, v127
	v_mul_f32_e32 v109, v150, v109
	v_mul_f32_e32 v110, v151, v110
	v_cvt_pk_bf16_f32 v109, v109, v110
	v_lshl_add_u64 v[110:111], s[74:75], 0, v[128:129]
	v_lshl_add_u64 v[110:111], v[110:111], 0, v[194:195]
	global_store_dwordx4 v[110:111], v[106:109], off
	s_nop 1
	v_pk_mul_f32 v[106:107], v[100:101], s[36:37] op_sel_hi:[1,0]
	v_pk_mul_f32 v[100:101], v[98:99], s[36:37] op_sel_hi:[1,0]
	v_lshlrev_b32_e32 v98, 16, v158
	v_and_b32_e32 v99, 0xffff0000, v158
	v_mul_f32_e32 v98, v102, v98
	v_mul_f32_e32 v99, v103, v99
	v_cvt_pk_bf16_f32 v98, v98, v99
	v_lshlrev_b32_e32 v99, 16, v159
	v_and_b32_e32 v102, 0xffff0000, v159
	v_mul_f32_e32 v99, v104, v99
	v_mul_f32_e32 v102, v105, v102
	v_cvt_pk_bf16_f32 v99, v99, v102
	v_lshlrev_b32_e32 v102, 16, v160
	v_mul_f32_e32 v100, v100, v102
	v_and_b32_e32 v102, 0xffff0000, v160
	v_mul_f32_e32 v101, v101, v102
	v_cvt_pk_bf16_f32 v100, v100, v101
	v_lshlrev_b32_e32 v101, 16, v161
	v_mul_f32_e32 v101, v106, v101
	v_and_b32_e32 v102, 0xffff0000, v161
	v_mul_f32_e32 v102, v107, v102
	v_cvt_pk_bf16_f32 v101, v101, v102
	global_store_dwordx4 v[110:111], v[98:101], off offset:256
	s_nop 1
	v_pk_mul_f32 v[100:101], v[92:93], s[36:37] op_sel_hi:[1,0]
	v_pk_mul_f32 v[92:93], v[90:91], s[36:37] op_sel_hi:[1,0]
	v_lshlrev_b32_e32 v90, 16, v162
	v_and_b32_e32 v91, 0xffff0000, v162
	v_mul_f32_e32 v90, v94, v90
	v_mul_f32_e32 v91, v95, v91
	v_cvt_pk_bf16_f32 v90, v90, v91
	v_lshlrev_b32_e32 v91, 16, v163
	v_and_b32_e32 v94, 0xffff0000, v163
	v_mul_f32_e32 v91, v96, v91
	v_mul_f32_e32 v94, v97, v94
	v_cvt_pk_bf16_f32 v91, v91, v94
	v_lshlrev_b32_e32 v94, 16, v164
	v_mul_f32_e32 v92, v92, v94
	v_and_b32_e32 v94, 0xffff0000, v164
	v_mul_f32_e32 v93, v93, v94
	v_cvt_pk_bf16_f32 v92, v92, v93
	v_lshlrev_b32_e32 v93, 16, v165
	v_and_b32_e32 v94, 0xffff0000, v165
	v_lshlrev_b64 v[98:99], 11, v[186:187]
	v_mul_f32_e32 v93, v100, v93
	v_mul_f32_e32 v94, v101, v94
	v_cvt_pk_bf16_f32 v93, v93, v94
	v_lshl_add_u64 v[94:95], s[74:75], 0, v[98:99]
	v_lshl_add_u64 v[94:95], v[94:95], 0, v[194:195]
	global_store_dwordx4 v[94:95], v[90:93], off
	s_nop 1
	v_pk_mul_f32 v[90:91], v[84:85], s[36:37] op_sel_hi:[1,0]
	v_pk_mul_f32 v[84:85], v[82:83], s[36:37] op_sel_hi:[1,0]
	v_lshlrev_b32_e32 v82, 16, v166
	v_and_b32_e32 v83, 0xffff0000, v166
	v_mul_f32_e32 v82, v86, v82
	v_mul_f32_e32 v83, v87, v83
	v_cvt_pk_bf16_f32 v82, v82, v83
	v_lshlrev_b32_e32 v83, 16, v167
	v_and_b32_e32 v86, 0xffff0000, v167
	v_mul_f32_e32 v83, v88, v83
	v_mul_f32_e32 v86, v89, v86
	v_cvt_pk_bf16_f32 v83, v83, v86
	v_lshlrev_b32_e32 v86, 16, v168
	v_mul_f32_e32 v84, v84, v86
	v_and_b32_e32 v86, 0xffff0000, v168
	v_mul_f32_e32 v85, v85, v86
	v_cvt_pk_bf16_f32 v84, v84, v85
	v_lshlrev_b32_e32 v85, 16, v169
	v_mul_f32_e32 v85, v90, v85
	v_and_b32_e32 v86, 0xffff0000, v169
	v_mul_f32_e32 v86, v91, v86
	v_cvt_pk_bf16_f32 v85, v85, v86
	global_store_dwordx4 v[94:95], v[82:85], off offset:256
	s_nop 1
	v_pk_mul_f32 v[84:85], v[76:77], s[36:37] op_sel_hi:[1,0]
	v_pk_mul_f32 v[76:77], v[74:75], s[36:37] op_sel_hi:[1,0]
	v_lshlrev_b32_e32 v74, 16, v118
	v_and_b32_e32 v75, 0xffff0000, v118
	v_mul_f32_e32 v74, v78, v74
	v_mul_f32_e32 v75, v79, v75
	v_cvt_pk_bf16_f32 v74, v74, v75
	v_lshlrev_b32_e32 v75, 16, v119
	v_and_b32_e32 v78, 0xffff0000, v119
	v_mul_f32_e32 v75, v80, v75
	v_mul_f32_e32 v78, v81, v78
	v_cvt_pk_bf16_f32 v75, v75, v78
	v_lshlrev_b32_e32 v78, 16, v120
	v_mul_f32_e32 v76, v76, v78
	v_and_b32_e32 v78, 0xffff0000, v120
	v_mul_f32_e32 v77, v77, v78
	v_cvt_pk_bf16_f32 v76, v76, v77
	v_lshlrev_b32_e32 v77, 16, v121
	v_and_b32_e32 v78, 0xffff0000, v121
	v_lshlrev_b64 v[82:83], 11, v[122:123]
	v_mul_f32_e32 v77, v84, v77
	v_mul_f32_e32 v78, v85, v78
	v_cvt_pk_bf16_f32 v77, v77, v78
	v_lshl_add_u64 v[78:79], s[74:75], 0, v[82:83]
	v_lshl_add_u64 v[78:79], v[78:79], 0, v[194:195]
	global_store_dwordx4 v[78:79], v[74:77], off
	s_nop 1
	v_pk_mul_f32 v[74:75], v[68:69], s[36:37] op_sel_hi:[1,0]
	v_pk_mul_f32 v[68:69], v[66:67], s[36:37] op_sel_hi:[1,0]
	v_lshlrev_b32_e32 v66, 16, v114
	v_and_b32_e32 v67, 0xffff0000, v114
	v_mul_f32_e32 v66, v70, v66
	v_mul_f32_e32 v67, v71, v67
	v_cvt_pk_bf16_f32 v66, v66, v67
	v_lshlrev_b32_e32 v67, 16, v115
	v_and_b32_e32 v70, 0xffff0000, v115
	v_mul_f32_e32 v67, v72, v67
	v_mul_f32_e32 v70, v73, v70
	v_cvt_pk_bf16_f32 v67, v67, v70
	v_lshlrev_b32_e32 v70, 16, v116
	v_mul_f32_e32 v68, v68, v70
	v_and_b32_e32 v70, 0xffff0000, v116
	v_mul_f32_e32 v69, v69, v70
	v_cvt_pk_bf16_f32 v68, v68, v69
	v_lshlrev_b32_e32 v69, 16, v117
	v_mul_f32_e32 v69, v74, v69
	v_and_b32_e32 v70, 0xffff0000, v117
	v_mul_f32_e32 v70, v75, v70
	v_cvt_pk_bf16_f32 v69, v69, v70
	global_store_dwordx4 v[78:79], v[66:69], off offset:256
	v_add_u32_e32 v78, 0x80, v144
	s_nop 0
	v_mad_i64_i32 v[66:67], s[6:7], v78, s37, v[142:143]
	v_lshl_add_u64 v[66:67], v[66:67], 0, v[194:195]
	v_add_co_u32_e32 v68, vcc, s16, v66
	v_add_u32_e32 v86, 0x90, v144
	s_nop 0
	v_addc_co_u32_e32 v69, vcc, 0, v67, vcc
	global_load_dwordx4 v[70:73], v[68:69], off offset:2048
	v_lshl_add_u64 v[66:67], v[66:67], 0, s[84:85]
	global_load_dwordx4 v[74:77], v[66:67], off offset:256
	v_pk_mul_f32 v[96:97], v[56:57], s[36:37] op_sel_hi:[1,0]
	v_mad_i64_i32 v[56:57], s[6:7], v86, s37, v[142:143]
	v_lshl_add_u64 v[56:57], v[56:57], 0, v[194:195]
	v_pk_mul_f32 v[94:95], v[58:59], s[36:37] op_sel_hi:[1,0]
	v_add_co_u32_e32 v58, vcc, s16, v56
	v_pk_mul_f32 v[92:93], v[60:61], s[36:37] op_sel_hi:[1,0]
	s_nop 0
	v_addc_co_u32_e32 v59, vcc, 0, v57, vcc
	global_load_dwordx4 v[58:61], v[58:59], off offset:2048
	v_add_u32_e32 v68, 0xa0, v144
	v_pk_mul_f32 v[102:103], v[50:51], s[36:37] op_sel_hi:[1,0]
	v_mad_i64_i32 v[50:51], s[6:7], v68, s37, v[142:143]
	v_add_u32_e32 v66, 0xb0, v144
	v_lshl_add_u64 v[50:51], v[50:51], 0, v[194:195]
	v_pk_mul_f32 v[100:101], v[52:53], s[36:37] op_sel_hi:[1,0]
	v_mad_i64_i32 v[52:53], s[6:7], v66, s37, v[142:143]
	v_lshl_add_u64 v[82:83], v[50:51], 0, s[84:85]
	v_add_co_u32_e32 v50, vcc, s16, v50
	v_lshl_add_u64 v[52:53], v[52:53], 0, v[194:195]
	s_nop 0
	v_addc_co_u32_e32 v51, vcc, 0, v51, vcc
	v_ashrrev_i32_e32 v79, 31, v78
	v_lshl_add_u64 v[104:105], v[52:53], 0, s[84:85]
	v_add_co_u32_e32 v52, vcc, s16, v52
	v_pk_mul_f32 v[98:99], v[54:55], s[36:37] op_sel_hi:[1,0]
	v_lshlrev_b64 v[54:55], 11, v[78:79]
	v_lshl_add_u64 v[56:57], v[56:57], 0, s[84:85]
	v_addc_co_u32_e32 v53, vcc, 0, v53, vcc
	v_pk_mul_f32 v[88:89], v[64:65], s[36:37] op_sel_hi:[1,0]
	v_pk_mul_f32 v[90:91], v[62:63], s[36:37] op_sel_hi:[1,0]
	v_lshl_add_u64 v[106:107], s[74:75], 0, v[54:55]
	global_load_dwordx4 v[62:65], v[56:57], off offset:256
	global_load_dwordx4 v[78:81], v[50:51], off offset:2048
	s_nop 0
	global_load_dwordx4 v[82:85], v[82:83], off offset:256
	s_nop 0
	global_load_dwordx4 v[54:57], v[52:53], off offset:2048
	s_nop 0
	global_load_dwordx4 v[50:53], v[104:105], off offset:256
	v_lshl_add_u64 v[104:105], v[106:107], 0, v[194:195]
	v_pk_mul_f32 v[46:47], v[46:47], s[36:37] op_sel_hi:[1,0]
	v_pk_mul_f32 v[48:49], v[48:49], s[36:37] op_sel_hi:[1,0]
	v_ashrrev_i32_e32 v87, 31, v86
	v_pk_mul_f32 v[38:39], v[38:39], s[36:37] op_sel_hi:[1,0]
	v_pk_mul_f32 v[40:41], v[40:41], s[36:37] op_sel_hi:[1,0]
	v_pk_mul_f32 v[30:31], v[30:31], s[36:37] op_sel_hi:[1,0]
	v_pk_mul_f32 v[32:33], v[32:33], s[36:37] op_sel_hi:[1,0]
	v_ashrrev_i32_e32 v69, 31, v68
	v_pk_mul_f32 v[22:23], v[22:23], s[36:37] op_sel_hi:[1,0]
	v_pk_mul_f32 v[24:25], v[24:25], s[36:37] op_sel_hi:[1,0]
	v_pk_mul_f32 v[14:15], v[14:15], s[36:37] op_sel_hi:[1,0]
	v_pk_mul_f32 v[16:17], v[16:17], s[36:37] op_sel_hi:[1,0]
	v_ashrrev_i32_e32 v67, 31, v66
	v_pk_mul_f32 v[6:7], v[6:7], s[36:37] op_sel_hi:[1,0]
	v_pk_mul_f32 v[8:9], v[8:9], s[36:37] op_sel_hi:[1,0]
	s_waitcnt vmcnt(0)
	v_lshlrev_b32_e32 v106, 16, v70
	v_and_b32_e32 v70, 0xffff0000, v70
	v_lshlrev_b32_e32 v107, 16, v71
	v_and_b32_e32 v71, 0xffff0000, v71
	v_lshlrev_b32_e32 v108, 16, v72
	v_and_b32_e32 v72, 0xffff0000, v72
	v_lshlrev_b32_e32 v109, 16, v73
	v_and_b32_e32 v73, 0xffff0000, v73
	v_mul_f32_e32 v70, v91, v70
	v_mul_f32_e32 v71, v89, v71
	v_mul_f32_e32 v72, v95, v72
	v_mul_f32_e32 v73, v93, v73
	v_mul_f32_e32 v90, v90, v106
	v_mul_f32_e32 v88, v88, v107
	v_mul_f32_e32 v89, v94, v108
	v_mul_f32_e32 v91, v92, v109
	v_cvt_pk_bf16_f32 v70, v90, v70
	v_cvt_pk_bf16_f32 v71, v88, v71
	v_cvt_pk_bf16_f32 v72, v89, v72
	v_cvt_pk_bf16_f32 v73, v91, v73
	v_lshlrev_b32_e32 v111, 16, v75
	v_and_b32_e32 v75, 0xffff0000, v75
	global_store_dwordx4 v[104:105], v[70:73], off
	v_lshlrev_b32_e32 v110, 16, v74
	v_and_b32_e32 v74, 0xffff0000, v74
	v_lshlrev_b32_e32 v72, 16, v76
	v_and_b32_e32 v73, 0xffff0000, v76
	v_mul_f32_e32 v71, v97, v75
	v_mul_f32_e32 v72, v102, v72
	v_mul_f32_e32 v73, v103, v73
	v_mul_f32_e32 v92, v98, v110
	v_mul_f32_e32 v74, v99, v74
	v_mul_f32_e32 v93, v96, v111
	v_cvt_pk_bf16_f32 v70, v92, v74
	v_cvt_pk_bf16_f32 v71, v93, v71
	v_cvt_pk_bf16_f32 v72, v72, v73
	v_lshlrev_b32_e32 v73, 16, v77
	v_mul_f32_e32 v73, v100, v73
	v_and_b32_e32 v74, 0xffff0000, v77
	v_mul_f32_e32 v74, v101, v74
	v_cvt_pk_bf16_f32 v73, v73, v74
	global_store_dwordx4 v[104:105], v[70:73], off offset:256
	s_nop 1
	v_pk_mul_f32 v[72:73], v[44:45], s[36:37] op_sel_hi:[1,0]
	v_pk_mul_f32 v[44:45], v[42:43], s[36:37] op_sel_hi:[1,0]
	v_lshlrev_b32_e32 v42, 16, v58
	v_and_b32_e32 v43, 0xffff0000, v58
	v_mul_f32_e32 v42, v46, v42
	v_mul_f32_e32 v43, v47, v43
	v_cvt_pk_bf16_f32 v42, v42, v43
	v_lshlrev_b32_e32 v43, 16, v59
	v_and_b32_e32 v46, 0xffff0000, v59
	v_mul_f32_e32 v43, v48, v43
	v_mul_f32_e32 v46, v49, v46
	v_cvt_pk_bf16_f32 v43, v43, v46
	v_lshlrev_b32_e32 v46, 16, v60
	v_mul_f32_e32 v44, v44, v46
	v_and_b32_e32 v46, 0xffff0000, v60
	v_mul_f32_e32 v45, v45, v46
	v_cvt_pk_bf16_f32 v44, v44, v45
	v_lshlrev_b32_e32 v45, 16, v61
	v_and_b32_e32 v46, 0xffff0000, v61
	v_lshlrev_b64 v[70:71], 11, v[86:87]
	v_mul_f32_e32 v45, v72, v45
	v_mul_f32_e32 v46, v73, v46
	v_cvt_pk_bf16_f32 v45, v45, v46
	v_lshl_add_u64 v[46:47], s[74:75], 0, v[70:71]
	v_lshl_add_u64 v[46:47], v[46:47], 0, v[194:195]
	global_store_dwordx4 v[46:47], v[42:45], off
	s_nop 1
	v_pk_mul_f32 v[42:43], v[36:37], s[36:37] op_sel_hi:[1,0]
	v_pk_mul_f32 v[36:37], v[34:35], s[36:37] op_sel_hi:[1,0]
	v_lshlrev_b32_e32 v34, 16, v62
	v_and_b32_e32 v35, 0xffff0000, v62
	v_mul_f32_e32 v34, v38, v34
	v_mul_f32_e32 v35, v39, v35
	v_cvt_pk_bf16_f32 v34, v34, v35
	v_lshlrev_b32_e32 v35, 16, v63
	v_and_b32_e32 v38, 0xffff0000, v63
	v_mul_f32_e32 v35, v40, v35
	v_mul_f32_e32 v38, v41, v38
	v_cvt_pk_bf16_f32 v35, v35, v38
	v_lshlrev_b32_e32 v38, 16, v64
	v_mul_f32_e32 v36, v36, v38
	v_and_b32_e32 v38, 0xffff0000, v64
	v_mul_f32_e32 v37, v37, v38
	v_cvt_pk_bf16_f32 v36, v36, v37
	v_lshlrev_b32_e32 v37, 16, v65
	v_mul_f32_e32 v37, v42, v37
	v_and_b32_e32 v38, 0xffff0000, v65
	v_mul_f32_e32 v38, v43, v38
	v_cvt_pk_bf16_f32 v37, v37, v38
	global_store_dwordx4 v[46:47], v[34:37], off offset:256
	s_nop 1
	v_pk_mul_f32 v[36:37], v[28:29], s[36:37] op_sel_hi:[1,0]
	v_pk_mul_f32 v[28:29], v[26:27], s[36:37] op_sel_hi:[1,0]
	v_lshlrev_b32_e32 v26, 16, v78
	v_and_b32_e32 v27, 0xffff0000, v78
	v_mul_f32_e32 v26, v30, v26
	v_mul_f32_e32 v27, v31, v27
	v_cvt_pk_bf16_f32 v26, v26, v27
	v_lshlrev_b32_e32 v27, 16, v79
	v_and_b32_e32 v30, 0xffff0000, v79
	v_mul_f32_e32 v27, v32, v27
	v_mul_f32_e32 v30, v33, v30
	v_cvt_pk_bf16_f32 v27, v27, v30
	v_lshlrev_b32_e32 v30, 16, v80
	v_mul_f32_e32 v28, v28, v30
	v_and_b32_e32 v30, 0xffff0000, v80
	v_mul_f32_e32 v29, v29, v30
	v_cvt_pk_bf16_f32 v28, v28, v29
	v_lshlrev_b32_e32 v29, 16, v81
	v_and_b32_e32 v30, 0xffff0000, v81
	v_lshlrev_b64 v[34:35], 11, v[68:69]
	v_mul_f32_e32 v29, v36, v29
	v_mul_f32_e32 v30, v37, v30
	v_cvt_pk_bf16_f32 v29, v29, v30
	v_lshl_add_u64 v[30:31], s[74:75], 0, v[34:35]
	v_lshl_add_u64 v[30:31], v[30:31], 0, v[194:195]
	global_store_dwordx4 v[30:31], v[26:29], off
	s_nop 1
	v_pk_mul_f32 v[26:27], v[20:21], s[36:37] op_sel_hi:[1,0]
	v_pk_mul_f32 v[20:21], v[18:19], s[36:37] op_sel_hi:[1,0]
	v_lshlrev_b32_e32 v18, 16, v82
	v_and_b32_e32 v19, 0xffff0000, v82
	v_mul_f32_e32 v18, v22, v18
	v_mul_f32_e32 v19, v23, v19
	v_cvt_pk_bf16_f32 v18, v18, v19
	v_lshlrev_b32_e32 v19, 16, v83
	v_and_b32_e32 v22, 0xffff0000, v83
	v_mul_f32_e32 v19, v24, v19
	v_mul_f32_e32 v22, v25, v22
	v_cvt_pk_bf16_f32 v19, v19, v22
	v_lshlrev_b32_e32 v22, 16, v84
	v_mul_f32_e32 v20, v20, v22
	v_and_b32_e32 v22, 0xffff0000, v84
	v_mul_f32_e32 v21, v21, v22
	v_cvt_pk_bf16_f32 v20, v20, v21
	v_lshlrev_b32_e32 v21, 16, v85
	v_mul_f32_e32 v21, v26, v21
	v_and_b32_e32 v22, 0xffff0000, v85
	v_mul_f32_e32 v22, v27, v22
	v_cvt_pk_bf16_f32 v21, v21, v22
	global_store_dwordx4 v[30:31], v[18:21], off offset:256
	s_nop 1
	v_pk_mul_f32 v[20:21], v[12:13], s[36:37] op_sel_hi:[1,0]
	v_pk_mul_f32 v[12:13], v[10:11], s[36:37] op_sel_hi:[1,0]
	v_lshlrev_b32_e32 v10, 16, v54
	v_and_b32_e32 v11, 0xffff0000, v54
	v_mul_f32_e32 v10, v14, v10
	v_mul_f32_e32 v11, v15, v11
	v_cvt_pk_bf16_f32 v10, v10, v11
	v_lshlrev_b32_e32 v11, 16, v55
	v_and_b32_e32 v14, 0xffff0000, v55
	v_mul_f32_e32 v11, v16, v11
	v_mul_f32_e32 v14, v17, v14
	v_cvt_pk_bf16_f32 v11, v11, v14
	v_lshlrev_b32_e32 v14, 16, v56
	v_mul_f32_e32 v12, v12, v14
	v_and_b32_e32 v14, 0xffff0000, v56
	v_mul_f32_e32 v13, v13, v14
	v_cvt_pk_bf16_f32 v12, v12, v13
	v_lshlrev_b32_e32 v13, 16, v57
	v_and_b32_e32 v14, 0xffff0000, v57
	v_lshlrev_b64 v[18:19], 11, v[66:67]
	v_mul_f32_e32 v13, v20, v13
	v_mul_f32_e32 v14, v21, v14
	v_cvt_pk_bf16_f32 v13, v13, v14
	v_lshl_add_u64 v[14:15], s[74:75], 0, v[18:19]
	v_lshl_add_u64 v[14:15], v[14:15], 0, v[194:195]
	global_store_dwordx4 v[14:15], v[10:13], off
	s_nop 1
	v_pk_mul_f32 v[10:11], v[4:5], s[36:37] op_sel_hi:[1,0]
	v_pk_mul_f32 v[4:5], v[2:3], s[36:37] op_sel_hi:[1,0]
	v_lshlrev_b32_e32 v2, 16, v50
	v_and_b32_e32 v3, 0xffff0000, v50
	v_mul_f32_e32 v2, v6, v2
	v_mul_f32_e32 v3, v7, v3
	v_cvt_pk_bf16_f32 v2, v2, v3
	v_lshlrev_b32_e32 v3, 16, v51
	v_and_b32_e32 v6, 0xffff0000, v51
	v_mul_f32_e32 v3, v8, v3
	v_mul_f32_e32 v6, v9, v6
	v_cvt_pk_bf16_f32 v3, v3, v6
	v_lshlrev_b32_e32 v6, 16, v52
	v_mul_f32_e32 v4, v4, v6
	v_and_b32_e32 v6, 0xffff0000, v52
	v_mul_f32_e32 v5, v5, v6
	v_cvt_pk_bf16_f32 v4, v4, v5
	v_lshlrev_b32_e32 v5, 16, v53
	v_mul_f32_e32 v5, v10, v5
	v_and_b32_e32 v6, 0xffff0000, v53
	v_mul_f32_e32 v6, v11, v6
	v_cvt_pk_bf16_f32 v5, v5, v6
	global_store_dwordx4 v[14:15], v[2:5], off offset:256
	s_and_b64 vcc, exec, s[52:53]
	s_mov_b32 s28, s4
	s_cbranch_vccz .LBB0_265
	s_waitcnt vmcnt(0)
	v_readlane_b32 s28, v250, 12
	s_cmpk_gt_u32 s12, 0xff
	v_readlane_b32 s29, v250, 13
	s_mov_b32 s70, 0x800000
	s_cbranch_scc1 .LBB0_270
	s_barrier

.LBB0_368:
	v_add_u32_e32 v253, 0x10000, v201
	ds_read_b128 v[130:133], v253
	ds_read_b128 v[134:137], v253 offset:1024
	ds_read_b128 v[138:141], v253 offset:2048
	ds_read_b128 v[142:145], v253 offset:3072
	s_add_u32 s10, s8, 0xfffc0080
	s_addc_u32 s11, s9, -1
	s_cmp_eq_u32 s29, 12
	s_cselect_b32 s11, s81, s11
	s_cselect_b32 s10, s80, s10
	s_cselect_b32 s53, s83, s28
	s_cselect_b32 s52, s82, s7
	v_lshl_add_u64 v[178:179], s[8:9], 0, v[212:213]
	s_add_i32 m0, s34, 0xc000
	ds_read_b128 v[146:149], v199
	ds_read_b128 v[150:153], v199 offset:1024
	ds_read_b128 v[154:157], v199 offset:2048
	ds_read_b128 v[158:161], v199 offset:3072
	ds_read_b128 v[162:165], v199 offset:4096
	ds_read_b128 v[166:169], v199 offset:5120
	ds_read_b128 v[170:173], v199 offset:6144
	ds_read_b128 v[174:177], v199 offset:7168
	global_load_lds_dwordx4 v[178:179], off
	v_lshl_add_u64 v[178:179], s[8:9], 0, v[214:215]
	s_add_i32 m0, s34, 0xe000
	s_nop 0
	global_load_lds_dwordx4 v[178:179], off
	s_waitcnt lgkmcnt(8)
	s_setprio 1
	s_barrier
	s_waitcnt lgkmcnt(0)
	v_mfma_f32_16x16x32_bf16 v[126:129], v[130:133], v[146:149], v[126:129]
	v_mfma_f32_16x16x32_bf16 v[122:125], v[138:141], v[146:149], v[122:125]
	v_mfma_f32_16x16x32_bf16 v[118:121], v[130:133], v[154:157], v[118:121]
	v_mfma_f32_16x16x32_bf16 v[114:117], v[138:141], v[154:157], v[114:117]
	v_mfma_f32_16x16x32_bf16 v[110:113], v[130:133], v[162:165], v[110:113]
	v_mfma_f32_16x16x32_bf16 v[106:109], v[138:141], v[162:165], v[106:109]
	v_mfma_f32_16x16x32_bf16 v[102:105], v[130:133], v[170:173], v[102:105]
	v_mfma_f32_16x16x32_bf16 v[98:101], v[138:141], v[170:173], v[98:101]
	v_mfma_f32_16x16x32_bf16 v[126:129], v[134:137], v[150:153], v[126:129]
	v_mfma_f32_16x16x32_bf16 v[122:125], v[142:145], v[150:153], v[122:125]
	v_mfma_f32_16x16x32_bf16 v[118:121], v[134:137], v[158:161], v[118:121]
	v_mfma_f32_16x16x32_bf16 v[114:117], v[142:145], v[158:161], v[114:117]
	v_mfma_f32_16x16x32_bf16 v[110:113], v[134:137], v[166:169], v[110:113]
	v_mfma_f32_16x16x32_bf16 v[106:109], v[142:145], v[166:169], v[106:109]
	v_mfma_f32_16x16x32_bf16 v[102:105], v[134:137], v[174:177], v[102:105]
	v_mfma_f32_16x16x32_bf16 v[98:101], v[142:145], v[174:177], v[98:101]
	s_barrier
	s_setprio 0
	s_mov_b32 m0, s35
	v_lshl_add_u64 v[216:217], s[52:53], 0, v[194:195]
	ds_read_b128 v[178:181], v253 offset:16384
	ds_read_b128 v[182:185], v253 offset:17408
	ds_read_b128 v[186:189], v253 offset:18432
	ds_read_b128 v[190:193], v253 offset:19456
	global_load_lds_dwordx4 v[216:217], off
	v_lshl_add_u64 v[218:219], s[52:53], 0, v[210:211]
	s_mov_b32 m0, s42
	s_nop 0
	global_load_lds_dwordx4 v[218:219], off
	s_setprio 1
	s_barrier
	s_waitcnt lgkmcnt(0)
	v_mfma_f32_16x16x32_bf16 v[94:97], v[178:181], v[146:149], v[94:97]
	v_mfma_f32_16x16x32_bf16 v[90:93], v[186:189], v[146:149], v[90:93]
	v_mfma_f32_16x16x32_bf16 v[86:89], v[178:181], v[154:157], v[86:89]
	v_mfma_f32_16x16x32_bf16 v[82:85], v[186:189], v[154:157], v[82:85]
	v_mfma_f32_16x16x32_bf16 v[78:81], v[178:181], v[162:165], v[78:81]
	v_mfma_f32_16x16x32_bf16 v[74:77], v[186:189], v[162:165], v[74:77]
	v_mfma_f32_16x16x32_bf16 v[70:73], v[178:181], v[170:173], v[70:73]
	v_mfma_f32_16x16x32_bf16 v[66:69], v[186:189], v[170:173], v[66:69]
	v_mfma_f32_16x16x32_bf16 v[94:97], v[182:185], v[150:153], v[94:97]
	v_mfma_f32_16x16x32_bf16 v[90:93], v[190:193], v[150:153], v[90:93]
	v_mfma_f32_16x16x32_bf16 v[86:89], v[182:185], v[158:161], v[86:89]
	v_mfma_f32_16x16x32_bf16 v[82:85], v[190:193], v[158:161], v[82:85]
	v_mfma_f32_16x16x32_bf16 v[78:81], v[182:185], v[166:169], v[78:81]
	v_mfma_f32_16x16x32_bf16 v[74:77], v[190:193], v[166:169], v[74:77]
	s_mov_b32 m0, s34
	v_mfma_f32_16x16x32_bf16 v[70:73], v[182:185], v[174:177], v[70:73]
	v_lshl_add_u64 v[220:221], s[10:11], 0, v[206:207]
	v_mfma_f32_16x16x32_bf16 v[66:69], v[190:193], v[174:177], v[66:69]
	s_barrier
	s_setprio 0
	ds_read_b128 v[146:149], v199 offset:16384
	ds_read_b128 v[150:153], v199 offset:17408
	ds_read_b128 v[154:157], v199 offset:18432
	ds_read_b128 v[158:161], v199 offset:19456
	ds_read_b128 v[162:165], v199 offset:20480
	ds_read_b128 v[166:169], v199 offset:21504
	ds_read_b128 v[170:173], v199 offset:22528
	ds_read_b128 v[174:177], v199 offset:23552
	global_load_lds_dwordx4 v[220:221], off
	v_lshl_add_u64 v[222:223], s[10:11], 0, v[208:209]
	s_mov_b32 m0, s56
	s_nop 0
	global_load_lds_dwordx4 v[222:223], off
	s_setprio 1
	s_barrier
	s_waitcnt lgkmcnt(0)
	v_mfma_f32_16x16x32_bf16 v[62:65], v[130:133], v[146:149], v[62:65]
	v_mfma_f32_16x16x32_bf16 v[58:61], v[138:141], v[146:149], v[58:61]
	v_mfma_f32_16x16x32_bf16 v[54:57], v[130:133], v[154:157], v[54:57]
	v_mfma_f32_16x16x32_bf16 v[50:53], v[138:141], v[154:157], v[50:53]
	v_mfma_f32_16x16x32_bf16 v[46:49], v[130:133], v[162:165], v[46:49]
	v_mfma_f32_16x16x32_bf16 v[42:45], v[138:141], v[162:165], v[42:45]
	v_mfma_f32_16x16x32_bf16 v[38:41], v[130:133], v[170:173], v[38:41]
	v_mfma_f32_16x16x32_bf16 v[34:37], v[138:141], v[170:173], v[34:37]
	v_mfma_f32_16x16x32_bf16 v[62:65], v[134:137], v[150:153], v[62:65]
	v_mfma_f32_16x16x32_bf16 v[58:61], v[142:145], v[150:153], v[58:61]
	v_mfma_f32_16x16x32_bf16 v[54:57], v[134:137], v[158:161], v[54:57]
	v_mfma_f32_16x16x32_bf16 v[50:53], v[142:145], v[158:161], v[50:53]
	v_mfma_f32_16x16x32_bf16 v[46:49], v[134:137], v[166:169], v[46:49]
	v_mfma_f32_16x16x32_bf16 v[42:45], v[142:145], v[166:169], v[42:45]
	v_mfma_f32_16x16x32_bf16 v[38:41], v[134:137], v[174:177], v[38:41]
	v_mfma_f32_16x16x32_bf16 v[34:37], v[142:145], v[174:177], v[34:37]
	s_barrier
	s_setprio 0
	s_add_u32 s86, s52, 0x40000
	s_addc_u32 s87, s53, 0
	s_mov_b32 m0, s57
	v_lshl_add_u64 v[130:131], s[86:87], 0, v[194:195]
	global_load_lds_dwordx4 v[130:131], off
	v_lshl_add_u64 v[130:131], s[86:87], 0, v[210:211]
	s_mov_b32 m0, s67
	s_nop 0
	global_load_lds_dwordx4 v[130:131], off
	s_waitcnt vmcnt(6)
	s_setprio 1
	s_barrier
	v_mfma_f32_16x16x32_bf16 v[30:33], v[178:181], v[146:149], v[30:33]
	v_mfma_f32_16x16x32_bf16 v[26:29], v[186:189], v[146:149], v[26:29]
	v_mfma_f32_16x16x32_bf16 v[22:25], v[178:181], v[154:157], v[22:25]
	v_mfma_f32_16x16x32_bf16 v[18:21], v[186:189], v[154:157], v[18:21]
	v_mfma_f32_16x16x32_bf16 v[14:17], v[178:181], v[162:165], v[14:17]
	v_mfma_f32_16x16x32_bf16 v[10:13], v[186:189], v[162:165], v[10:13]
	v_mfma_f32_16x16x32_bf16 v[6:9], v[178:181], v[170:173], v[6:9]
	v_mfma_f32_16x16x32_bf16 v[2:5], v[186:189], v[170:173], v[2:5]
	v_mfma_f32_16x16x32_bf16 v[30:33], v[182:185], v[150:153], v[30:33]
	v_mfma_f32_16x16x32_bf16 v[26:29], v[190:193], v[150:153], v[26:29]
	v_mfma_f32_16x16x32_bf16 v[22:25], v[182:185], v[158:161], v[22:25]
	v_mfma_f32_16x16x32_bf16 v[18:21], v[190:193], v[158:161], v[18:21]
	v_mfma_f32_16x16x32_bf16 v[14:17], v[182:185], v[166:169], v[14:17]
	v_mfma_f32_16x16x32_bf16 v[10:13], v[190:193], v[166:169], v[10:13]
	v_mfma_f32_16x16x32_bf16 v[6:9], v[182:185], v[174:177], v[6:9]
	v_mfma_f32_16x16x32_bf16 v[2:5], v[190:193], v[174:177], v[2:5]
	s_barrier
	s_setprio 0
	ds_read_b128 v[130:133], v253 offset:32768
	ds_read_b128 v[134:137], v253 offset:33792
	ds_read_b128 v[138:141], v253 offset:34816
	ds_read_b128 v[142:145], v253 offset:35840
	s_add_u32 s10, s10, 0x40000
	s_addc_u32 s11, s11, 0
	s_mov_b32 m0, s70
	v_lshl_add_u64 v[178:179], s[10:11], 0, v[206:207]
	ds_read_b128 v[146:149], v199 offset:32768
	ds_read_b128 v[150:153], v199 offset:33792
	ds_read_b128 v[154:157], v199 offset:34816
	ds_read_b128 v[158:161], v199 offset:35840
	ds_read_b128 v[162:165], v199 offset:36864
	ds_read_b128 v[166:169], v199 offset:37888
	ds_read_b128 v[170:173], v199 offset:38912
	ds_read_b128 v[174:177], v199 offset:39936
	global_load_lds_dwordx4 v[178:179], off
	v_lshl_add_u64 v[178:179], s[10:11], 0, v[208:209]
	s_mov_b32 m0, s71
	s_nop 0
	global_load_lds_dwordx4 v[178:179], off
	s_waitcnt lgkmcnt(8)
	s_setprio 1
	s_barrier
	s_waitcnt lgkmcnt(0)
	v_mfma_f32_16x16x32_bf16 v[126:129], v[130:133], v[146:149], v[126:129]
	v_mfma_f32_16x16x32_bf16 v[122:125], v[138:141], v[146:149], v[122:125]
	v_mfma_f32_16x16x32_bf16 v[118:121], v[130:133], v[154:157], v[118:121]
	v_mfma_f32_16x16x32_bf16 v[114:117], v[138:141], v[154:157], v[114:117]
	v_mfma_f32_16x16x32_bf16 v[110:113], v[130:133], v[162:165], v[110:113]
	v_mfma_f32_16x16x32_bf16 v[106:109], v[138:141], v[162:165], v[106:109]
	v_mfma_f32_16x16x32_bf16 v[102:105], v[130:133], v[170:173], v[102:105]
	v_mfma_f32_16x16x32_bf16 v[98:101], v[138:141], v[170:173], v[98:101]
	v_mfma_f32_16x16x32_bf16 v[126:129], v[134:137], v[150:153], v[126:129]
	v_mfma_f32_16x16x32_bf16 v[122:125], v[142:145], v[150:153], v[122:125]
	v_mfma_f32_16x16x32_bf16 v[118:121], v[134:137], v[158:161], v[118:121]
	v_mfma_f32_16x16x32_bf16 v[114:117], v[142:145], v[158:161], v[114:117]
	v_mfma_f32_16x16x32_bf16 v[110:113], v[134:137], v[166:169], v[110:113]
	v_mfma_f32_16x16x32_bf16 v[106:109], v[142:145], v[166:169], v[106:109]
	v_mfma_f32_16x16x32_bf16 v[102:105], v[134:137], v[174:177], v[102:105]
	v_mfma_f32_16x16x32_bf16 v[98:101], v[142:145], v[174:177], v[98:101]
	s_barrier
	s_setprio 0
	s_mov_b32 m0, s78
	v_lshl_add_u64 v[216:217], v[216:217], 0, s[76:77]
	ds_read_b128 v[178:181], v253 offset:49152
	ds_read_b128 v[182:185], v253 offset:50176
	ds_read_b128 v[186:189], v253 offset:51200
	ds_read_b128 v[190:193], v253 offset:52224
	global_load_lds_dwordx4 v[216:217], off
	v_lshl_add_u64 v[216:217], v[218:219], 0, s[76:77]
	s_mov_b32 m0, s79
	s_nop 0
	global_load_lds_dwordx4 v[216:217], off
	s_setprio 1
	s_barrier
	s_waitcnt lgkmcnt(0)
	v_mfma_f32_16x16x32_bf16 v[94:97], v[178:181], v[146:149], v[94:97]
	v_mfma_f32_16x16x32_bf16 v[90:93], v[186:189], v[146:149], v[90:93]
	v_mfma_f32_16x16x32_bf16 v[86:89], v[178:181], v[154:157], v[86:89]
	v_mfma_f32_16x16x32_bf16 v[82:85], v[186:189], v[154:157], v[82:85]
	v_mfma_f32_16x16x32_bf16 v[78:81], v[178:181], v[162:165], v[78:81]
	v_mfma_f32_16x16x32_bf16 v[74:77], v[186:189], v[162:165], v[74:77]
	v_mfma_f32_16x16x32_bf16 v[70:73], v[178:181], v[170:173], v[70:73]
	v_mfma_f32_16x16x32_bf16 v[66:69], v[186:189], v[170:173], v[66:69]
	v_mfma_f32_16x16x32_bf16 v[94:97], v[182:185], v[150:153], v[94:97]
	v_mfma_f32_16x16x32_bf16 v[90:93], v[190:193], v[150:153], v[90:93]
	v_mfma_f32_16x16x32_bf16 v[86:89], v[182:185], v[158:161], v[86:89]
	v_mfma_f32_16x16x32_bf16 v[82:85], v[190:193], v[158:161], v[82:85]
	v_mfma_f32_16x16x32_bf16 v[78:81], v[182:185], v[166:169], v[78:81]
	v_mfma_f32_16x16x32_bf16 v[74:77], v[190:193], v[166:169], v[74:77]
	s_mov_b32 m0, s26
	v_mfma_f32_16x16x32_bf16 v[70:73], v[182:185], v[174:177], v[70:73]
	v_lshl_add_u64 v[216:217], v[220:221], 0, s[76:77]
	v_mfma_f32_16x16x32_bf16 v[66:69], v[190:193], v[174:177], v[66:69]
	s_barrier
	s_setprio 0
	ds_read_b128 v[146:149], v199 offset:49152
	ds_read_b128 v[150:153], v199 offset:50176
	ds_read_b128 v[154:157], v199 offset:51200
	ds_read_b128 v[158:161], v199 offset:52224
	ds_read_b128 v[162:165], v199 offset:53248
	ds_read_b128 v[166:169], v199 offset:54272
	ds_read_b128 v[170:173], v199 offset:55296
	ds_read_b128 v[174:177], v199 offset:56320
	global_load_lds_dwordx4 v[216:217], off
	v_lshl_add_u64 v[216:217], v[222:223], 0, s[76:77]
	s_mov_b32 m0, s4
	s_nop 0
	global_load_lds_dwordx4 v[216:217], off
	s_setprio 1
	s_barrier
	s_waitcnt lgkmcnt(0)
	v_mfma_f32_16x16x32_bf16 v[62:65], v[130:133], v[146:149], v[62:65]
	v_mfma_f32_16x16x32_bf16 v[58:61], v[138:141], v[146:149], v[58:61]
	v_mfma_f32_16x16x32_bf16 v[54:57], v[130:133], v[154:157], v[54:57]
	v_mfma_f32_16x16x32_bf16 v[50:53], v[138:141], v[154:157], v[50:53]
	v_mfma_f32_16x16x32_bf16 v[46:49], v[130:133], v[162:165], v[46:49]
	v_mfma_f32_16x16x32_bf16 v[42:45], v[138:141], v[162:165], v[42:45]
	v_mfma_f32_16x16x32_bf16 v[38:41], v[130:133], v[170:173], v[38:41]
	v_mfma_f32_16x16x32_bf16 v[34:37], v[138:141], v[170:173], v[34:37]
	v_mfma_f32_16x16x32_bf16 v[62:65], v[134:137], v[150:153], v[62:65]
	v_mfma_f32_16x16x32_bf16 v[58:61], v[142:145], v[150:153], v[58:61]
	v_mfma_f32_16x16x32_bf16 v[54:57], v[134:137], v[158:161], v[54:57]
	v_mfma_f32_16x16x32_bf16 v[50:53], v[142:145], v[158:161], v[50:53]
	v_mfma_f32_16x16x32_bf16 v[46:49], v[134:137], v[166:169], v[46:49]
	v_mfma_f32_16x16x32_bf16 v[42:45], v[142:145], v[166:169], v[42:45]
	v_mfma_f32_16x16x32_bf16 v[38:41], v[134:137], v[174:177], v[38:41]
	v_mfma_f32_16x16x32_bf16 v[34:37], v[142:145], v[174:177], v[34:37]
	s_barrier
	s_setprio 0
	s_add_u32 s10, s52, 0x40080
	s_addc_u32 s11, s53, 0
	s_mov_b32 m0, s5
	v_lshl_add_u64 v[130:131], s[10:11], 0, v[194:195]
	global_load_lds_dwordx4 v[130:131], off
	v_lshl_add_u64 v[130:131], s[10:11], 0, v[210:211]
	s_mov_b32 m0, s58
	s_nop 0
	global_load_lds_dwordx4 v[130:131], off
	s_waitcnt vmcnt(6)
	s_setprio 1
	s_barrier
	v_mfma_f32_16x16x32_bf16 v[30:33], v[178:181], v[146:149], v[30:33]
	v_mfma_f32_16x16x32_bf16 v[26:29], v[186:189], v[146:149], v[26:29]
	v_mfma_f32_16x16x32_bf16 v[22:25], v[178:181], v[154:157], v[22:25]
	v_mfma_f32_16x16x32_bf16 v[18:21], v[186:189], v[154:157], v[18:21]
	v_mfma_f32_16x16x32_bf16 v[14:17], v[178:181], v[162:165], v[14:17]
	v_mfma_f32_16x16x32_bf16 v[10:13], v[186:189], v[162:165], v[10:13]
	v_mfma_f32_16x16x32_bf16 v[6:9], v[178:181], v[170:173], v[6:9]
	v_mfma_f32_16x16x32_bf16 v[2:5], v[186:189], v[170:173], v[2:5]
	v_mfma_f32_16x16x32_bf16 v[30:33], v[182:185], v[150:153], v[30:33]
	v_mfma_f32_16x16x32_bf16 v[26:29], v[190:193], v[150:153], v[26:29]
	v_mfma_f32_16x16x32_bf16 v[22:25], v[182:185], v[158:161], v[22:25]
	v_mfma_f32_16x16x32_bf16 v[18:21], v[190:193], v[158:161], v[18:21]
	v_mfma_f32_16x16x32_bf16 v[14:17], v[182:185], v[166:169], v[14:17]
	v_mfma_f32_16x16x32_bf16 v[10:13], v[190:193], v[166:169], v[10:13]
	v_mfma_f32_16x16x32_bf16 v[6:9], v[182:185], v[174:177], v[6:9]
	v_mfma_f32_16x16x32_bf16 v[2:5], v[190:193], v[174:177], v[2:5]
	s_setprio 0
	s_add_i32 s29, s29, 2
	s_add_u32 s8, s8, 0x100
	s_addc_u32 s9, s9, 0
	s_add_u32 s7, s7, 0x100
	s_addc_u32 s28, s28, 0
	s_cmp_gt_u32 s29, 13
	s_barrier
	s_cbranch_scc0 .LBB0_368
	s_cmp_gt_i32 s95, 1
	s_cselect_b64 s[52:53], -1, 0
	s_mul_i32 s7, s6, 0x680000
	s_lshl_b32 s8, s95, 12
	s_lshl_b32 s9, s54, 9
	s_add_i32 s7, s7, s8
	s_add_i32 s7, s7, s9
	s_add_i32 s7, s7, 0x3800
	s_add_u32 s20, s50, s7
	s_addc_u32 s21, s51, 0
	s_lshl_b32 s7, s6, 20
	s_add_i32 s7, s7, s9
	s_add_u32 s10, s96, s7
	s_addc_u32 s11, s97, 0
	s_mov_b32 s86, 0xbfb8aa3b
	s_mov_b32 s87, 0xbfb8aa3b
	v_mul_u32_u24_e32 v253, 0x6800, v197
	v_lshlrev_b32_e32 v255, 12, v197
	v_lshl_add_u32 v253, v203, 1, v253
	v_lshl_add_u32 v255, v203, 1, v255
	v_add_u32_e32 v254, 0x1000, v253
	s_cmp_eq_u32 s95, 2
	s_cbranch_scc1 .Lem_br2
	global_load_dwordx4 v[130:133], v253, s[20:21]
	global_load_dwordx4 v[134:137], v254, s[20:21]
	global_load_dwordx4 v[138:141], v253, s[20:21] offset:256
	global_load_dwordx4 v[142:145], v254, s[20:21] offset:256
	s_add_u32 s28, s20, 0x68000
	s_addc_u32 s29, s21, 0
	global_load_dwordx4 v[146:149], v253, s[28:29]
	global_load_dwordx4 v[150:153], v254, s[28:29]
	global_load_dwordx4 v[154:157], v253, s[28:29] offset:256
	global_load_dwordx4 v[158:161], v254, s[28:29] offset:256
	s_add_u32 s28, s20, 0xd0000
	s_addc_u32 s29, s21, 0
	global_load_dwordx4 v[162:165], v253, s[28:29]
	global_load_dwordx4 v[166:169], v254, s[28:29]
	global_load_dwordx4 v[170:173], v253, s[28:29] offset:256
	global_load_dwordx4 v[174:177], v254, s[28:29] offset:256
	s_add_u32 s28, s20, 0x138000
	s_addc_u32 s29, s21, 0
	global_load_dwordx4 v[178:181], v253, s[28:29]
	global_load_dwordx4 v[182:185], v254, s[28:29]
	global_load_dwordx4 v[186:189], v253, s[28:29] offset:256
	global_load_dwordx4 v[190:193], v254, s[28:29] offset:256
	s_waitcnt vmcnt(12)
	v_lshlrev_b32_e32 v216, 16, v130
	v_and_b32_e32 v217, 0xffff0000, v130
	v_lshlrev_b32_e32 v218, 16, v131
	v_and_b32_e32 v219, 0xffff0000, v131
	v_lshlrev_b32_e32 v220, 16, v132
	v_and_b32_e32 v221, 0xffff0000, v132
	v_lshlrev_b32_e32 v222, 16, v133
	v_and_b32_e32 v223, 0xffff0000, v133
	v_pk_mul_f32 v[216:217], v[216:217], s[86:87] op_sel_hi:[1,0]
	v_pk_mul_f32 v[218:219], v[218:219], s[86:87] op_sel_hi:[1,0]
	v_pk_mul_f32 v[220:221], v[220:221], s[86:87] op_sel_hi:[1,0]
	v_pk_mul_f32 v[222:223], v[222:223], s[86:87] op_sel_hi:[1,0]
	v_exp_f32_e32 v216, v216
	v_exp_f32_e32 v217, v217
	v_exp_f32_e32 v218, v218
	v_exp_f32_e32 v219, v219
	v_exp_f32_e32 v220, v220
	v_exp_f32_e32 v221, v221
	v_exp_f32_e32 v222, v222
	v_exp_f32_e32 v223, v223
	v_pk_add_f32 v[216:217], v[216:217], 1.0 op_sel_hi:[1,0]
	v_pk_add_f32 v[218:219], v[218:219], 1.0 op_sel_hi:[1,0]
	v_pk_add_f32 v[220:221], v[220:221], 1.0 op_sel_hi:[1,0]
	v_pk_add_f32 v[222:223], v[222:223], 1.0 op_sel_hi:[1,0]
	v_rcp_f32_e32 v216, v216
	v_rcp_f32_e32 v217, v217
	v_rcp_f32_e32 v218, v218
	v_rcp_f32_e32 v219, v219
	v_rcp_f32_e32 v220, v220
	v_rcp_f32_e32 v221, v221
	v_rcp_f32_e32 v222, v222
	v_rcp_f32_e32 v223, v223
	v_lshlrev_b32_e32 v242, 16, v134
	v_and_b32_e32 v243, 0xffff0000, v134
	v_lshlrev_b32_e32 v244, 16, v135
	v_and_b32_e32 v245, 0xffff0000, v135
	v_lshlrev_b32_e32 v246, 16, v136
	v_and_b32_e32 v247, 0xffff0000, v136
	v_lshlrev_b32_e32 v248, 16, v137
	v_and_b32_e32 v249, 0xffff0000, v137
	v_pk_mul_f32 v[242:243], v[242:243], s[86:87] op_sel_hi:[1,0]
	v_pk_mul_f32 v[244:245], v[244:245], s[86:87] op_sel_hi:[1,0]
	v_pk_mul_f32 v[246:247], v[246:247], s[86:87] op_sel_hi:[1,0]
	v_pk_mul_f32 v[248:249], v[248:249], s[86:87] op_sel_hi:[1,0]
	v_exp_f32_e32 v242, v242
	v_exp_f32_e32 v243, v243
	v_exp_f32_e32 v244, v244
	v_exp_f32_e32 v245, v245
	v_exp_f32_e32 v246, v246
	v_exp_f32_e32 v247, v247
	v_exp_f32_e32 v248, v248
	v_exp_f32_e32 v249, v249
	v_pk_add_f32 v[242:243], v[242:243], 1.0 op_sel_hi:[1,0]
	v_pk_add_f32 v[244:245], v[244:245], 1.0 op_sel_hi:[1,0]
	v_pk_add_f32 v[246:247], v[246:247], 1.0 op_sel_hi:[1,0]
	v_pk_add_f32 v[248:249], v[248:249], 1.0 op_sel_hi:[1,0]
	v_pk_mul_f32 v[216:217], v[216:217], v[242:243]
	v_pk_mul_f32 v[218:219], v[218:219], v[244:245]
	v_pk_mul_f32 v[220:221], v[220:221], v[246:247]
	v_pk_mul_f32 v[222:223], v[222:223], v[248:249]
	v_pk_mul_f32 v[126:127], v[126:127], v[216:217]
	v_pk_mul_f32 v[128:129], v[128:129], v[218:219]
	v_pk_mul_f32 v[122:123], v[122:123], v[220:221]
	v_pk_mul_f32 v[124:125], v[124:125], v[222:223]
	v_lshlrev_b32_e32 v216, 16, v138
	v_and_b32_e32 v217, 0xffff0000, v138
	v_lshlrev_b32_e32 v218, 16, v139
	v_and_b32_e32 v219, 0xffff0000, v139
	v_lshlrev_b32_e32 v220, 16, v140
	v_and_b32_e32 v221, 0xffff0000, v140
	v_lshlrev_b32_e32 v222, 16, v141
	v_and_b32_e32 v223, 0xffff0000, v141
	v_pk_mul_f32 v[216:217], v[216:217], s[86:87] op_sel_hi:[1,0]
	v_pk_mul_f32 v[218:219], v[218:219], s[86:87] op_sel_hi:[1,0]
	v_pk_mul_f32 v[220:221], v[220:221], s[86:87] op_sel_hi:[1,0]
	v_pk_mul_f32 v[222:223], v[222:223], s[86:87] op_sel_hi:[1,0]
	v_exp_f32_e32 v216, v216
	v_exp_f32_e32 v217, v217
	v_exp_f32_e32 v218, v218
	v_exp_f32_e32 v219, v219
	v_exp_f32_e32 v220, v220
	v_exp_f32_e32 v221, v221
	v_exp_f32_e32 v222, v222
	v_exp_f32_e32 v223, v223
	v_pk_add_f32 v[216:217], v[216:217], 1.0 op_sel_hi:[1,0]
	v_pk_add_f32 v[218:219], v[218:219], 1.0 op_sel_hi:[1,0]
	v_pk_add_f32 v[220:221], v[220:221], 1.0 op_sel_hi:[1,0]
	v_pk_add_f32 v[222:223], v[222:223], 1.0 op_sel_hi:[1,0]
	v_rcp_f32_e32 v216, v216
	v_rcp_f32_e32 v217, v217
	v_rcp_f32_e32 v218, v218
	v_rcp_f32_e32 v219, v219
	v_rcp_f32_e32 v220, v220
	v_rcp_f32_e32 v221, v221
	v_rcp_f32_e32 v222, v222
	v_rcp_f32_e32 v223, v223
	v_lshlrev_b32_e32 v242, 16, v142
	v_and_b32_e32 v243, 0xffff0000, v142
	v_lshlrev_b32_e32 v244, 16, v143
	v_and_b32_e32 v245, 0xffff0000, v143
	v_lshlrev_b32_e32 v246, 16, v144
	v_and_b32_e32 v247, 0xffff0000, v144
	v_lshlrev_b32_e32 v248, 16, v145
	v_and_b32_e32 v249, 0xffff0000, v145
	v_pk_mul_f32 v[242:243], v[242:243], s[86:87] op_sel_hi:[1,0]
	v_pk_mul_f32 v[244:245], v[244:245], s[86:87] op_sel_hi:[1,0]
	v_pk_mul_f32 v[246:247], v[246:247], s[86:87] op_sel_hi:[1,0]
	v_pk_mul_f32 v[248:249], v[248:249], s[86:87] op_sel_hi:[1,0]
	v_exp_f32_e32 v242, v242
	v_exp_f32_e32 v243, v243
	v_exp_f32_e32 v244, v244
	v_exp_f32_e32 v245, v245
	v_exp_f32_e32 v246, v246
	v_exp_f32_e32 v247, v247
	v_exp_f32_e32 v248, v248
	v_exp_f32_e32 v249, v249
	v_pk_add_f32 v[242:243], v[242:243], 1.0 op_sel_hi:[1,0]
	v_pk_add_f32 v[244:245], v[244:245], 1.0 op_sel_hi:[1,0]
	v_pk_add_f32 v[246:247], v[246:247], 1.0 op_sel_hi:[1,0]
	v_pk_add_f32 v[248:249], v[248:249], 1.0 op_sel_hi:[1,0]
	v_pk_mul_f32 v[216:217], v[216:217], v[242:243]
	v_pk_mul_f32 v[218:219], v[218:219], v[244:245]
	v_pk_mul_f32 v[220:221], v[220:221], v[246:247]
	v_pk_mul_f32 v[222:223], v[222:223], v[248:249]
	v_pk_mul_f32 v[94:95], v[94:95], v[216:217]
	v_pk_mul_f32 v[96:97], v[96:97], v[218:219]
	v_pk_mul_f32 v[90:91], v[90:91], v[220:221]
	v_pk_mul_f32 v[92:93], v[92:93], v[222:223]
	s_add_u32 s28, s20, 0x340000
	s_addc_u32 s29, s21, 0
	global_load_dwordx4 v[130:133], v253, s[28:29]
	global_load_dwordx4 v[134:137], v254, s[28:29]
	global_load_dwordx4 v[138:141], v253, s[28:29] offset:256
	global_load_dwordx4 v[142:145], v254, s[28:29] offset:256
	s_waitcnt vmcnt(12)
	v_lshlrev_b32_e32 v216, 16, v146
	v_and_b32_e32 v217, 0xffff0000, v146
	v_lshlrev_b32_e32 v218, 16, v147
	v_and_b32_e32 v219, 0xffff0000, v147
	v_lshlrev_b32_e32 v220, 16, v148
	v_and_b32_e32 v221, 0xffff0000, v148
	v_lshlrev_b32_e32 v222, 16, v149
	v_and_b32_e32 v223, 0xffff0000, v149
	v_pk_mul_f32 v[216:217], v[216:217], s[86:87] op_sel_hi:[1,0]
	v_pk_mul_f32 v[218:219], v[218:219], s[86:87] op_sel_hi:[1,0]
	v_pk_mul_f32 v[220:221], v[220:221], s[86:87] op_sel_hi:[1,0]
	v_pk_mul_f32 v[222:223], v[222:223], s[86:87] op_sel_hi:[1,0]
	v_exp_f32_e32 v216, v216
	v_exp_f32_e32 v217, v217
	v_exp_f32_e32 v218, v218
	v_exp_f32_e32 v219, v219
	v_exp_f32_e32 v220, v220
	v_exp_f32_e32 v221, v221
	v_exp_f32_e32 v222, v222
	v_exp_f32_e32 v223, v223
	v_pk_add_f32 v[216:217], v[216:217], 1.0 op_sel_hi:[1,0]
	v_pk_add_f32 v[218:219], v[218:219], 1.0 op_sel_hi:[1,0]
	v_pk_add_f32 v[220:221], v[220:221], 1.0 op_sel_hi:[1,0]
	v_pk_add_f32 v[222:223], v[222:223], 1.0 op_sel_hi:[1,0]
	v_rcp_f32_e32 v216, v216
	v_rcp_f32_e32 v217, v217
	v_rcp_f32_e32 v218, v218
	v_rcp_f32_e32 v219, v219
	v_rcp_f32_e32 v220, v220
	v_rcp_f32_e32 v221, v221
	v_rcp_f32_e32 v222, v222
	v_rcp_f32_e32 v223, v223
	v_lshlrev_b32_e32 v242, 16, v150
	v_and_b32_e32 v243, 0xffff0000, v150
	v_lshlrev_b32_e32 v244, 16, v151
	v_and_b32_e32 v245, 0xffff0000, v151
	v_lshlrev_b32_e32 v246, 16, v152
	v_and_b32_e32 v247, 0xffff0000, v152
	v_lshlrev_b32_e32 v248, 16, v153
	v_and_b32_e32 v249, 0xffff0000, v153
	v_pk_mul_f32 v[242:243], v[242:243], s[86:87] op_sel_hi:[1,0]
	v_pk_mul_f32 v[244:245], v[244:245], s[86:87] op_sel_hi:[1,0]
	v_pk_mul_f32 v[246:247], v[246:247], s[86:87] op_sel_hi:[1,0]
	v_pk_mul_f32 v[248:249], v[248:249], s[86:87] op_sel_hi:[1,0]
	v_exp_f32_e32 v242, v242
	v_exp_f32_e32 v243, v243
	v_exp_f32_e32 v244, v244
	v_exp_f32_e32 v245, v245
	v_exp_f32_e32 v246, v246
	v_exp_f32_e32 v247, v247
	v_exp_f32_e32 v248, v248
	v_exp_f32_e32 v249, v249
	v_pk_add_f32 v[242:243], v[242:243], 1.0 op_sel_hi:[1,0]
	v_pk_add_f32 v[244:245], v[244:245], 1.0 op_sel_hi:[1,0]
	v_pk_add_f32 v[246:247], v[246:247], 1.0 op_sel_hi:[1,0]
	v_pk_add_f32 v[248:249], v[248:249], 1.0 op_sel_hi:[1,0]
	v_pk_mul_f32 v[216:217], v[216:217], v[242:243]
	v_pk_mul_f32 v[218:219], v[218:219], v[244:245]
	v_pk_mul_f32 v[220:221], v[220:221], v[246:247]
	v_pk_mul_f32 v[222:223], v[222:223], v[248:249]
	v_pk_mul_f32 v[118:119], v[118:119], v[216:217]
	v_pk_mul_f32 v[120:121], v[120:121], v[218:219]
	v_pk_mul_f32 v[114:115], v[114:115], v[220:221]
	v_pk_mul_f32 v[116:117], v[116:117], v[222:223]
	v_lshlrev_b32_e32 v216, 16, v154
	v_and_b32_e32 v217, 0xffff0000, v154
	v_lshlrev_b32_e32 v218, 16, v155
	v_and_b32_e32 v219, 0xffff0000, v155
	v_lshlrev_b32_e32 v220, 16, v156
	v_and_b32_e32 v221, 0xffff0000, v156
	v_lshlrev_b32_e32 v222, 16, v157
	v_and_b32_e32 v223, 0xffff0000, v157
	v_pk_mul_f32 v[216:217], v[216:217], s[86:87] op_sel_hi:[1,0]
	v_pk_mul_f32 v[218:219], v[218:219], s[86:87] op_sel_hi:[1,0]
	v_pk_mul_f32 v[220:221], v[220:221], s[86:87] op_sel_hi:[1,0]
	v_pk_mul_f32 v[222:223], v[222:223], s[86:87] op_sel_hi:[1,0]
	v_exp_f32_e32 v216, v216
	v_exp_f32_e32 v217, v217
	v_exp_f32_e32 v218, v218
	v_exp_f32_e32 v219, v219
	v_exp_f32_e32 v220, v220
	v_exp_f32_e32 v221, v221
	v_exp_f32_e32 v222, v222
	v_exp_f32_e32 v223, v223
	v_pk_add_f32 v[216:217], v[216:217], 1.0 op_sel_hi:[1,0]
	v_pk_add_f32 v[218:219], v[218:219], 1.0 op_sel_hi:[1,0]
	v_pk_add_f32 v[220:221], v[220:221], 1.0 op_sel_hi:[1,0]
	v_pk_add_f32 v[222:223], v[222:223], 1.0 op_sel_hi:[1,0]
	v_rcp_f32_e32 v216, v216
	v_rcp_f32_e32 v217, v217
	v_rcp_f32_e32 v218, v218
	v_rcp_f32_e32 v219, v219
	v_rcp_f32_e32 v220, v220
	v_rcp_f32_e32 v221, v221
	v_rcp_f32_e32 v222, v222
	v_rcp_f32_e32 v223, v223
	v_lshlrev_b32_e32 v242, 16, v158
	v_and_b32_e32 v243, 0xffff0000, v158
	v_lshlrev_b32_e32 v244, 16, v159
	v_and_b32_e32 v245, 0xffff0000, v159
	v_lshlrev_b32_e32 v246, 16, v160
	v_and_b32_e32 v247, 0xffff0000, v160
	v_lshlrev_b32_e32 v248, 16, v161
	v_and_b32_e32 v249, 0xffff0000, v161
	v_pk_mul_f32 v[242:243], v[242:243], s[86:87] op_sel_hi:[1,0]
	v_pk_mul_f32 v[244:245], v[244:245], s[86:87] op_sel_hi:[1,0]
	v_pk_mul_f32 v[246:247], v[246:247], s[86:87] op_sel_hi:[1,0]
	v_pk_mul_f32 v[248:249], v[248:249], s[86:87] op_sel_hi:[1,0]
	v_exp_f32_e32 v242, v242
	v_exp_f32_e32 v243, v243
	v_exp_f32_e32 v244, v244
	v_exp_f32_e32 v245, v245
	v_exp_f32_e32 v246, v246
	v_exp_f32_e32 v247, v247
	v_exp_f32_e32 v248, v248
	v_exp_f32_e32 v249, v249
	v_pk_add_f32 v[242:243], v[242:243], 1.0 op_sel_hi:[1,0]
	v_pk_add_f32 v[244:245], v[244:245], 1.0 op_sel_hi:[1,0]
	v_pk_add_f32 v[246:247], v[246:247], 1.0 op_sel_hi:[1,0]
	v_pk_add_f32 v[248:249], v[248:249], 1.0 op_sel_hi:[1,0]
	v_pk_mul_f32 v[216:217], v[216:217], v[242:243]
	v_pk_mul_f32 v[218:219], v[218:219], v[244:245]
	v_pk_mul_f32 v[220:221], v[220:221], v[246:247]
	v_pk_mul_f32 v[222:223], v[222:223], v[248:249]
	v_pk_mul_f32 v[86:87], v[86:87], v[216:217]
	v_pk_mul_f32 v[88:89], v[88:89], v[218:219]
	v_pk_mul_f32 v[82:83], v[82:83], v[220:221]
	v_pk_mul_f32 v[84:85], v[84:85], v[222:223]
	s_add_u32 s28, s20, 0x3a8000
	s_addc_u32 s29, s21, 0
	global_load_dwordx4 v[146:149], v253, s[28:29]
	global_load_dwordx4 v[150:153], v254, s[28:29]
	global_load_dwordx4 v[154:157], v253, s[28:29] offset:256
	global_load_dwordx4 v[158:161], v254, s[28:29] offset:256
	s_waitcnt vmcnt(12)
	v_lshlrev_b32_e32 v216, 16, v162
	v_and_b32_e32 v217, 0xffff0000, v162
	v_lshlrev_b32_e32 v218, 16, v163
	v_and_b32_e32 v219, 0xffff0000, v163
	v_lshlrev_b32_e32 v220, 16, v164
	v_and_b32_e32 v221, 0xffff0000, v164
	v_lshlrev_b32_e32 v222, 16, v165
	v_and_b32_e32 v223, 0xffff0000, v165
	v_pk_mul_f32 v[216:217], v[216:217], s[86:87] op_sel_hi:[1,0]
	v_pk_mul_f32 v[218:219], v[218:219], s[86:87] op_sel_hi:[1,0]
	v_pk_mul_f32 v[220:221], v[220:221], s[86:87] op_sel_hi:[1,0]
	v_pk_mul_f32 v[222:223], v[222:223], s[86:87] op_sel_hi:[1,0]
	v_exp_f32_e32 v216, v216
	v_exp_f32_e32 v217, v217
	v_exp_f32_e32 v218, v218
	v_exp_f32_e32 v219, v219
	v_exp_f32_e32 v220, v220
	v_exp_f32_e32 v221, v221
	v_exp_f32_e32 v222, v222
	v_exp_f32_e32 v223, v223
	v_pk_add_f32 v[216:217], v[216:217], 1.0 op_sel_hi:[1,0]
	v_pk_add_f32 v[218:219], v[218:219], 1.0 op_sel_hi:[1,0]
	v_pk_add_f32 v[220:221], v[220:221], 1.0 op_sel_hi:[1,0]
	v_pk_add_f32 v[222:223], v[222:223], 1.0 op_sel_hi:[1,0]
	v_rcp_f32_e32 v216, v216
	v_rcp_f32_e32 v217, v217
	v_rcp_f32_e32 v218, v218
	v_rcp_f32_e32 v219, v219
	v_rcp_f32_e32 v220, v220
	v_rcp_f32_e32 v221, v221
	v_rcp_f32_e32 v222, v222
	v_rcp_f32_e32 v223, v223
	v_lshlrev_b32_e32 v242, 16, v166
	v_and_b32_e32 v243, 0xffff0000, v166
	v_lshlrev_b32_e32 v244, 16, v167
	v_and_b32_e32 v245, 0xffff0000, v167
	v_lshlrev_b32_e32 v246, 16, v168
	v_and_b32_e32 v247, 0xffff0000, v168
	v_lshlrev_b32_e32 v248, 16, v169
	v_and_b32_e32 v249, 0xffff0000, v169
	v_pk_mul_f32 v[242:243], v[242:243], s[86:87] op_sel_hi:[1,0]
	v_pk_mul_f32 v[244:245], v[244:245], s[86:87] op_sel_hi:[1,0]
	v_pk_mul_f32 v[246:247], v[246:247], s[86:87] op_sel_hi:[1,0]
	v_pk_mul_f32 v[248:249], v[248:249], s[86:87] op_sel_hi:[1,0]
	v_exp_f32_e32 v242, v242
	v_exp_f32_e32 v243, v243
	v_exp_f32_e32 v244, v244
	v_exp_f32_e32 v245, v245
	v_exp_f32_e32 v246, v246
	v_exp_f32_e32 v247, v247
	v_exp_f32_e32 v248, v248
	v_exp_f32_e32 v249, v249
	v_pk_add_f32 v[242:243], v[242:243], 1.0 op_sel_hi:[1,0]
	v_pk_add_f32 v[244:245], v[244:245], 1.0 op_sel_hi:[1,0]
	v_pk_add_f32 v[246:247], v[246:247], 1.0 op_sel_hi:[1,0]
	v_pk_add_f32 v[248:249], v[248:249], 1.0 op_sel_hi:[1,0]
	v_pk_mul_f32 v[216:217], v[216:217], v[242:243]
	v_pk_mul_f32 v[218:219], v[218:219], v[244:245]
	v_pk_mul_f32 v[220:221], v[220:221], v[246:247]
	v_pk_mul_f32 v[222:223], v[222:223], v[248:249]
	v_pk_mul_f32 v[110:111], v[110:111], v[216:217]
	v_pk_mul_f32 v[112:113], v[112:113], v[218:219]
	v_pk_mul_f32 v[106:107], v[106:107], v[220:221]
	v_pk_mul_f32 v[108:109], v[108:109], v[222:223]
	v_lshlrev_b32_e32 v216, 16, v170
	v_and_b32_e32 v217, 0xffff0000, v170
	v_lshlrev_b32_e32 v218, 16, v171
	v_and_b32_e32 v219, 0xffff0000, v171
	v_lshlrev_b32_e32 v220, 16, v172
	v_and_b32_e32 v221, 0xffff0000, v172
	v_lshlrev_b32_e32 v222, 16, v173
	v_and_b32_e32 v223, 0xffff0000, v173
	v_pk_mul_f32 v[216:217], v[216:217], s[86:87] op_sel_hi:[1,0]
	v_pk_mul_f32 v[218:219], v[218:219], s[86:87] op_sel_hi:[1,0]
	v_pk_mul_f32 v[220:221], v[220:221], s[86:87] op_sel_hi:[1,0]
	v_pk_mul_f32 v[222:223], v[222:223], s[86:87] op_sel_hi:[1,0]
	v_exp_f32_e32 v216, v216
	v_exp_f32_e32 v217, v217
	v_exp_f32_e32 v218, v218
	v_exp_f32_e32 v219, v219
	v_exp_f32_e32 v220, v220
	v_exp_f32_e32 v221, v221
	v_exp_f32_e32 v222, v222
	v_exp_f32_e32 v223, v223
	v_pk_add_f32 v[216:217], v[216:217], 1.0 op_sel_hi:[1,0]
	v_pk_add_f32 v[218:219], v[218:219], 1.0 op_sel_hi:[1,0]
	v_pk_add_f32 v[220:221], v[220:221], 1.0 op_sel_hi:[1,0]
	v_pk_add_f32 v[222:223], v[222:223], 1.0 op_sel_hi:[1,0]
	v_rcp_f32_e32 v216, v216
	v_rcp_f32_e32 v217, v217
	v_rcp_f32_e32 v218, v218
	v_rcp_f32_e32 v219, v219
	v_rcp_f32_e32 v220, v220
	v_rcp_f32_e32 v221, v221
	v_rcp_f32_e32 v222, v222
	v_rcp_f32_e32 v223, v223
	v_lshlrev_b32_e32 v242, 16, v174
	v_and_b32_e32 v243, 0xffff0000, v174
	v_lshlrev_b32_e32 v244, 16, v175
	v_and_b32_e32 v245, 0xffff0000, v175
	v_lshlrev_b32_e32 v246, 16, v176
	v_and_b32_e32 v247, 0xffff0000, v176
	v_lshlrev_b32_e32 v248, 16, v177
	v_and_b32_e32 v249, 0xffff0000, v177
	v_pk_mul_f32 v[242:243], v[242:243], s[86:87] op_sel_hi:[1,0]
	v_pk_mul_f32 v[244:245], v[244:245], s[86:87] op_sel_hi:[1,0]
	v_pk_mul_f32 v[246:247], v[246:247], s[86:87] op_sel_hi:[1,0]
	v_pk_mul_f32 v[248:249], v[248:249], s[86:87] op_sel_hi:[1,0]
	v_exp_f32_e32 v242, v242
	v_exp_f32_e32 v243, v243
	v_exp_f32_e32 v244, v244
	v_exp_f32_e32 v245, v245
	v_exp_f32_e32 v246, v246
	v_exp_f32_e32 v247, v247
	v_exp_f32_e32 v248, v248
	v_exp_f32_e32 v249, v249
	v_pk_add_f32 v[242:243], v[242:243], 1.0 op_sel_hi:[1,0]
	v_pk_add_f32 v[244:245], v[244:245], 1.0 op_sel_hi:[1,0]
	v_pk_add_f32 v[246:247], v[246:247], 1.0 op_sel_hi:[1,0]
	v_pk_add_f32 v[248:249], v[248:249], 1.0 op_sel_hi:[1,0]
	v_pk_mul_f32 v[216:217], v[216:217], v[242:243]
	v_pk_mul_f32 v[218:219], v[218:219], v[244:245]
	v_pk_mul_f32 v[220:221], v[220:221], v[246:247]
	v_pk_mul_f32 v[222:223], v[222:223], v[248:249]
	v_pk_mul_f32 v[78:79], v[78:79], v[216:217]
	v_pk_mul_f32 v[80:81], v[80:81], v[218:219]
	v_pk_mul_f32 v[74:75], v[74:75], v[220:221]
	v_pk_mul_f32 v[76:77], v[76:77], v[222:223]
	s_add_u32 s28, s20, 0x410000
	s_addc_u32 s29, s21, 0
	global_load_dwordx4 v[162:165], v253, s[28:29]
	global_load_dwordx4 v[166:169], v254, s[28:29]
	global_load_dwordx4 v[170:173], v253, s[28:29] offset:256
	global_load_dwordx4 v[174:177], v254, s[28:29] offset:256
	s_waitcnt vmcnt(12)
	v_lshlrev_b32_e32 v216, 16, v178
	v_and_b32_e32 v217, 0xffff0000, v178
	v_lshlrev_b32_e32 v218, 16, v179
	v_and_b32_e32 v219, 0xffff0000, v179
	v_lshlrev_b32_e32 v220, 16, v180
	v_and_b32_e32 v221, 0xffff0000, v180
	v_lshlrev_b32_e32 v222, 16, v181
	v_and_b32_e32 v223, 0xffff0000, v181
	v_pk_mul_f32 v[216:217], v[216:217], s[86:87] op_sel_hi:[1,0]
	v_pk_mul_f32 v[218:219], v[218:219], s[86:87] op_sel_hi:[1,0]
	v_pk_mul_f32 v[220:221], v[220:221], s[86:87] op_sel_hi:[1,0]
	v_pk_mul_f32 v[222:223], v[222:223], s[86:87] op_sel_hi:[1,0]
	v_exp_f32_e32 v216, v216
	v_exp_f32_e32 v217, v217
	v_exp_f32_e32 v218, v218
	v_exp_f32_e32 v219, v219
	v_exp_f32_e32 v220, v220
	v_exp_f32_e32 v221, v221
	v_exp_f32_e32 v222, v222
	v_exp_f32_e32 v223, v223
	v_pk_add_f32 v[216:217], v[216:217], 1.0 op_sel_hi:[1,0]
	v_pk_add_f32 v[218:219], v[218:219], 1.0 op_sel_hi:[1,0]
	v_pk_add_f32 v[220:221], v[220:221], 1.0 op_sel_hi:[1,0]
	v_pk_add_f32 v[222:223], v[222:223], 1.0 op_sel_hi:[1,0]
	v_rcp_f32_e32 v216, v216
	v_rcp_f32_e32 v217, v217
	v_rcp_f32_e32 v218, v218
	v_rcp_f32_e32 v219, v219
	v_rcp_f32_e32 v220, v220
	v_rcp_f32_e32 v221, v221
	v_rcp_f32_e32 v222, v222
	v_rcp_f32_e32 v223, v223
	v_lshlrev_b32_e32 v242, 16, v182
	v_and_b32_e32 v243, 0xffff0000, v182
	v_lshlrev_b32_e32 v244, 16, v183
	v_and_b32_e32 v245, 0xffff0000, v183
	v_lshlrev_b32_e32 v246, 16, v184
	v_and_b32_e32 v247, 0xffff0000, v184
	v_lshlrev_b32_e32 v248, 16, v185
	v_and_b32_e32 v249, 0xffff0000, v185
	v_pk_mul_f32 v[242:243], v[242:243], s[86:87] op_sel_hi:[1,0]
	v_pk_mul_f32 v[244:245], v[244:245], s[86:87] op_sel_hi:[1,0]
	v_pk_mul_f32 v[246:247], v[246:247], s[86:87] op_sel_hi:[1,0]
	v_pk_mul_f32 v[248:249], v[248:249], s[86:87] op_sel_hi:[1,0]
	v_exp_f32_e32 v242, v242
	v_exp_f32_e32 v243, v243
	v_exp_f32_e32 v244, v244
	v_exp_f32_e32 v245, v245
	v_exp_f32_e32 v246, v246
	v_exp_f32_e32 v247, v247
	v_exp_f32_e32 v248, v248
	v_exp_f32_e32 v249, v249
	v_pk_add_f32 v[242:243], v[242:243], 1.0 op_sel_hi:[1,0]
	v_pk_add_f32 v[244:245], v[244:245], 1.0 op_sel_hi:[1,0]
	v_pk_add_f32 v[246:247], v[246:247], 1.0 op_sel_hi:[1,0]
	v_pk_add_f32 v[248:249], v[248:249], 1.0 op_sel_hi:[1,0]
	v_pk_mul_f32 v[216:217], v[216:217], v[242:243]
	v_pk_mul_f32 v[218:219], v[218:219], v[244:245]
	v_pk_mul_f32 v[220:221], v[220:221], v[246:247]
	v_pk_mul_f32 v[222:223], v[222:223], v[248:249]
	v_pk_mul_f32 v[102:103], v[102:103], v[216:217]
	v_pk_mul_f32 v[104:105], v[104:105], v[218:219]
	v_pk_mul_f32 v[98:99], v[98:99], v[220:221]
	v_pk_mul_f32 v[100:101], v[100:101], v[222:223]
	v_lshlrev_b32_e32 v216, 16, v186
	v_and_b32_e32 v217, 0xffff0000, v186
	v_lshlrev_b32_e32 v218, 16, v187
	v_and_b32_e32 v219, 0xffff0000, v187
	v_lshlrev_b32_e32 v220, 16, v188
	v_and_b32_e32 v221, 0xffff0000, v188
	v_lshlrev_b32_e32 v222, 16, v189
	v_and_b32_e32 v223, 0xffff0000, v189
	v_pk_mul_f32 v[216:217], v[216:217], s[86:87] op_sel_hi:[1,0]
	v_pk_mul_f32 v[218:219], v[218:219], s[86:87] op_sel_hi:[1,0]
	v_pk_mul_f32 v[220:221], v[220:221], s[86:87] op_sel_hi:[1,0]
	v_pk_mul_f32 v[222:223], v[222:223], s[86:87] op_sel_hi:[1,0]
	v_exp_f32_e32 v216, v216
	v_exp_f32_e32 v217, v217
	v_exp_f32_e32 v218, v218
	v_exp_f32_e32 v219, v219
	v_exp_f32_e32 v220, v220
	v_exp_f32_e32 v221, v221
	v_exp_f32_e32 v222, v222
	v_exp_f32_e32 v223, v223
	v_pk_add_f32 v[216:217], v[216:217], 1.0 op_sel_hi:[1,0]
	v_pk_add_f32 v[218:219], v[218:219], 1.0 op_sel_hi:[1,0]
	v_pk_add_f32 v[220:221], v[220:221], 1.0 op_sel_hi:[1,0]
	v_pk_add_f32 v[222:223], v[222:223], 1.0 op_sel_hi:[1,0]
	v_rcp_f32_e32 v216, v216
	v_rcp_f32_e32 v217, v217
	v_rcp_f32_e32 v218, v218
	v_rcp_f32_e32 v219, v219
	v_rcp_f32_e32 v220, v220
	v_rcp_f32_e32 v221, v221
	v_rcp_f32_e32 v222, v222
	v_rcp_f32_e32 v223, v223
	v_lshlrev_b32_e32 v242, 16, v190
	v_and_b32_e32 v243, 0xffff0000, v190
	v_lshlrev_b32_e32 v244, 16, v191
	v_and_b32_e32 v245, 0xffff0000, v191
	v_lshlrev_b32_e32 v246, 16, v192
	v_and_b32_e32 v247, 0xffff0000, v192
	v_lshlrev_b32_e32 v248, 16, v193
	v_and_b32_e32 v249, 0xffff0000, v193
	v_pk_mul_f32 v[242:243], v[242:243], s[86:87] op_sel_hi:[1,0]
	v_pk_mul_f32 v[244:245], v[244:245], s[86:87] op_sel_hi:[1,0]
	v_pk_mul_f32 v[246:247], v[246:247], s[86:87] op_sel_hi:[1,0]
	v_pk_mul_f32 v[248:249], v[248:249], s[86:87] op_sel_hi:[1,0]
	v_exp_f32_e32 v242, v242
	v_exp_f32_e32 v243, v243
	v_exp_f32_e32 v244, v244
	v_exp_f32_e32 v245, v245
	v_exp_f32_e32 v246, v246
	v_exp_f32_e32 v247, v247
	v_exp_f32_e32 v248, v248
	v_exp_f32_e32 v249, v249
	v_pk_add_f32 v[242:243], v[242:243], 1.0 op_sel_hi:[1,0]
	v_pk_add_f32 v[244:245], v[244:245], 1.0 op_sel_hi:[1,0]
	v_pk_add_f32 v[246:247], v[246:247], 1.0 op_sel_hi:[1,0]
	v_pk_add_f32 v[248:249], v[248:249], 1.0 op_sel_hi:[1,0]
	v_pk_mul_f32 v[216:217], v[216:217], v[242:243]
	v_pk_mul_f32 v[218:219], v[218:219], v[244:245]
	v_pk_mul_f32 v[220:221], v[220:221], v[246:247]
	v_pk_mul_f32 v[222:223], v[222:223], v[248:249]
	v_pk_mul_f32 v[70:71], v[70:71], v[216:217]
	v_pk_mul_f32 v[72:73], v[72:73], v[218:219]
	v_pk_mul_f32 v[66:67], v[66:67], v[220:221]
	v_pk_mul_f32 v[68:69], v[68:69], v[222:223]
	s_add_u32 s28, s20, 0x478000
	s_addc_u32 s29, s21, 0
	global_load_dwordx4 v[178:181], v253, s[28:29]
	global_load_dwordx4 v[182:185], v254, s[28:29]
	global_load_dwordx4 v[186:189], v253, s[28:29] offset:256
	global_load_dwordx4 v[190:193], v254, s[28:29] offset:256
	s_waitcnt vmcnt(12)
	v_lshlrev_b32_e32 v216, 16, v130
	v_and_b32_e32 v217, 0xffff0000, v130
	v_lshlrev_b32_e32 v218, 16, v131
	v_and_b32_e32 v219, 0xffff0000, v131
	v_lshlrev_b32_e32 v220, 16, v132
	v_and_b32_e32 v221, 0xffff0000, v132
	v_lshlrev_b32_e32 v222, 16, v133
	v_and_b32_e32 v223, 0xffff0000, v133
	v_pk_mul_f32 v[216:217], v[216:217], s[86:87] op_sel_hi:[1,0]
	v_pk_mul_f32 v[218:219], v[218:219], s[86:87] op_sel_hi:[1,0]
	v_pk_mul_f32 v[220:221], v[220:221], s[86:87] op_sel_hi:[1,0]
	v_pk_mul_f32 v[222:223], v[222:223], s[86:87] op_sel_hi:[1,0]
	v_exp_f32_e32 v216, v216
	v_exp_f32_e32 v217, v217
	v_exp_f32_e32 v218, v218
	v_exp_f32_e32 v219, v219
	v_exp_f32_e32 v220, v220
	v_exp_f32_e32 v221, v221
	v_exp_f32_e32 v222, v222
	v_exp_f32_e32 v223, v223
	v_pk_add_f32 v[216:217], v[216:217], 1.0 op_sel_hi:[1,0]
	v_pk_add_f32 v[218:219], v[218:219], 1.0 op_sel_hi:[1,0]
	v_pk_add_f32 v[220:221], v[220:221], 1.0 op_sel_hi:[1,0]
	v_pk_add_f32 v[222:223], v[222:223], 1.0 op_sel_hi:[1,0]
	v_rcp_f32_e32 v216, v216
	v_rcp_f32_e32 v217, v217
	v_rcp_f32_e32 v218, v218
	v_rcp_f32_e32 v219, v219
	v_rcp_f32_e32 v220, v220
	v_rcp_f32_e32 v221, v221
	v_rcp_f32_e32 v222, v222
	v_rcp_f32_e32 v223, v223
	v_lshlrev_b32_e32 v242, 16, v134
	v_and_b32_e32 v243, 0xffff0000, v134
	v_lshlrev_b32_e32 v244, 16, v135
	v_and_b32_e32 v245, 0xffff0000, v135
	v_lshlrev_b32_e32 v246, 16, v136
	v_and_b32_e32 v247, 0xffff0000, v136
	v_lshlrev_b32_e32 v248, 16, v137
	v_and_b32_e32 v249, 0xffff0000, v137
	v_pk_mul_f32 v[242:243], v[242:243], s[86:87] op_sel_hi:[1,0]
	v_pk_mul_f32 v[244:245], v[244:245], s[86:87] op_sel_hi:[1,0]
	v_pk_mul_f32 v[246:247], v[246:247], s[86:87] op_sel_hi:[1,0]
	v_pk_mul_f32 v[248:249], v[248:249], s[86:87] op_sel_hi:[1,0]
	v_exp_f32_e32 v242, v242
	v_exp_f32_e32 v243, v243
	v_exp_f32_e32 v244, v244
	v_exp_f32_e32 v245, v245
	v_exp_f32_e32 v246, v246
	v_exp_f32_e32 v247, v247
	v_exp_f32_e32 v248, v248
	v_exp_f32_e32 v249, v249
	v_pk_add_f32 v[242:243], v[242:243], 1.0 op_sel_hi:[1,0]
	v_pk_add_f32 v[244:245], v[244:245], 1.0 op_sel_hi:[1,0]
	v_pk_add_f32 v[246:247], v[246:247], 1.0 op_sel_hi:[1,0]
	v_pk_add_f32 v[248:249], v[248:249], 1.0 op_sel_hi:[1,0]
	v_pk_mul_f32 v[216:217], v[216:217], v[242:243]
	v_pk_mul_f32 v[218:219], v[218:219], v[244:245]
	v_pk_mul_f32 v[220:221], v[220:221], v[246:247]
	v_pk_mul_f32 v[222:223], v[222:223], v[248:249]
	v_pk_mul_f32 v[62:63], v[62:63], v[216:217]
	v_pk_mul_f32 v[64:65], v[64:65], v[218:219]
	v_pk_mul_f32 v[58:59], v[58:59], v[220:221]
	v_pk_mul_f32 v[60:61], v[60:61], v[222:223]
	v_lshlrev_b32_e32 v216, 16, v138
	v_and_b32_e32 v217, 0xffff0000, v138
	v_lshlrev_b32_e32 v218, 16, v139
	v_and_b32_e32 v219, 0xffff0000, v139
	v_lshlrev_b32_e32 v220, 16, v140
	v_and_b32_e32 v221, 0xffff0000, v140
	v_lshlrev_b32_e32 v222, 16, v141
	v_and_b32_e32 v223, 0xffff0000, v141
	v_pk_mul_f32 v[216:217], v[216:217], s[86:87] op_sel_hi:[1,0]
	v_pk_mul_f32 v[218:219], v[218:219], s[86:87] op_sel_hi:[1,0]
	v_pk_mul_f32 v[220:221], v[220:221], s[86:87] op_sel_hi:[1,0]
	v_pk_mul_f32 v[222:223], v[222:223], s[86:87] op_sel_hi:[1,0]
	v_exp_f32_e32 v216, v216
	v_exp_f32_e32 v217, v217
	v_exp_f32_e32 v218, v218
	v_exp_f32_e32 v219, v219
	v_exp_f32_e32 v220, v220
	v_exp_f32_e32 v221, v221
	v_exp_f32_e32 v222, v222
	v_exp_f32_e32 v223, v223
	v_pk_add_f32 v[216:217], v[216:217], 1.0 op_sel_hi:[1,0]
	v_pk_add_f32 v[218:219], v[218:219], 1.0 op_sel_hi:[1,0]
	v_pk_add_f32 v[220:221], v[220:221], 1.0 op_sel_hi:[1,0]
	v_pk_add_f32 v[222:223], v[222:223], 1.0 op_sel_hi:[1,0]
	v_rcp_f32_e32 v216, v216
	v_rcp_f32_e32 v217, v217
	v_rcp_f32_e32 v218, v218
	v_rcp_f32_e32 v219, v219
	v_rcp_f32_e32 v220, v220
	v_rcp_f32_e32 v221, v221
	v_rcp_f32_e32 v222, v222
	v_rcp_f32_e32 v223, v223
	v_lshlrev_b32_e32 v242, 16, v142
	v_and_b32_e32 v243, 0xffff0000, v142
	v_lshlrev_b32_e32 v244, 16, v143
	v_and_b32_e32 v245, 0xffff0000, v143
	v_lshlrev_b32_e32 v246, 16, v144
	v_and_b32_e32 v247, 0xffff0000, v144
	v_lshlrev_b32_e32 v248, 16, v145
	v_and_b32_e32 v249, 0xffff0000, v145
	v_pk_mul_f32 v[242:243], v[242:243], s[86:87] op_sel_hi:[1,0]
	v_pk_mul_f32 v[244:245], v[244:245], s[86:87] op_sel_hi:[1,0]
	v_pk_mul_f32 v[246:247], v[246:247], s[86:87] op_sel_hi:[1,0]
	v_pk_mul_f32 v[248:249], v[248:249], s[86:87] op_sel_hi:[1,0]
	v_exp_f32_e32 v242, v242
	v_exp_f32_e32 v243, v243
	v_exp_f32_e32 v244, v244
	v_exp_f32_e32 v245, v245
	v_exp_f32_e32 v246, v246
	v_exp_f32_e32 v247, v247
	v_exp_f32_e32 v248, v248
	v_exp_f32_e32 v249, v249
	v_pk_add_f32 v[242:243], v[242:243], 1.0 op_sel_hi:[1,0]
	v_pk_add_f32 v[244:245], v[244:245], 1.0 op_sel_hi:[1,0]
	v_pk_add_f32 v[246:247], v[246:247], 1.0 op_sel_hi:[1,0]
	v_pk_add_f32 v[248:249], v[248:249], 1.0 op_sel_hi:[1,0]
	v_pk_mul_f32 v[216:217], v[216:217], v[242:243]
	v_pk_mul_f32 v[218:219], v[218:219], v[244:245]
	v_pk_mul_f32 v[220:221], v[220:221], v[246:247]
	v_pk_mul_f32 v[222:223], v[222:223], v[248:249]
	v_pk_mul_f32 v[30:31], v[30:31], v[216:217]
	v_pk_mul_f32 v[32:33], v[32:33], v[218:219]
	v_pk_mul_f32 v[26:27], v[26:27], v[220:221]
	v_pk_mul_f32 v[28:29], v[28:29], v[222:223]
	s_waitcnt vmcnt(8)
	v_lshlrev_b32_e32 v216, 16, v146
	v_and_b32_e32 v217, 0xffff0000, v146
	v_lshlrev_b32_e32 v218, 16, v147
	v_and_b32_e32 v219, 0xffff0000, v147
	v_lshlrev_b32_e32 v220, 16, v148
	v_and_b32_e32 v221, 0xffff0000, v148
	v_lshlrev_b32_e32 v222, 16, v149
	v_and_b32_e32 v223, 0xffff0000, v149
	v_pk_mul_f32 v[216:217], v[216:217], s[86:87] op_sel_hi:[1,0]
	v_pk_mul_f32 v[218:219], v[218:219], s[86:87] op_sel_hi:[1,0]
	v_pk_mul_f32 v[220:221], v[220:221], s[86:87] op_sel_hi:[1,0]
	v_pk_mul_f32 v[222:223], v[222:223], s[86:87] op_sel_hi:[1,0]
	v_exp_f32_e32 v216, v216
	v_exp_f32_e32 v217, v217
	v_exp_f32_e32 v218, v218
	v_exp_f32_e32 v219, v219
	v_exp_f32_e32 v220, v220
	v_exp_f32_e32 v221, v221
	v_exp_f32_e32 v222, v222
	v_exp_f32_e32 v223, v223
	v_pk_add_f32 v[216:217], v[216:217], 1.0 op_sel_hi:[1,0]
	v_pk_add_f32 v[218:219], v[218:219], 1.0 op_sel_hi:[1,0]
	v_pk_add_f32 v[220:221], v[220:221], 1.0 op_sel_hi:[1,0]
	v_pk_add_f32 v[222:223], v[222:223], 1.0 op_sel_hi:[1,0]
	v_rcp_f32_e32 v216, v216
	v_rcp_f32_e32 v217, v217
	v_rcp_f32_e32 v218, v218
	v_rcp_f32_e32 v219, v219
	v_rcp_f32_e32 v220, v220
	v_rcp_f32_e32 v221, v221
	v_rcp_f32_e32 v222, v222
	v_rcp_f32_e32 v223, v223
	v_lshlrev_b32_e32 v242, 16, v150
	v_and_b32_e32 v243, 0xffff0000, v150
	v_lshlrev_b32_e32 v244, 16, v151
	v_and_b32_e32 v245, 0xffff0000, v151
	v_lshlrev_b32_e32 v246, 16, v152
	v_and_b32_e32 v247, 0xffff0000, v152
	v_lshlrev_b32_e32 v248, 16, v153
	v_and_b32_e32 v249, 0xffff0000, v153
	v_pk_mul_f32 v[242:243], v[242:243], s[86:87] op_sel_hi:[1,0]
	v_pk_mul_f32 v[244:245], v[244:245], s[86:87] op_sel_hi:[1,0]
	v_pk_mul_f32 v[246:247], v[246:247], s[86:87] op_sel_hi:[1,0]
	v_pk_mul_f32 v[248:249], v[248:249], s[86:87] op_sel_hi:[1,0]
	v_exp_f32_e32 v242, v242
	v_exp_f32_e32 v243, v243
	v_exp_f32_e32 v244, v244
	v_exp_f32_e32 v245, v245
	v_exp_f32_e32 v246, v246
	v_exp_f32_e32 v247, v247
	v_exp_f32_e32 v248, v248
	v_exp_f32_e32 v249, v249
	v_pk_add_f32 v[242:243], v[242:243], 1.0 op_sel_hi:[1,0]
	v_pk_add_f32 v[244:245], v[244:245], 1.0 op_sel_hi:[1,0]
	v_pk_add_f32 v[246:247], v[246:247], 1.0 op_sel_hi:[1,0]
	v_pk_add_f32 v[248:249], v[248:249], 1.0 op_sel_hi:[1,0]
	v_pk_mul_f32 v[216:217], v[216:217], v[242:243]
	v_pk_mul_f32 v[218:219], v[218:219], v[244:245]
	v_pk_mul_f32 v[220:221], v[220:221], v[246:247]
	v_pk_mul_f32 v[222:223], v[222:223], v[248:249]
	v_pk_mul_f32 v[54:55], v[54:55], v[216:217]
	v_pk_mul_f32 v[56:57], v[56:57], v[218:219]
	v_pk_mul_f32 v[50:51], v[50:51], v[220:221]
	v_pk_mul_f32 v[52:53], v[52:53], v[222:223]
	v_lshlrev_b32_e32 v216, 16, v154
	v_and_b32_e32 v217, 0xffff0000, v154
	v_lshlrev_b32_e32 v218, 16, v155
	v_and_b32_e32 v219, 0xffff0000, v155
	v_lshlrev_b32_e32 v220, 16, v156
	v_and_b32_e32 v221, 0xffff0000, v156
	v_lshlrev_b32_e32 v222, 16, v157
	v_and_b32_e32 v223, 0xffff0000, v157
	v_pk_mul_f32 v[216:217], v[216:217], s[86:87] op_sel_hi:[1,0]
	v_pk_mul_f32 v[218:219], v[218:219], s[86:87] op_sel_hi:[1,0]
	v_pk_mul_f32 v[220:221], v[220:221], s[86:87] op_sel_hi:[1,0]
	v_pk_mul_f32 v[222:223], v[222:223], s[86:87] op_sel_hi:[1,0]
	v_exp_f32_e32 v216, v216
	v_exp_f32_e32 v217, v217
	v_exp_f32_e32 v218, v218
	v_exp_f32_e32 v219, v219
	v_exp_f32_e32 v220, v220
	v_exp_f32_e32 v221, v221
	v_exp_f32_e32 v222, v222
	v_exp_f32_e32 v223, v223
	v_pk_add_f32 v[216:217], v[216:217], 1.0 op_sel_hi:[1,0]
	v_pk_add_f32 v[218:219], v[218:219], 1.0 op_sel_hi:[1,0]
	v_pk_add_f32 v[220:221], v[220:221], 1.0 op_sel_hi:[1,0]
	v_pk_add_f32 v[222:223], v[222:223], 1.0 op_sel_hi:[1,0]
	v_rcp_f32_e32 v216, v216
	v_rcp_f32_e32 v217, v217
	v_rcp_f32_e32 v218, v218
	v_rcp_f32_e32 v219, v219
	v_rcp_f32_e32 v220, v220
	v_rcp_f32_e32 v221, v221
	v_rcp_f32_e32 v222, v222
	v_rcp_f32_e32 v223, v223
	v_lshlrev_b32_e32 v242, 16, v158
	v_and_b32_e32 v243, 0xffff0000, v158
	v_lshlrev_b32_e32 v244, 16, v159
	v_and_b32_e32 v245, 0xffff0000, v159
	v_lshlrev_b32_e32 v246, 16, v160
	v_and_b32_e32 v247, 0xffff0000, v160
	v_lshlrev_b32_e32 v248, 16, v161
	v_and_b32_e32 v249, 0xffff0000, v161
	v_pk_mul_f32 v[242:243], v[242:243], s[86:87] op_sel_hi:[1,0]
	v_pk_mul_f32 v[244:245], v[244:245], s[86:87] op_sel_hi:[1,0]
	v_pk_mul_f32 v[246:247], v[246:247], s[86:87] op_sel_hi:[1,0]
	v_pk_mul_f32 v[248:249], v[248:249], s[86:87] op_sel_hi:[1,0]
	v_exp_f32_e32 v242, v242
	v_exp_f32_e32 v243, v243
	v_exp_f32_e32 v244, v244
	v_exp_f32_e32 v245, v245
	v_exp_f32_e32 v246, v246
	v_exp_f32_e32 v247, v247
	v_exp_f32_e32 v248, v248
	v_exp_f32_e32 v249, v249
	v_pk_add_f32 v[242:243], v[242:243], 1.0 op_sel_hi:[1,0]
	v_pk_add_f32 v[244:245], v[244:245], 1.0 op_sel_hi:[1,0]
	v_pk_add_f32 v[246:247], v[246:247], 1.0 op_sel_hi:[1,0]
	v_pk_add_f32 v[248:249], v[248:249], 1.0 op_sel_hi:[1,0]
	v_pk_mul_f32 v[216:217], v[216:217], v[242:243]
	v_pk_mul_f32 v[218:219], v[218:219], v[244:245]
	v_pk_mul_f32 v[220:221], v[220:221], v[246:247]
	v_pk_mul_f32 v[222:223], v[222:223], v[248:249]
	v_pk_mul_f32 v[22:23], v[22:23], v[216:217]
	v_pk_mul_f32 v[24:25], v[24:25], v[218:219]
	v_pk_mul_f32 v[18:19], v[18:19], v[220:221]
	v_pk_mul_f32 v[20:21], v[20:21], v[222:223]
	s_waitcnt vmcnt(4)
	v_lshlrev_b32_e32 v216, 16, v162
	v_and_b32_e32 v217, 0xffff0000, v162
	v_lshlrev_b32_e32 v218, 16, v163
	v_and_b32_e32 v219, 0xffff0000, v163
	v_lshlrev_b32_e32 v220, 16, v164
	v_and_b32_e32 v221, 0xffff0000, v164
	v_lshlrev_b32_e32 v222, 16, v165
	v_and_b32_e32 v223, 0xffff0000, v165
	v_pk_mul_f32 v[216:217], v[216:217], s[86:87] op_sel_hi:[1,0]
	v_pk_mul_f32 v[218:219], v[218:219], s[86:87] op_sel_hi:[1,0]
	v_pk_mul_f32 v[220:221], v[220:221], s[86:87] op_sel_hi:[1,0]
	v_pk_mul_f32 v[222:223], v[222:223], s[86:87] op_sel_hi:[1,0]
	v_exp_f32_e32 v216, v216
	v_exp_f32_e32 v217, v217
	v_exp_f32_e32 v218, v218
	v_exp_f32_e32 v219, v219
	v_exp_f32_e32 v220, v220
	v_exp_f32_e32 v221, v221
	v_exp_f32_e32 v222, v222
	v_exp_f32_e32 v223, v223
	v_pk_add_f32 v[216:217], v[216:217], 1.0 op_sel_hi:[1,0]
	v_pk_add_f32 v[218:219], v[218:219], 1.0 op_sel_hi:[1,0]
	v_pk_add_f32 v[220:221], v[220:221], 1.0 op_sel_hi:[1,0]
	v_pk_add_f32 v[222:223], v[222:223], 1.0 op_sel_hi:[1,0]
	v_rcp_f32_e32 v216, v216
	v_rcp_f32_e32 v217, v217
	v_rcp_f32_e32 v218, v218
	v_rcp_f32_e32 v219, v219
	v_rcp_f32_e32 v220, v220
	v_rcp_f32_e32 v221, v221
	v_rcp_f32_e32 v222, v222
	v_rcp_f32_e32 v223, v223
	v_lshlrev_b32_e32 v242, 16, v166
	v_and_b32_e32 v243, 0xffff0000, v166
	v_lshlrev_b32_e32 v244, 16, v167
	v_and_b32_e32 v245, 0xffff0000, v167
	v_lshlrev_b32_e32 v246, 16, v168
	v_and_b32_e32 v247, 0xffff0000, v168
	v_lshlrev_b32_e32 v248, 16, v169
	v_and_b32_e32 v249, 0xffff0000, v169
	v_pk_mul_f32 v[242:243], v[242:243], s[86:87] op_sel_hi:[1,0]
	v_pk_mul_f32 v[244:245], v[244:245], s[86:87] op_sel_hi:[1,0]
	v_pk_mul_f32 v[246:247], v[246:247], s[86:87] op_sel_hi:[1,0]
	v_pk_mul_f32 v[248:249], v[248:249], s[86:87] op_sel_hi:[1,0]
	v_exp_f32_e32 v242, v242
	v_exp_f32_e32 v243, v243
	v_exp_f32_e32 v244, v244
	v_exp_f32_e32 v245, v245
	v_exp_f32_e32 v246, v246
	v_exp_f32_e32 v247, v247
	v_exp_f32_e32 v248, v248
	v_exp_f32_e32 v249, v249
	v_pk_add_f32 v[242:243], v[242:243], 1.0 op_sel_hi:[1,0]
	v_pk_add_f32 v[244:245], v[244:245], 1.0 op_sel_hi:[1,0]
	v_pk_add_f32 v[246:247], v[246:247], 1.0 op_sel_hi:[1,0]
	v_pk_add_f32 v[248:249], v[248:249], 1.0 op_sel_hi:[1,0]
	v_pk_mul_f32 v[216:217], v[216:217], v[242:243]
	v_pk_mul_f32 v[218:219], v[218:219], v[244:245]
	v_pk_mul_f32 v[220:221], v[220:221], v[246:247]
	v_pk_mul_f32 v[222:223], v[222:223], v[248:249]
	v_pk_mul_f32 v[46:47], v[46:47], v[216:217]
	v_pk_mul_f32 v[48:49], v[48:49], v[218:219]
	v_pk_mul_f32 v[42:43], v[42:43], v[220:221]
	v_pk_mul_f32 v[44:45], v[44:45], v[222:223]
	v_lshlrev_b32_e32 v216, 16, v170
	v_and_b32_e32 v217, 0xffff0000, v170
	v_lshlrev_b32_e32 v218, 16, v171
	v_and_b32_e32 v219, 0xffff0000, v171
	v_lshlrev_b32_e32 v220, 16, v172
	v_and_b32_e32 v221, 0xffff0000, v172
	v_lshlrev_b32_e32 v222, 16, v173
	v_and_b32_e32 v223, 0xffff0000, v173
	v_pk_mul_f32 v[216:217], v[216:217], s[86:87] op_sel_hi:[1,0]
	v_pk_mul_f32 v[218:219], v[218:219], s[86:87] op_sel_hi:[1,0]
	v_pk_mul_f32 v[220:221], v[220:221], s[86:87] op_sel_hi:[1,0]
	v_pk_mul_f32 v[222:223], v[222:223], s[86:87] op_sel_hi:[1,0]
	v_exp_f32_e32 v216, v216
	v_exp_f32_e32 v217, v217
	v_exp_f32_e32 v218, v218
	v_exp_f32_e32 v219, v219
	v_exp_f32_e32 v220, v220
	v_exp_f32_e32 v221, v221
	v_exp_f32_e32 v222, v222
	v_exp_f32_e32 v223, v223
	v_pk_add_f32 v[216:217], v[216:217], 1.0 op_sel_hi:[1,0]
	v_pk_add_f32 v[218:219], v[218:219], 1.0 op_sel_hi:[1,0]
	v_pk_add_f32 v[220:221], v[220:221], 1.0 op_sel_hi:[1,0]
	v_pk_add_f32 v[222:223], v[222:223], 1.0 op_sel_hi:[1,0]
	v_rcp_f32_e32 v216, v216
	v_rcp_f32_e32 v217, v217
	v_rcp_f32_e32 v218, v218
	v_rcp_f32_e32 v219, v219
	v_rcp_f32_e32 v220, v220
	v_rcp_f32_e32 v221, v221
	v_rcp_f32_e32 v222, v222
	v_rcp_f32_e32 v223, v223
	v_lshlrev_b32_e32 v242, 16, v174
	v_and_b32_e32 v243, 0xffff0000, v174
	v_lshlrev_b32_e32 v244, 16, v175
	v_and_b32_e32 v245, 0xffff0000, v175
	v_lshlrev_b32_e32 v246, 16, v176
	v_and_b32_e32 v247, 0xffff0000, v176
	v_lshlrev_b32_e32 v248, 16, v177
	v_and_b32_e32 v249, 0xffff0000, v177
	v_pk_mul_f32 v[242:243], v[242:243], s[86:87] op_sel_hi:[1,0]
	v_pk_mul_f32 v[244:245], v[244:245], s[86:87] op_sel_hi:[1,0]
	v_pk_mul_f32 v[246:247], v[246:247], s[86:87] op_sel_hi:[1,0]
	v_pk_mul_f32 v[248:249], v[248:249], s[86:87] op_sel_hi:[1,0]
	v_exp_f32_e32 v242, v242
	v_exp_f32_e32 v243, v243
	v_exp_f32_e32 v244, v244
	v_exp_f32_e32 v245, v245
	v_exp_f32_e32 v246, v246
	v_exp_f32_e32 v247, v247
	v_exp_f32_e32 v248, v248
	v_exp_f32_e32 v249, v249
	v_pk_add_f32 v[242:243], v[242:243], 1.0 op_sel_hi:[1,0]
	v_pk_add_f32 v[244:245], v[244:245], 1.0 op_sel_hi:[1,0]
	v_pk_add_f32 v[246:247], v[246:247], 1.0 op_sel_hi:[1,0]
	v_pk_add_f32 v[248:249], v[248:249], 1.0 op_sel_hi:[1,0]
	v_pk_mul_f32 v[216:217], v[216:217], v[242:243]
	v_pk_mul_f32 v[218:219], v[218:219], v[244:245]
	v_pk_mul_f32 v[220:221], v[220:221], v[246:247]
	v_pk_mul_f32 v[222:223], v[222:223], v[248:249]
	v_pk_mul_f32 v[14:15], v[14:15], v[216:217]
	v_pk_mul_f32 v[16:17], v[16:17], v[218:219]
	v_pk_mul_f32 v[10:11], v[10:11], v[220:221]
	v_pk_mul_f32 v[12:13], v[12:13], v[222:223]
	s_waitcnt vmcnt(0)
	v_lshlrev_b32_e32 v216, 16, v178
	v_and_b32_e32 v217, 0xffff0000, v178
	v_lshlrev_b32_e32 v218, 16, v179
	v_and_b32_e32 v219, 0xffff0000, v179
	v_lshlrev_b32_e32 v220, 16, v180
	v_and_b32_e32 v221, 0xffff0000, v180
	v_lshlrev_b32_e32 v222, 16, v181
	v_and_b32_e32 v223, 0xffff0000, v181
	v_pk_mul_f32 v[216:217], v[216:217], s[86:87] op_sel_hi:[1,0]
	v_pk_mul_f32 v[218:219], v[218:219], s[86:87] op_sel_hi:[1,0]
	v_pk_mul_f32 v[220:221], v[220:221], s[86:87] op_sel_hi:[1,0]
	v_pk_mul_f32 v[222:223], v[222:223], s[86:87] op_sel_hi:[1,0]
	v_exp_f32_e32 v216, v216
	v_exp_f32_e32 v217, v217
	v_exp_f32_e32 v218, v218
	v_exp_f32_e32 v219, v219
	v_exp_f32_e32 v220, v220
	v_exp_f32_e32 v221, v221
	v_exp_f32_e32 v222, v222
	v_exp_f32_e32 v223, v223
	v_pk_add_f32 v[216:217], v[216:217], 1.0 op_sel_hi:[1,0]
	v_pk_add_f32 v[218:219], v[218:219], 1.0 op_sel_hi:[1,0]
	v_pk_add_f32 v[220:221], v[220:221], 1.0 op_sel_hi:[1,0]
	v_pk_add_f32 v[222:223], v[222:223], 1.0 op_sel_hi:[1,0]
	v_rcp_f32_e32 v216, v216
	v_rcp_f32_e32 v217, v217
	v_rcp_f32_e32 v218, v218
	v_rcp_f32_e32 v219, v219
	v_rcp_f32_e32 v220, v220
	v_rcp_f32_e32 v221, v221
	v_rcp_f32_e32 v222, v222
	v_rcp_f32_e32 v223, v223
	v_lshlrev_b32_e32 v242, 16, v182
	v_and_b32_e32 v243, 0xffff0000, v182
	v_lshlrev_b32_e32 v244, 16, v183
	v_and_b32_e32 v245, 0xffff0000, v183
	v_lshlrev_b32_e32 v246, 16, v184
	v_and_b32_e32 v247, 0xffff0000, v184
	v_lshlrev_b32_e32 v248, 16, v185
	v_and_b32_e32 v249, 0xffff0000, v185
	v_pk_mul_f32 v[242:243], v[242:243], s[86:87] op_sel_hi:[1,0]
	v_pk_mul_f32 v[244:245], v[244:245], s[86:87] op_sel_hi:[1,0]
	v_pk_mul_f32 v[246:247], v[246:247], s[86:87] op_sel_hi:[1,0]
	v_pk_mul_f32 v[248:249], v[248:249], s[86:87] op_sel_hi:[1,0]
	v_exp_f32_e32 v242, v242
	v_exp_f32_e32 v243, v243
	v_exp_f32_e32 v244, v244
	v_exp_f32_e32 v245, v245
	v_exp_f32_e32 v246, v246
	v_exp_f32_e32 v247, v247
	v_exp_f32_e32 v248, v248
	v_exp_f32_e32 v249, v249
	v_pk_add_f32 v[242:243], v[242:243], 1.0 op_sel_hi:[1,0]
	v_pk_add_f32 v[244:245], v[244:245], 1.0 op_sel_hi:[1,0]
	v_pk_add_f32 v[246:247], v[246:247], 1.0 op_sel_hi:[1,0]
	v_pk_add_f32 v[248:249], v[248:249], 1.0 op_sel_hi:[1,0]
	v_pk_mul_f32 v[216:217], v[216:217], v[242:243]
	v_pk_mul_f32 v[218:219], v[218:219], v[244:245]
	v_pk_mul_f32 v[220:221], v[220:221], v[246:247]
	v_pk_mul_f32 v[222:223], v[222:223], v[248:249]
	v_pk_mul_f32 v[38:39], v[38:39], v[216:217]
	v_pk_mul_f32 v[40:41], v[40:41], v[218:219]
	v_pk_mul_f32 v[34:35], v[34:35], v[220:221]
	v_pk_mul_f32 v[36:37], v[36:37], v[222:223]
	v_lshlrev_b32_e32 v216, 16, v186
	v_and_b32_e32 v217, 0xffff0000, v186
	v_lshlrev_b32_e32 v218, 16, v187
	v_and_b32_e32 v219, 0xffff0000, v187
	v_lshlrev_b32_e32 v220, 16, v188
	v_and_b32_e32 v221, 0xffff0000, v188
	v_lshlrev_b32_e32 v222, 16, v189
	v_and_b32_e32 v223, 0xffff0000, v189
	v_pk_mul_f32 v[216:217], v[216:217], s[86:87] op_sel_hi:[1,0]
	v_pk_mul_f32 v[218:219], v[218:219], s[86:87] op_sel_hi:[1,0]
	v_pk_mul_f32 v[220:221], v[220:221], s[86:87] op_sel_hi:[1,0]
	v_pk_mul_f32 v[222:223], v[222:223], s[86:87] op_sel_hi:[1,0]
	v_exp_f32_e32 v216, v216
	v_exp_f32_e32 v217, v217
	v_exp_f32_e32 v218, v218
	v_exp_f32_e32 v219, v219
	v_exp_f32_e32 v220, v220
	v_exp_f32_e32 v221, v221
	v_exp_f32_e32 v222, v222
	v_exp_f32_e32 v223, v223
	v_pk_add_f32 v[216:217], v[216:217], 1.0 op_sel_hi:[1,0]
	v_pk_add_f32 v[218:219], v[218:219], 1.0 op_sel_hi:[1,0]
	v_pk_add_f32 v[220:221], v[220:221], 1.0 op_sel_hi:[1,0]
	v_pk_add_f32 v[222:223], v[222:223], 1.0 op_sel_hi:[1,0]
	v_rcp_f32_e32 v216, v216
	v_rcp_f32_e32 v217, v217
	v_rcp_f32_e32 v218, v218
	v_rcp_f32_e32 v219, v219
	v_rcp_f32_e32 v220, v220
	v_rcp_f32_e32 v221, v221
	v_rcp_f32_e32 v222, v222
	v_rcp_f32_e32 v223, v223
	v_lshlrev_b32_e32 v242, 16, v190
	v_and_b32_e32 v243, 0xffff0000, v190
	v_lshlrev_b32_e32 v244, 16, v191
	v_and_b32_e32 v245, 0xffff0000, v191
	v_lshlrev_b32_e32 v246, 16, v192
	v_and_b32_e32 v247, 0xffff0000, v192
	v_lshlrev_b32_e32 v248, 16, v193
	v_and_b32_e32 v249, 0xffff0000, v193
	v_pk_mul_f32 v[242:243], v[242:243], s[86:87] op_sel_hi:[1,0]
	v_pk_mul_f32 v[244:245], v[244:245], s[86:87] op_sel_hi:[1,0]
	v_pk_mul_f32 v[246:247], v[246:247], s[86:87] op_sel_hi:[1,0]
	v_pk_mul_f32 v[248:249], v[248:249], s[86:87] op_sel_hi:[1,0]
	v_exp_f32_e32 v242, v242
	v_exp_f32_e32 v243, v243
	v_exp_f32_e32 v244, v244
	v_exp_f32_e32 v245, v245
	v_exp_f32_e32 v246, v246
	v_exp_f32_e32 v247, v247
	v_exp_f32_e32 v248, v248
	v_exp_f32_e32 v249, v249
	v_pk_add_f32 v[242:243], v[242:243], 1.0 op_sel_hi:[1,0]
	v_pk_add_f32 v[244:245], v[244:245], 1.0 op_sel_hi:[1,0]
	v_pk_add_f32 v[246:247], v[246:247], 1.0 op_sel_hi:[1,0]
	v_pk_add_f32 v[248:249], v[248:249], 1.0 op_sel_hi:[1,0]
	v_pk_mul_f32 v[216:217], v[216:217], v[242:243]
	v_pk_mul_f32 v[218:219], v[218:219], v[244:245]
	v_pk_mul_f32 v[220:221], v[220:221], v[246:247]
	v_pk_mul_f32 v[222:223], v[222:223], v[248:249]
	v_pk_mul_f32 v[6:7], v[6:7], v[216:217]
	v_pk_mul_f32 v[8:9], v[8:9], v[218:219]
	v_pk_mul_f32 v[2:3], v[2:3], v[220:221]
	v_pk_mul_f32 v[4:5], v[4:5], v[222:223]
	s_branch .Lem_done

.LBB0_504:
	v_add_u32_e32 v253, 0x10000, v163
	ds_read_b128 v[130:133], v253
	ds_read_b128 v[134:137], v253 offset:1024
	ds_read_b128 v[150:153], v253 offset:2048
	ds_read_b128 v[154:157], v253 offset:3072
	s_add_u32 s10, s52, 0xfff80080
	s_addc_u32 s11, s53, -1
	s_cmp_eq_u32 s29, 28
	s_cselect_b32 s11, s9, s11
	s_cselect_b32 s10, s8, s10
	s_cselect_b32 s55, s35, s7
	s_cselect_b32 s54, s34, s5
	v_lshl_add_u64 v[206:207], s[52:53], 0, v[146:147]
	s_add_i32 m0, s42, 0xc000
	ds_read_b128 v[158:161], v162
	ds_read_b128 v[166:169], v162 offset:1024
	ds_read_b128 v[170:173], v162 offset:2048
	ds_read_b128 v[174:177], v162 offset:3072
	ds_read_b128 v[178:181], v162 offset:4096
	ds_read_b128 v[182:185], v162 offset:5120
	ds_read_b128 v[186:189], v162 offset:6144
	ds_read_b128 v[190:193], v162 offset:7168
	global_load_lds_dwordx4 v[206:207], off
	v_lshl_add_u64 v[206:207], s[52:53], 0, v[148:149]
	s_add_i32 m0, s42, 0xe000
	s_nop 0
	global_load_lds_dwordx4 v[206:207], off
	s_waitcnt lgkmcnt(8)
	s_setprio 1
	s_barrier
	s_waitcnt lgkmcnt(0)
	v_mfma_f32_16x16x32_bf16 v[126:129], v[130:133], v[158:161], v[126:129]
	v_mfma_f32_16x16x32_bf16 v[122:125], v[150:153], v[158:161], v[122:125]
	v_mfma_f32_16x16x32_bf16 v[118:121], v[130:133], v[170:173], v[118:121]
	v_mfma_f32_16x16x32_bf16 v[114:117], v[150:153], v[170:173], v[114:117]
	v_mfma_f32_16x16x32_bf16 v[110:113], v[130:133], v[178:181], v[110:113]
	v_mfma_f32_16x16x32_bf16 v[106:109], v[150:153], v[178:181], v[106:109]
	v_mfma_f32_16x16x32_bf16 v[102:105], v[130:133], v[186:189], v[102:105]
	v_mfma_f32_16x16x32_bf16 v[98:101], v[150:153], v[186:189], v[98:101]
	v_mfma_f32_16x16x32_bf16 v[126:129], v[134:137], v[166:169], v[126:129]
	v_mfma_f32_16x16x32_bf16 v[122:125], v[154:157], v[166:169], v[122:125]
	v_mfma_f32_16x16x32_bf16 v[118:121], v[134:137], v[174:177], v[118:121]
	v_mfma_f32_16x16x32_bf16 v[114:117], v[154:157], v[174:177], v[114:117]
	v_mfma_f32_16x16x32_bf16 v[110:113], v[134:137], v[182:185], v[110:113]
	v_mfma_f32_16x16x32_bf16 v[106:109], v[154:157], v[182:185], v[106:109]
	v_mfma_f32_16x16x32_bf16 v[102:105], v[134:137], v[190:193], v[102:105]
	v_mfma_f32_16x16x32_bf16 v[98:101], v[154:157], v[190:193], v[98:101]
	s_barrier
	s_setprio 0
	s_mov_b32 m0, s41
	ds_read_b128 v[206:209], v253 offset:16384
	ds_read_b128 v[210:213], v253 offset:17408
	v_lshl_add_u64 v[222:223], s[54:55], 0, v[194:195]
	ds_read_b128 v[214:217], v253 offset:18432
	ds_read_b128 v[218:221], v253 offset:19456
	global_load_lds_dwordx4 v[222:223], off
	v_lshl_add_u64 v[224:225], s[54:55], 0, v[138:139]
	s_mov_b32 m0, s57
	s_nop 0
	global_load_lds_dwordx4 v[224:225], off
	s_setprio 1
	s_barrier
	s_waitcnt lgkmcnt(0)
	v_mfma_f32_16x16x32_bf16 v[62:65], v[206:209], v[158:161], v[62:65]
	v_mfma_f32_16x16x32_bf16 v[58:61], v[214:217], v[158:161], v[58:61]
	v_mfma_f32_16x16x32_bf16 v[54:57], v[206:209], v[170:173], v[54:57]
	v_mfma_f32_16x16x32_bf16 v[46:49], v[214:217], v[170:173], v[46:49]
	v_mfma_f32_16x16x32_bf16 v[50:53], v[206:209], v[178:181], v[50:53]
	v_mfma_f32_16x16x32_bf16 v[42:45], v[214:217], v[178:181], v[42:45]
	v_mfma_f32_16x16x32_bf16 v[38:41], v[206:209], v[186:189], v[38:41]
	v_mfma_f32_16x16x32_bf16 v[34:37], v[214:217], v[186:189], v[34:37]
	v_mfma_f32_16x16x32_bf16 v[62:65], v[210:213], v[166:169], v[62:65]
	v_mfma_f32_16x16x32_bf16 v[58:61], v[218:221], v[166:169], v[58:61]
	v_mfma_f32_16x16x32_bf16 v[54:57], v[210:213], v[174:177], v[54:57]
	v_mfma_f32_16x16x32_bf16 v[46:49], v[218:221], v[174:177], v[46:49]
	v_mfma_f32_16x16x32_bf16 v[50:53], v[210:213], v[182:185], v[50:53]
	v_mfma_f32_16x16x32_bf16 v[42:45], v[218:221], v[182:185], v[42:45]
	s_mov_b32 m0, s42
	v_mfma_f32_16x16x32_bf16 v[38:41], v[210:213], v[190:193], v[38:41]
	v_lshl_add_u64 v[226:227], s[10:11], 0, v[142:143]
	v_mfma_f32_16x16x32_bf16 v[34:37], v[218:221], v[190:193], v[34:37]
	s_barrier
	s_setprio 0
	ds_read_b128 v[158:161], v162 offset:16384
	ds_read_b128 v[166:169], v162 offset:17408
	ds_read_b128 v[170:173], v162 offset:18432
	ds_read_b128 v[174:177], v162 offset:19456
	ds_read_b128 v[178:181], v162 offset:20480
	ds_read_b128 v[182:185], v162 offset:21504
	ds_read_b128 v[186:189], v162 offset:22528
	ds_read_b128 v[190:193], v162 offset:23552
	global_load_lds_dwordx4 v[226:227], off
	v_lshl_add_u64 v[228:229], s[10:11], 0, v[140:141]
	s_mov_b32 m0, s58
	s_nop 0
	global_load_lds_dwordx4 v[228:229], off
	s_setprio 1
	s_barrier
	s_waitcnt lgkmcnt(0)
	v_mfma_f32_16x16x32_bf16 v[94:97], v[130:133], v[158:161], v[94:97]
	v_mfma_f32_16x16x32_bf16 v[90:93], v[150:153], v[158:161], v[90:93]
	v_mfma_f32_16x16x32_bf16 v[86:89], v[130:133], v[170:173], v[86:89]
	v_mfma_f32_16x16x32_bf16 v[82:85], v[150:153], v[170:173], v[82:85]
	v_mfma_f32_16x16x32_bf16 v[78:81], v[130:133], v[178:181], v[78:81]
	v_mfma_f32_16x16x32_bf16 v[74:77], v[150:153], v[178:181], v[74:77]
	v_mfma_f32_16x16x32_bf16 v[70:73], v[130:133], v[186:189], v[70:73]
	v_mfma_f32_16x16x32_bf16 v[66:69], v[150:153], v[186:189], v[66:69]
	v_mfma_f32_16x16x32_bf16 v[94:97], v[134:137], v[166:169], v[94:97]
	v_mfma_f32_16x16x32_bf16 v[90:93], v[154:157], v[166:169], v[90:93]
	v_mfma_f32_16x16x32_bf16 v[86:89], v[134:137], v[174:177], v[86:89]
	v_mfma_f32_16x16x32_bf16 v[82:85], v[154:157], v[174:177], v[82:85]
	v_mfma_f32_16x16x32_bf16 v[78:81], v[134:137], v[182:185], v[78:81]
	v_mfma_f32_16x16x32_bf16 v[74:77], v[154:157], v[182:185], v[74:77]
	v_mfma_f32_16x16x32_bf16 v[70:73], v[134:137], v[190:193], v[70:73]
	v_mfma_f32_16x16x32_bf16 v[66:69], v[154:157], v[190:193], v[66:69]
	s_barrier
	s_setprio 0
	s_add_u32 s86, s54, 0x80000
	s_addc_u32 s87, s55, 0
	s_mov_b32 m0, s59
	v_lshl_add_u64 v[130:131], s[86:87], 0, v[194:195]
	global_load_lds_dwordx4 v[130:131], off
	v_lshl_add_u64 v[130:131], s[86:87], 0, v[138:139]
	s_mov_b32 m0, s60
	s_nop 0
	global_load_lds_dwordx4 v[130:131], off
	s_waitcnt vmcnt(6)
	s_setprio 1
	s_barrier
	v_mfma_f32_16x16x32_bf16 v[30:33], v[206:209], v[158:161], v[30:33]
	v_mfma_f32_16x16x32_bf16 v[18:21], v[214:217], v[158:161], v[18:21]
	v_mfma_f32_16x16x32_bf16 v[26:29], v[206:209], v[170:173], v[26:29]
	v_mfma_f32_16x16x32_bf16 v[14:17], v[214:217], v[170:173], v[14:17]
	v_mfma_f32_16x16x32_bf16 v[22:25], v[206:209], v[178:181], v[22:25]
	v_mfma_f32_16x16x32_bf16 v[6:9], v[214:217], v[178:181], v[6:9]
	v_mfma_f32_16x16x32_bf16 v[10:13], v[206:209], v[186:189], v[10:13]
	v_mfma_f32_16x16x32_bf16 v[2:5], v[214:217], v[186:189], v[2:5]
	v_mfma_f32_16x16x32_bf16 v[30:33], v[210:213], v[166:169], v[30:33]
	v_mfma_f32_16x16x32_bf16 v[18:21], v[218:221], v[166:169], v[18:21]
	v_mfma_f32_16x16x32_bf16 v[26:29], v[210:213], v[174:177], v[26:29]
	v_mfma_f32_16x16x32_bf16 v[14:17], v[218:221], v[174:177], v[14:17]
	v_mfma_f32_16x16x32_bf16 v[22:25], v[210:213], v[182:185], v[22:25]
	v_mfma_f32_16x16x32_bf16 v[6:9], v[218:221], v[182:185], v[6:9]
	v_mfma_f32_16x16x32_bf16 v[10:13], v[210:213], v[190:193], v[10:13]
	v_mfma_f32_16x16x32_bf16 v[2:5], v[218:221], v[190:193], v[2:5]
	s_barrier
	s_setprio 0
	ds_read_b128 v[130:133], v253 offset:32768
	ds_read_b128 v[134:137], v253 offset:33792
	ds_read_b128 v[150:153], v253 offset:34816
	ds_read_b128 v[154:157], v253 offset:35840
	s_add_u32 s10, s10, 0x80000
	s_addc_u32 s11, s11, 0
	s_mov_b32 m0, s61
	v_lshl_add_u64 v[206:207], s[10:11], 0, v[142:143]
	ds_read_b128 v[158:161], v162 offset:32768
	ds_read_b128 v[166:169], v162 offset:33792
	ds_read_b128 v[170:173], v162 offset:34816
	ds_read_b128 v[174:177], v162 offset:35840
	ds_read_b128 v[178:181], v162 offset:36864
	ds_read_b128 v[182:185], v162 offset:37888
	ds_read_b128 v[186:189], v162 offset:38912
	ds_read_b128 v[190:193], v162 offset:39936
	global_load_lds_dwordx4 v[206:207], off
	v_lshl_add_u64 v[206:207], s[10:11], 0, v[140:141]
	s_mov_b32 m0, s62
	s_nop 0
	global_load_lds_dwordx4 v[206:207], off
	s_waitcnt lgkmcnt(8)
	s_setprio 1
	s_barrier
	s_waitcnt lgkmcnt(0)
	v_mfma_f32_16x16x32_bf16 v[126:129], v[130:133], v[158:161], v[126:129]
	v_mfma_f32_16x16x32_bf16 v[122:125], v[150:153], v[158:161], v[122:125]
	v_mfma_f32_16x16x32_bf16 v[118:121], v[130:133], v[170:173], v[118:121]
	v_mfma_f32_16x16x32_bf16 v[114:117], v[150:153], v[170:173], v[114:117]
	v_mfma_f32_16x16x32_bf16 v[110:113], v[130:133], v[178:181], v[110:113]
	v_mfma_f32_16x16x32_bf16 v[106:109], v[150:153], v[178:181], v[106:109]
	v_mfma_f32_16x16x32_bf16 v[102:105], v[130:133], v[186:189], v[102:105]
	v_mfma_f32_16x16x32_bf16 v[98:101], v[150:153], v[186:189], v[98:101]
	v_mfma_f32_16x16x32_bf16 v[126:129], v[134:137], v[166:169], v[126:129]
	v_mfma_f32_16x16x32_bf16 v[122:125], v[154:157], v[166:169], v[122:125]
	v_mfma_f32_16x16x32_bf16 v[118:121], v[134:137], v[174:177], v[118:121]
	v_mfma_f32_16x16x32_bf16 v[114:117], v[154:157], v[174:177], v[114:117]
	v_mfma_f32_16x16x32_bf16 v[110:113], v[134:137], v[182:185], v[110:113]
	v_mfma_f32_16x16x32_bf16 v[106:109], v[154:157], v[182:185], v[106:109]
	v_mfma_f32_16x16x32_bf16 v[102:105], v[134:137], v[190:193], v[102:105]
	v_mfma_f32_16x16x32_bf16 v[98:101], v[154:157], v[190:193], v[98:101]
	s_barrier
	s_setprio 0
	s_mov_b32 m0, s70
	ds_read_b128 v[206:209], v253 offset:49152
	ds_read_b128 v[210:213], v253 offset:50176
	v_lshl_add_u64 v[222:223], v[222:223], 0, s[76:77]
	ds_read_b128 v[214:217], v253 offset:51200
	ds_read_b128 v[218:221], v253 offset:52224
	global_load_lds_dwordx4 v[222:223], off
	v_lshl_add_u64 v[222:223], v[224:225], 0, s[76:77]
	s_mov_b32 m0, s71
	s_nop 0
	global_load_lds_dwordx4 v[222:223], off
	s_setprio 1
	s_barrier
	s_waitcnt lgkmcnt(0)
	v_mfma_f32_16x16x32_bf16 v[62:65], v[206:209], v[158:161], v[62:65]
	v_mfma_f32_16x16x32_bf16 v[58:61], v[214:217], v[158:161], v[58:61]
	v_mfma_f32_16x16x32_bf16 v[54:57], v[206:209], v[170:173], v[54:57]
	v_mfma_f32_16x16x32_bf16 v[46:49], v[214:217], v[170:173], v[46:49]
	v_mfma_f32_16x16x32_bf16 v[50:53], v[206:209], v[178:181], v[50:53]
	v_mfma_f32_16x16x32_bf16 v[42:45], v[214:217], v[178:181], v[42:45]
	v_mfma_f32_16x16x32_bf16 v[38:41], v[206:209], v[186:189], v[38:41]
	v_mfma_f32_16x16x32_bf16 v[34:37], v[214:217], v[186:189], v[34:37]
	v_mfma_f32_16x16x32_bf16 v[62:65], v[210:213], v[166:169], v[62:65]
	v_mfma_f32_16x16x32_bf16 v[58:61], v[218:221], v[166:169], v[58:61]
	v_mfma_f32_16x16x32_bf16 v[54:57], v[210:213], v[174:177], v[54:57]
	v_mfma_f32_16x16x32_bf16 v[46:49], v[218:221], v[174:177], v[46:49]
	v_mfma_f32_16x16x32_bf16 v[50:53], v[210:213], v[182:185], v[50:53]
	v_mfma_f32_16x16x32_bf16 v[42:45], v[218:221], v[182:185], v[42:45]
	s_mov_b32 m0, s78
	v_mfma_f32_16x16x32_bf16 v[38:41], v[210:213], v[190:193], v[38:41]
	v_lshl_add_u64 v[222:223], v[226:227], 0, s[76:77]
	v_mfma_f32_16x16x32_bf16 v[34:37], v[218:221], v[190:193], v[34:37]
	s_barrier
	s_setprio 0
	ds_read_b128 v[158:161], v162 offset:49152
	ds_read_b128 v[166:169], v162 offset:50176
	ds_read_b128 v[170:173], v162 offset:51200
	ds_read_b128 v[174:177], v162 offset:52224
	ds_read_b128 v[178:181], v162 offset:53248
	ds_read_b128 v[182:185], v162 offset:54272
	ds_read_b128 v[186:189], v162 offset:55296
	ds_read_b128 v[190:193], v162 offset:56320
	global_load_lds_dwordx4 v[222:223], off
	v_lshl_add_u64 v[222:223], v[228:229], 0, s[76:77]
	s_mov_b32 m0, s79
	s_nop 0
	global_load_lds_dwordx4 v[222:223], off
	s_setprio 1
	s_barrier
	s_waitcnt lgkmcnt(0)
	v_mfma_f32_16x16x32_bf16 v[94:97], v[130:133], v[158:161], v[94:97]
	v_mfma_f32_16x16x32_bf16 v[90:93], v[150:153], v[158:161], v[90:93]
	v_mfma_f32_16x16x32_bf16 v[86:89], v[130:133], v[170:173], v[86:89]
	v_mfma_f32_16x16x32_bf16 v[82:85], v[150:153], v[170:173], v[82:85]
	v_mfma_f32_16x16x32_bf16 v[78:81], v[130:133], v[178:181], v[78:81]
	v_mfma_f32_16x16x32_bf16 v[74:77], v[150:153], v[178:181], v[74:77]
	v_mfma_f32_16x16x32_bf16 v[70:73], v[130:133], v[186:189], v[70:73]
	v_mfma_f32_16x16x32_bf16 v[66:69], v[150:153], v[186:189], v[66:69]
	v_mfma_f32_16x16x32_bf16 v[94:97], v[134:137], v[166:169], v[94:97]
	v_mfma_f32_16x16x32_bf16 v[90:93], v[154:157], v[166:169], v[90:93]
	v_mfma_f32_16x16x32_bf16 v[86:89], v[134:137], v[174:177], v[86:89]
	v_mfma_f32_16x16x32_bf16 v[82:85], v[154:157], v[174:177], v[82:85]
	v_mfma_f32_16x16x32_bf16 v[78:81], v[134:137], v[182:185], v[78:81]
	v_mfma_f32_16x16x32_bf16 v[74:77], v[154:157], v[182:185], v[74:77]
	v_mfma_f32_16x16x32_bf16 v[70:73], v[134:137], v[190:193], v[70:73]
	v_mfma_f32_16x16x32_bf16 v[66:69], v[154:157], v[190:193], v[66:69]
	s_barrier
	s_setprio 0
	s_add_u32 s10, s54, 0x80080
	s_addc_u32 s11, s55, 0
	s_mov_b32 m0, s80
	v_lshl_add_u64 v[130:131], s[10:11], 0, v[194:195]
	global_load_lds_dwordx4 v[130:131], off
	v_lshl_add_u64 v[130:131], s[10:11], 0, v[138:139]
	s_mov_b32 m0, s81
	s_nop 0
	global_load_lds_dwordx4 v[130:131], off
	s_waitcnt vmcnt(6)
	s_setprio 1
	s_barrier
	v_mfma_f32_16x16x32_bf16 v[30:33], v[206:209], v[158:161], v[30:33]
	v_mfma_f32_16x16x32_bf16 v[18:21], v[214:217], v[158:161], v[18:21]
	v_mfma_f32_16x16x32_bf16 v[26:29], v[206:209], v[170:173], v[26:29]
	v_mfma_f32_16x16x32_bf16 v[14:17], v[214:217], v[170:173], v[14:17]
	v_mfma_f32_16x16x32_bf16 v[22:25], v[206:209], v[178:181], v[22:25]
	v_mfma_f32_16x16x32_bf16 v[6:9], v[214:217], v[178:181], v[6:9]
	v_mfma_f32_16x16x32_bf16 v[10:13], v[206:209], v[186:189], v[10:13]
	v_mfma_f32_16x16x32_bf16 v[2:5], v[214:217], v[186:189], v[2:5]
	v_mfma_f32_16x16x32_bf16 v[30:33], v[210:213], v[166:169], v[30:33]
	v_mfma_f32_16x16x32_bf16 v[18:21], v[218:221], v[166:169], v[18:21]
	v_mfma_f32_16x16x32_bf16 v[26:29], v[210:213], v[174:177], v[26:29]
	v_mfma_f32_16x16x32_bf16 v[14:17], v[218:221], v[174:177], v[14:17]
	v_mfma_f32_16x16x32_bf16 v[22:25], v[210:213], v[182:185], v[22:25]
	v_mfma_f32_16x16x32_bf16 v[6:9], v[218:221], v[182:185], v[6:9]
	v_mfma_f32_16x16x32_bf16 v[10:13], v[210:213], v[190:193], v[10:13]
	v_mfma_f32_16x16x32_bf16 v[2:5], v[218:221], v[190:193], v[2:5]
	s_setprio 0
	s_add_i32 s29, s29, 2
	s_add_u32 s52, s52, 0x100
	s_addc_u32 s53, s53, 0
	s_add_u32 s5, s5, 0x100
	s_addc_u32 s7, s7, 0
	s_cmp_gt_u32 s29, 29
	s_barrier
	s_cbranch_scc0 .LBB0_504
	v_readlane_b32 s10, v250, 21
	s_cmp_gt_i32 s40, 63
	v_readlane_b32 s11, v250, 22
	s_mov_b64 s[20:21], s[48:49]
	s_cselect_b32 s11, s21, s11
	s_cselect_b32 s10, s20, s10
	v_readlane_b32 s20, v252, 0
	v_readlane_b32 s26, v252, 6
	v_readlane_b32 s27, v252, 7
	s_cselect_b32 s53, s3, s27
	s_cselect_b32 s52, s2, s26
	s_sub_i32 s5, s40, 64
	s_cmp_gt_i32 s40, 63
	s_cselect_b32 s54, s5, s40
	s_lshr_b32 s5, s40, 3
	s_cmp_gt_i32 s40, 63
	s_mulk_i32 s5, 0x1800
	v_lshl_or_b32 v130, s28, 8, v164
	s_cselect_b32 s28, 0xc000, s5
	s_ashr_i32 s29, s28, 31
	s_lshl_b64 s[28:29], s[28:29], 2
	s_add_u32 s28, s63, s28
	v_ashrrev_i32_e32 v131, 31, v130
	s_addc_u32 s29, s67, s29
	v_lshlrev_b64 v[130:131], 2, v[130:131]
	v_lshl_add_u64 v[132:133], s[28:29], 0, v[130:131]
	s_mov_b64 s[28:29], 0x6484000
	s_ashr_i32 s55, s54, 31
	v_lshl_add_u64 v[154:155], v[132:133], 0, s[28:29]
	s_lshl_b64 s[28:29], s[54:55], 19
	v_lshl_add_u64 v[134:135], s[28:29], 0, v[144:145]
	v_lshlrev_b64 v[134:135], 2, v[134:135]
	v_lshl_add_u64 v[136:137], s[10:11], 0, v[134:135]
	v_lshl_add_u64 v[134:135], s[52:53], 0, v[134:135]
	s_mov_b32 s5, 0x6484000
	v_lshl_add_u64 v[150:151], v[136:137], 0, v[130:131]
	v_lshl_add_u64 v[152:153], v[134:135], 0, v[130:131]
	v_add_co_u32_e32 v130, vcc, s5, v132
	s_mov_b64 s[10:11], 0x20000
	s_nop 0
	v_addc_co_u32_e32 v131, vcc, 0, v133, vcc
	v_add_co_u32_e32 v156, vcc, s13, v150
	global_load_dwordx4 v[134:137], v[130:131], off
	s_nop 0
	global_load_dwordx4 v[130:133], v[154:155], off offset:16
	global_load_dwordx4 v[166:169], v[150:151], off offset:16
	global_load_dwordx4 v[170:173], v[150:151], off
	v_lshl_add_u64 v[158:159], v[150:151], 0, s[10:11]
	v_addc_co_u32_e32 v157, vcc, 0, v151, vcc
	s_mov_b32 s5, 0x40000
	global_load_dwordx4 v[174:177], v[156:157], off
	global_load_dwordx4 v[178:181], v[158:159], off offset:16
	s_mov_b64 s[10:11], 0x40000
	v_add_co_u32_e32 v158, vcc, s5, v150
	v_lshl_add_u64 v[160:161], v[150:151], 0, s[10:11]
	s_nop 0
	v_addc_co_u32_e32 v159, vcc, 0, v151, vcc
	s_mov_b32 s7, 0x60000
	global_load_dwordx4 v[182:185], v[158:159], off
	global_load_dwordx4 v[186:189], v[160:161], off offset:16
	s_mov_b64 s[10:11], 0x60000
	v_add_co_u32_e32 v160, vcc, s7, v150
	v_lshl_add_u64 v[206:207], v[150:151], 0, s[10:11]
	s_nop 0
	v_addc_co_u32_e32 v161, vcc, 0, v151, vcc
	global_load_dwordx4 v[190:193], v[160:161], off
	s_nop 0
	global_load_dwordx4 v[206:209], v[206:207], off offset:16
	v_readlane_b32 s21, v252, 1
	v_readlane_b32 s22, v252, 2
	v_readlane_b32 s23, v252, 3
	v_readlane_b32 s24, v252, 4
	v_readlane_b32 s25, v252, 5
	s_waitcnt vmcnt(0)
	v_pk_fma_f32 v[124:125], v[124:125], v[132:133], v[168:169]
	v_pk_fma_f32 v[122:123], v[122:123], v[130:131], v[166:167]
	global_store_dwordx4 v[152:153], v[122:125], off offset:16
	v_pk_fma_f32 v[128:129], v[128:129], v[136:137], v[172:173]
	v_pk_fma_f32 v[126:127], v[126:127], v[134:135], v[170:171]
	v_pk_fma_f32 v[122:123], v[120:121], v[136:137], v[176:177]
	v_pk_fma_f32 v[120:121], v[118:119], v[134:135], v[174:175]
	v_add_co_u32_e32 v118, vcc, s13, v152
	v_pk_fma_f32 v[116:117], v[116:117], v[132:133], v[180:181]
	s_nop 0
	v_addc_co_u32_e32 v119, vcc, 0, v153, vcc
	v_pk_fma_f32 v[114:115], v[114:115], v[130:131], v[178:179]
	global_store_dwordx4 v[118:119], v[114:117], off offset:16
	v_pk_fma_f32 v[108:109], v[108:109], v[132:133], v[188:189]
	v_pk_fma_f32 v[106:107], v[106:107], v[130:131], v[186:187]
	v_pk_fma_f32 v[114:115], v[112:113], v[136:137], v[184:185]
	v_pk_fma_f32 v[112:113], v[110:111], v[134:135], v[182:183]
	v_add_co_u32_e32 v110, vcc, s5, v152
	global_store_dwordx4 v[152:153], v[126:129], off
	s_nop 0
	v_addc_co_u32_e32 v111, vcc, 0, v153, vcc
	global_store_dwordx4 v[110:111], v[106:109], off offset:16
	v_pk_fma_f32 v[100:101], v[100:101], v[132:133], v[208:209]
	v_pk_fma_f32 v[98:99], v[98:99], v[130:131], v[206:207]
	v_pk_fma_f32 v[106:107], v[104:105], v[136:137], v[192:193]
	v_pk_fma_f32 v[104:105], v[102:103], v[134:135], v[190:191]
	v_add_co_u32_e32 v102, vcc, s7, v152
	global_store_dwordx4 v[118:119], v[120:123], off
	s_nop 0
	v_addc_co_u32_e32 v103, vcc, 0, v153, vcc
	global_store_dwordx4 v[110:111], v[112:115], off
	global_store_dwordx4 v[102:103], v[104:107], off
	global_store_dwordx4 v[102:103], v[98:101], off offset:16
	s_mov_b32 s5, 0x100000
	s_mov_b64 s[10:11], 0x100000
	v_add_co_u32_e32 v98, vcc, s5, v150
	v_lshl_add_u64 v[100:101], v[150:151], 0, s[10:11]
	s_nop 0
	v_addc_co_u32_e32 v99, vcc, 0, v151, vcc
	global_load_dwordx4 v[112:115], v[98:99], off
	global_load_dwordx4 v[120:123], v[100:101], off offset:16
	s_mov_b64 s[10:11], 0x120000
	v_add_co_u32_e32 v100, vcc, s45, v150
	v_lshl_add_u64 v[104:105], v[150:151], 0, s[10:11]
	s_nop 0
	v_addc_co_u32_e32 v101, vcc, 0, v151, vcc
	s_mov_b64 s[10:11], 0x140000
	s_mov_b32 s7, 0x140000
	global_load_dwordx4 v[124:127], v[100:101], off
	global_load_dwordx4 v[166:169], v[104:105], off offset:16
	v_lshl_add_u64 v[106:107], v[150:151], 0, s[10:11]
	v_add_co_u32_e32 v104, vcc, s7, v150
	s_mov_b64 s[10:11], 0x160000
	s_nop 0
	v_addc_co_u32_e32 v105, vcc, 0, v151, vcc
	v_lshl_add_u64 v[108:109], v[150:151], 0, s[10:11]
	s_mov_b32 s10, 0x160000
	global_load_dwordx4 v[170:173], v[104:105], off
	global_load_dwordx4 v[174:177], v[106:107], off offset:16
	v_add_co_u32_e32 v106, vcc, s10, v150
	s_waitcnt vmcnt(0)
	v_pk_fma_f32 v[112:113], v[94:95], v[134:135], v[112:113]
	v_addc_co_u32_e32 v107, vcc, 0, v151, vcc
	global_load_dwordx4 v[178:181], v[106:107], off
	global_load_dwordx4 v[182:185], v[108:109], off offset:16
	v_add_co_u32_e32 v94, vcc, s5, v152
	v_pk_fma_f32 v[92:93], v[92:93], v[132:133], v[122:123]
	s_nop 0
	v_addc_co_u32_e32 v95, vcc, 0, v153, vcc
	v_pk_fma_f32 v[90:91], v[90:91], v[130:131], v[120:121]
	global_store_dwordx4 v[94:95], v[90:93], off offset:16
	v_pk_fma_f32 v[84:85], v[84:85], v[132:133], v[168:169]
	v_pk_fma_f32 v[82:83], v[82:83], v[130:131], v[166:167]
	v_pk_fma_f32 v[90:91], v[88:89], v[136:137], v[126:127]
	v_pk_fma_f32 v[88:89], v[86:87], v[134:135], v[124:125]
	v_add_co_u32_e32 v86, vcc, s45, v152
	v_pk_fma_f32 v[114:115], v[96:97], v[136:137], v[114:115]
	s_nop 0
	v_addc_co_u32_e32 v87, vcc, 0, v153, vcc
	global_store_dwordx4 v[86:87], v[82:85], off offset:16
	v_pk_fma_f32 v[76:77], v[76:77], v[132:133], v[176:177]
	v_pk_fma_f32 v[74:75], v[74:75], v[130:131], v[174:175]
	v_pk_fma_f32 v[82:83], v[80:81], v[136:137], v[172:173]
	v_pk_fma_f32 v[80:81], v[78:79], v[134:135], v[170:171]
	v_add_co_u32_e32 v78, vcc, s7, v152
	global_store_dwordx4 v[94:95], v[112:115], off
	s_nop 0
	v_addc_co_u32_e32 v79, vcc, 0, v153, vcc
	global_store_dwordx4 v[78:79], v[74:77], off offset:16
	global_store_dwordx4 v[86:87], v[88:91], off
	global_store_dwordx4 v[78:79], v[80:83], off
	v_add_co_u32_e32 v74, vcc, s10, v152
	s_waitcnt vmcnt(0)
	v_pk_fma_f32 v[72:73], v[72:73], v[136:137], v[180:181]
	v_pk_fma_f32 v[70:71], v[70:71], v[134:135], v[178:179]
	v_addc_co_u32_e32 v75, vcc, 0, v153, vcc
	v_pk_fma_f32 v[68:69], v[68:69], v[132:133], v[184:185]
	v_pk_fma_f32 v[66:67], v[66:67], v[130:131], v[182:183]
	global_store_dwordx4 v[74:75], v[70:73], off
	global_store_dwordx4 v[74:75], v[66:69], off offset:16
	s_mov_b64 s[10:11], 0x20200
	v_lshl_add_u64 v[76:77], v[150:151], 0, s[10:11]
	s_mov_b64 s[10:11], 0x40200
	global_load_dwordx4 v[80:83], v[150:151], off offset:512
	global_load_dwordx4 v[70:73], v[154:155], off offset:512
	global_load_dwordx4 v[66:69], v[154:155], off offset:528
	global_load_dwordx4 v[88:91], v[150:151], off offset:528
	global_load_dwordx4 v[112:115], v[156:157], off offset:512
	global_load_dwordx4 v[120:123], v[158:159], off offset:512
	global_load_dwordx4 v[124:127], v[76:77], off offset:16
	v_lshl_add_u64 v[76:77], v[150:151], 0, s[10:11]
	s_mov_b64 s[10:11], 0x60200
	global_load_dwordx4 v[128:131], v[76:77], off offset:16
	global_load_dwordx4 v[132:135], v[160:161], off offset:512
	v_lshl_add_u64 v[76:77], v[150:151], 0, s[10:11]
	global_load_dwordx4 v[154:157], v[76:77], off offset:16
	s_waitcnt vmcnt(0)
	v_pk_fma_f32 v[64:65], v[64:65], v[72:73], v[82:83]
	v_pk_fma_f32 v[62:63], v[62:63], v[70:71], v[80:81]
	v_pk_fma_f32 v[60:61], v[60:61], v[68:69], v[90:91]
	v_pk_fma_f32 v[58:59], v[58:59], v[66:67], v[88:89]
	v_pk_fma_f32 v[52:53], v[52:53], v[72:73], v[122:123]
	v_pk_fma_f32 v[50:51], v[50:51], v[70:71], v[120:121]
	v_pk_fma_f32 v[48:49], v[48:49], v[68:69], v[126:127]
	v_pk_fma_f32 v[46:47], v[46:47], v[66:67], v[124:125]
	v_pk_fma_f32 v[56:57], v[56:57], v[72:73], v[114:115]
	v_pk_fma_f32 v[54:55], v[54:55], v[70:71], v[112:113]
	global_store_dwordx4 v[152:153], v[62:65], off offset:512
	global_store_dwordx4 v[152:153], v[58:61], off offset:528
	global_store_dwordx4 v[118:119], v[54:57], off offset:512
	global_store_dwordx4 v[110:111], v[50:53], off offset:512
	v_pk_fma_f32 v[44:45], v[44:45], v[68:69], v[130:131]
	v_pk_fma_f32 v[42:43], v[42:43], v[66:67], v[128:129]
	v_pk_fma_f32 v[40:41], v[40:41], v[72:73], v[134:135]
	v_pk_fma_f32 v[38:39], v[38:39], v[70:71], v[132:133]
	v_pk_fma_f32 v[36:37], v[36:37], v[68:69], v[156:157]
	v_pk_fma_f32 v[34:35], v[34:35], v[66:67], v[154:155]
	global_store_dwordx4 v[118:119], v[46:49], off offset:528
	global_store_dwordx4 v[110:111], v[42:45], off offset:528
	global_store_dwordx4 v[102:103], v[38:41], off offset:512
	global_store_dwordx4 v[102:103], v[34:37], off offset:528
	s_mov_b64 s[10:11], 0x100200
	v_lshl_add_u64 v[50:51], v[150:151], 0, s[10:11]
	s_mov_b64 s[10:11], 0x120200
	v_lshl_add_u64 v[54:55], v[150:151], 0, s[10:11]
	s_mov_b64 s[10:11], 0x140200
	v_lshl_add_u64 v[58:59], v[150:151], 0, s[10:11]
	s_mov_b64 s[10:11], 0x160200
	global_load_dwordx4 v[34:37], v[98:99], off offset:512
	global_load_dwordx4 v[38:41], v[100:101], off offset:512
	global_load_dwordx4 v[42:45], v[104:105], off offset:512
	global_load_dwordx4 v[46:49], v[106:107], off offset:512
	v_lshl_add_u64 v[62:63], v[150:151], 0, s[10:11]
	global_load_dwordx4 v[50:53], v[50:51], off offset:16
	s_waitcnt vmcnt(0)
	v_pk_fma_f32 v[32:33], v[32:33], v[72:73], v[36:37]
	global_load_dwordx4 v[54:57], v[54:55], off offset:16
	v_pk_fma_f32 v[30:31], v[30:31], v[70:71], v[34:35]
	global_load_dwordx4 v[58:61], v[58:59], off offset:16
	v_pk_fma_f32 v[28:29], v[28:29], v[72:73], v[40:41]
	global_load_dwordx4 v[62:65], v[62:63], off offset:16
	v_pk_fma_f32 v[26:27], v[26:27], v[70:71], v[38:39]
	v_pk_fma_f32 v[24:25], v[24:25], v[72:73], v[44:45]
	v_pk_fma_f32 v[22:23], v[22:23], v[70:71], v[42:43]
	v_pk_fma_f32 v[12:13], v[12:13], v[72:73], v[48:49]
	v_pk_fma_f32 v[10:11], v[10:11], v[70:71], v[46:47]
	v_pk_fma_f32 v[20:21], v[20:21], v[68:69], v[52:53]
	v_pk_fma_f32 v[18:19], v[18:19], v[66:67], v[50:51]
	global_store_dwordx4 v[94:95], v[30:33], off offset:512
	global_store_dwordx4 v[86:87], v[26:29], off offset:512
	global_store_dwordx4 v[78:79], v[22:25], off offset:512
	global_store_dwordx4 v[74:75], v[10:13], off offset:512
	s_waitcnt vmcnt(0)
	v_pk_fma_f32 v[16:17], v[16:17], v[68:69], v[56:57]
	v_pk_fma_f32 v[14:15], v[14:15], v[66:67], v[54:55]
	v_pk_fma_f32 v[8:9], v[8:9], v[68:69], v[60:61]
	v_pk_fma_f32 v[6:7], v[6:7], v[66:67], v[58:59]
	v_pk_fma_f32 v[4:5], v[4:5], v[68:69], v[64:65]
	v_pk_fma_f32 v[2:3], v[2:3], v[66:67], v[62:63]
	global_store_dwordx4 v[94:95], v[18:21], off offset:528
	global_store_dwordx4 v[86:87], v[14:17], off offset:528
	global_store_dwordx4 v[78:79], v[6:9], off offset:528
	global_store_dwordx4 v[74:75], v[2:5], off offset:528
	s_and_b64 vcc, exec, s[0:1]
	s_mov_b32 s40, s6
	s_mov_b32 s28, s4
	s_mov_b64 s[54:55], s[34:35]
	s_mov_b64 s[52:53], s[8:9]
	s_cbranch_vccz .LBB0_501
	s_waitcnt vmcnt(0)
	v_readlane_b32 s28, v250, 12
	v_readlane_b32 s26, v250, 15
	s_cmpk_gt_u32 s12, 0xff
	v_readlane_b32 s29, v250, 13
	v_readlane_b32 s27, v250, 16
	s_mov_b32 s70, 0x800000
	v_readlane_b32 s79, v250, 18
	s_cbranch_scc1 .LBB0_508
	s_barrier
